# resid epilogue batched loads + NSA cmp-loop wait moved to consumer + adjacent setprio 0/1 pairs removed inside MFMA streams
# speedup vs baseline: 1.0009x; 1.0009x over previous
; #define PG8_STAGE(bufoff, gbase, voff) do { _Pragma("unroll") for (int _i = 0; _i < 2; ++_i) \
;         __builtin_amdgcn_global_load_lds((const unsigned*)((const char*)(gbase) + (voff)[_i]), (PG8_LAS unsigned*)(lds + (bufoff) + ldsw + _i * 8192), 16, 0, 0); } while (0)
; #define PG8_LDA(dst, b, h) do { _Pragma("unroll") for (int m = 0; m < 4; ++m) _Pragma("unroll") for (int k = 0; k < 2; ++k) dst[m][k] = *(const PG8_LAS bf16x8*)(lds + PG8_SA(b, h) + aoff + m * 2048 + k * 1024); } while (0)
; #define PG8_LDB(dst, b, h) do { _Pragma("unroll") for (int n = 0; n < 2; ++n) _Pragma("unroll") for (int k = 0; k < 2; ++k) dst[n][k] = *(const PG8_LAS bf16x8*)(lds + PG8_SB(b, h) + boff + n * 2048 + k * 1024); } while (0)
; #define PG8_MMA(ai, bj, At, Bt) do { __builtin_amdgcn_s_setprio(1); _Pragma("unroll") for (int m = 0; m < 4; ++m) _Pragma("unroll") for (int n = 0; n < 2; ++n) _Pragma("unroll") for (int k = 0; k < 2; ++k) \
;         acc[ai][bj][m][n] = __builtin_amdgcn_mfma_f32_16x16x32_bf16(Bt[n][k], At[m][k], acc[ai][bj][m][n], 0, 0, 0); __builtin_amdgcn_s_setprio(0); } while (0)
; #define PG8_WAIT_V(n) asm volatile("s_waitcnt vmcnt(" #n ")" ::: "memory")
; #define PG8_BAR __builtin_amdgcn_s_barrier()
; template <class Epi, class Sched, bool ALIGN_EPI = false, bool SP2 = false>
; __device__ __forceinline__ void gemm_phase(PG8_LAS unsigned char* lds, const Gemm g, const Sched& S, const Epi& E) {
;     ...
;         for (int t = 0; t < nt; t += 2) {
;             const bool last = (t == nt - 2);
;             const char* a1 = cA + (size_t)(t + 1) * kstep;
;             const char* a2 = last ? nA : cA + (size_t)(t + 2) * kstep; const char* b2 = last ? nB : cB + (size_t)(t + 2) * kstep;
;             const char* a3 = a2 + kstep; const char* b3 = b2 + kstep;
;             if (last && has_next) S.a_ready(nxt);
;             if constexpr (SP2) {
;             PG8_LDB(B0, 0, 0); PG8_LDB(B1, 0, 1); PG8_SCHED; PG8_LDA(At, 0, 0); PG8_STAGE(PG8_SA(1, 1), a1 + hstep, voffA);
;             PG8_WAIT_V(8); PG8_WAIT_L(0); PG8_BAR; PG8_MMA(0, 0, At, B0); PG8_MMA(0, 1, At, B1); PG8_BAR; PG8_SCHED;
;             PG8_LDA(At, 0, 1); PG8_STAGE(PG8_SB(0, 0), b2, voffB); PG8_STAGE(PG8_SB(0, 1), b2 + hstep, voffB); PG8_STAGE(PG8_SA(0, 0), a2, voffA);
;             PG8_WAIT_V(8); PG8_WAIT_L(0); PG8_BAR; PG8_MMA(1, 0, At, B0); PG8_MMA(1, 1, At, B1); PG8_BAR; PG8_SCHED;
.LBB0_482:
	ds_read_b128 v[146:149], v162
	ds_read_b128 v[150:153], v162 offset:1024
	ds_read_b128 v[154:157], v162 offset:2048
	ds_read_b128 v[166:169], v162 offset:3072
	ds_read_b128 v[170:173], v163
	ds_read_b128 v[174:177], v163 offset:1024
	ds_read_b128 v[178:181], v163 offset:2048
	ds_read_b128 v[182:185], v163 offset:3072
	s_add_u32 s34, s30, 0xfff80080
	s_addc_u32 s35, s31, -1
	s_cmp_eq_u32 s60, 28
	s_cselect_b32 s37, s23, s35
	s_cselect_b32 s36, s29, s34
	s_cselect_b32 s35, s21, s59
	s_cselect_b32 s34, s57, s58
	v_lshl_add_u64 v[194:195], s[30:31], 0, v[140:141]
	s_add_i32 m0, s42, 0xc000
	ds_read_b128 v[186:189], v164
	ds_read_b128 v[190:193], v164 offset:1024
	ds_read_b128 v[198:201], v164 offset:2048
	ds_read_b128 v[202:205], v164 offset:3072
	ds_read_b128 v[206:209], v164 offset:4096
	ds_read_b128 v[210:213], v164 offset:5120
	ds_read_b128 v[214:217], v164 offset:6144
	ds_read_b128 v[218:221], v164 offset:7168
	global_load_lds_dwordx4 v[194:195], off
	v_lshl_add_u64 v[194:195], s[30:31], 0, v[138:139]
	s_add_i32 m0, s42, 0xe000
	s_nop 0
	global_load_lds_dwordx4 v[194:195], off
	s_waitcnt vmcnt(8)
	s_waitcnt lgkmcnt(0)
	s_barrier
	s_setprio 1
	s_waitcnt lgkmcnt(0)
	v_mfma_f32_16x16x32_bf16 v[124:127], v[146:149], v[186:189], v[124:127]
	v_mfma_f32_16x16x32_bf16 v[116:119], v[154:157], v[186:189], v[116:119]
	v_mfma_f32_16x16x32_bf16 v[108:111], v[146:149], v[198:201], v[108:111]
	v_mfma_f32_16x16x32_bf16 v[100:103], v[154:157], v[198:201], v[100:103]
	v_mfma_f32_16x16x32_bf16 v[92:95], v[146:149], v[206:209], v[92:95]
	v_mfma_f32_16x16x32_bf16 v[84:87], v[154:157], v[206:209], v[84:87]
	v_mfma_f32_16x16x32_bf16 v[76:79], v[146:149], v[214:217], v[76:79]
	v_mfma_f32_16x16x32_bf16 v[68:71], v[154:157], v[214:217], v[68:71]
	v_mfma_f32_16x16x32_bf16 v[124:127], v[150:153], v[190:193], v[124:127]
	v_mfma_f32_16x16x32_bf16 v[116:119], v[166:169], v[190:193], v[116:119]
	v_mfma_f32_16x16x32_bf16 v[108:111], v[150:153], v[202:205], v[108:111]
	v_mfma_f32_16x16x32_bf16 v[100:103], v[166:169], v[202:205], v[100:103]
	v_mfma_f32_16x16x32_bf16 v[92:95], v[150:153], v[210:213], v[92:95]
	v_mfma_f32_16x16x32_bf16 v[84:87], v[166:169], v[210:213], v[84:87]
	v_mfma_f32_16x16x32_bf16 v[76:79], v[150:153], v[218:221], v[76:79]
	v_mfma_f32_16x16x32_bf16 v[68:71], v[166:169], v[218:221], v[68:71]
	v_mfma_f32_16x16x32_bf16 v[120:123], v[170:173], v[186:189], v[120:123]
	v_mfma_f32_16x16x32_bf16 v[112:115], v[178:181], v[186:189], v[112:115]
	v_mfma_f32_16x16x32_bf16 v[104:107], v[170:173], v[198:201], v[104:107]
	v_mfma_f32_16x16x32_bf16 v[96:99], v[178:181], v[198:201], v[96:99]
	v_mfma_f32_16x16x32_bf16 v[88:91], v[170:173], v[206:209], v[88:91]
	v_mfma_f32_16x16x32_bf16 v[80:83], v[178:181], v[206:209], v[80:83]
	v_mfma_f32_16x16x32_bf16 v[72:75], v[170:173], v[214:217], v[72:75]
	v_mfma_f32_16x16x32_bf16 v[64:67], v[178:181], v[214:217], v[64:67]
	v_mfma_f32_16x16x32_bf16 v[120:123], v[174:177], v[190:193], v[120:123]
	v_mfma_f32_16x16x32_bf16 v[112:115], v[182:185], v[190:193], v[112:115]
	v_mfma_f32_16x16x32_bf16 v[104:107], v[174:177], v[202:205], v[104:107]
	v_mfma_f32_16x16x32_bf16 v[96:99], v[182:185], v[202:205], v[96:99]
	v_mfma_f32_16x16x32_bf16 v[88:91], v[174:177], v[210:213], v[88:91]
	v_mfma_f32_16x16x32_bf16 v[80:83], v[182:185], v[210:213], v[80:83]
	v_mfma_f32_16x16x32_bf16 v[72:75], v[174:177], v[218:221], v[72:75]
	v_mfma_f32_16x16x32_bf16 v[64:67], v[182:185], v[218:221], v[64:67]
	s_setprio 0
	s_barrier
	s_add_i32 s61, s50, s39
	v_lshl_add_u64 v[194:195], s[34:35], 0, v[132:133]
	s_mov_b32 m0, s61
	ds_read_b128 v[186:189], v164 offset:16384
	ds_read_b128 v[190:193], v164 offset:17408
	ds_read_b128 v[198:201], v164 offset:18432
	ds_read_b128 v[202:205], v164 offset:19456
	ds_read_b128 v[206:209], v164 offset:20480
	ds_read_b128 v[210:213], v164 offset:21504
	ds_read_b128 v[214:217], v164 offset:22528
	ds_read_b128 v[218:221], v164 offset:23552
	global_load_lds_dwordx4 v[194:195], off
	s_add_i32 m0, s61, 0x2000
	s_add_u32 s62, s34, 0x80000
	v_lshl_add_u64 v[222:223], s[34:35], 0, v[128:129]
	s_addc_u32 s63, s35, 0
	s_add_i32 s61, s51, s39
	global_load_lds_dwordx4 v[222:223], off
	v_lshl_add_u64 v[224:225], s[62:63], 0, v[132:133]
	s_mov_b32 m0, s61
	v_lshl_add_u64 v[226:227], s[36:37], 0, v[130:131]
	global_load_lds_dwordx4 v[224:225], off
	v_lshl_add_u64 v[224:225], s[62:63], 0, v[128:129]
	s_add_i32 m0, s61, 0x2000
	s_nop 0
	global_load_lds_dwordx4 v[224:225], off
	v_lshl_add_u64 v[224:225], s[36:37], 0, v[134:135]
	s_mov_b32 m0, s42
	s_nop 0
	global_load_lds_dwordx4 v[224:225], off
	s_mov_b32 m0, s43
	s_nop 0
	global_load_lds_dwordx4 v[226:227], off
	s_waitcnt vmcnt(8)
	s_waitcnt lgkmcnt(0)
	s_barrier
; #define PG8_STAGE(bufoff, gbase, voff) do { _Pragma("unroll") for (int _i = 0; _i < 2; ++_i) \
;         __builtin_amdgcn_global_load_lds((const unsigned*)((const char*)(gbase) + (voff)[_i]), (PG8_LAS unsigned*)(lds + (bufoff) + ldsw + _i * 8192), 16, 0, 0); } while (0)
; #define PG8_LDA(dst, b, h) do { _Pragma("unroll") for (int m = 0; m < 4; ++m) _Pragma("unroll") for (int k = 0; k < 2; ++k) dst[m][k] = *(const PG8_LAS bf16x8*)(lds + PG8_SA(b, h) + aoff + m * 2048 + k * 1024); } while (0)
; #define PG8_LDB(dst, b, h) do { _Pragma("unroll") for (int n = 0; n < 2; ++n) _Pragma("unroll") for (int k = 0; k < 2; ++k) dst[n][k] = *(const PG8_LAS bf16x8*)(lds + PG8_SB(b, h) + boff + n * 2048 + k * 1024); } while (0)
; #define PG8_MMA(ai, bj, At, Bt) do { __builtin_amdgcn_s_setprio(1); _Pragma("unroll") for (int m = 0; m < 4; ++m) _Pragma("unroll") for (int n = 0; n < 2; ++n) _Pragma("unroll") for (int k = 0; k < 2; ++k) \
;         acc[ai][bj][m][n] = __builtin_amdgcn_mfma_f32_16x16x32_bf16(Bt[n][k], At[m][k], acc[ai][bj][m][n], 0, 0, 0); __builtin_amdgcn_s_setprio(0); } while (0)
; #define PG8_WAIT_V(n) asm volatile("s_waitcnt vmcnt(" #n ")" ::: "memory")
; #define PG8_WAIT_L(n) asm volatile("s_waitcnt lgkmcnt(" #n ")" ::: "memory")
; #define PG8_BAR __builtin_amdgcn_s_barrier()
; #define PG8_SCHED __builtin_amdgcn_sched_barrier(0)
; template <class Epi, class Sched, bool ALIGN_EPI = false, bool SP2 = false>
; __device__ __forceinline__ void gemm_phase(PG8_LAS unsigned char* lds, const Gemm g, const Sched& S, const Epi& E) {
;     ...
;             PG8_WAIT_V(8); PG8_WAIT_L(0); PG8_BAR; PG8_MMA(1, 0, At, B0); PG8_MMA(1, 1, At, B1); PG8_BAR; PG8_SCHED;
;             PG8_LDB(B0, 1, 0); PG8_LDB(B1, 1, 1); PG8_SCHED; PG8_LDA(At, 1, 0); PG8_STAGE(PG8_SA(0, 1), a2 + hstep, voffA);
;             PG8_WAIT_V(8); PG8_WAIT_L(0); PG8_BAR; PG8_MMA(0, 0, At, B0); PG8_MMA(0, 1, At, B1); PG8_BAR; PG8_SCHED;
	s_setprio 1
	s_waitcnt lgkmcnt(0)
	v_mfma_f32_16x16x32_bf16 v[60:63], v[146:149], v[186:189], v[60:63]
	v_mfma_f32_16x16x32_bf16 v[52:55], v[154:157], v[186:189], v[52:55]
	v_mfma_f32_16x16x32_bf16 v[44:47], v[146:149], v[198:201], v[44:47]
	v_mfma_f32_16x16x32_bf16 v[36:39], v[154:157], v[198:201], v[36:39]
	v_mfma_f32_16x16x32_bf16 v[28:31], v[146:149], v[206:209], v[28:31]
	v_mfma_f32_16x16x32_bf16 v[20:23], v[154:157], v[206:209], v[20:23]
	v_mfma_f32_16x16x32_bf16 v[12:15], v[146:149], v[214:217], v[12:15]
	v_mfma_f32_16x16x32_bf16 v[4:7], v[154:157], v[214:217], v[4:7]
	v_mfma_f32_16x16x32_bf16 v[60:63], v[150:153], v[190:193], v[60:63]
	v_mfma_f32_16x16x32_bf16 v[52:55], v[166:169], v[190:193], v[52:55]
	v_mfma_f32_16x16x32_bf16 v[44:47], v[150:153], v[202:205], v[44:47]
	v_mfma_f32_16x16x32_bf16 v[36:39], v[166:169], v[202:205], v[36:39]
	v_mfma_f32_16x16x32_bf16 v[28:31], v[150:153], v[210:213], v[28:31]
	v_mfma_f32_16x16x32_bf16 v[20:23], v[166:169], v[210:213], v[20:23]
	v_mfma_f32_16x16x32_bf16 v[12:15], v[150:153], v[218:221], v[12:15]
	v_mfma_f32_16x16x32_bf16 v[4:7], v[166:169], v[218:221], v[4:7]
	v_mfma_f32_16x16x32_bf16 v[56:59], v[170:173], v[186:189], v[56:59]
	v_mfma_f32_16x16x32_bf16 v[48:51], v[178:181], v[186:189], v[48:51]
	v_mfma_f32_16x16x32_bf16 v[40:43], v[170:173], v[198:201], v[40:43]
	v_mfma_f32_16x16x32_bf16 v[32:35], v[178:181], v[198:201], v[32:35]
	v_mfma_f32_16x16x32_bf16 v[24:27], v[170:173], v[206:209], v[24:27]
	v_mfma_f32_16x16x32_bf16 v[16:19], v[178:181], v[206:209], v[16:19]
	v_mfma_f32_16x16x32_bf16 v[8:11], v[170:173], v[214:217], v[8:11]
	v_mfma_f32_16x16x32_bf16 v[0:3], v[178:181], v[214:217], v[0:3]
	v_mfma_f32_16x16x32_bf16 v[56:59], v[174:177], v[190:193], v[56:59]
	v_mfma_f32_16x16x32_bf16 v[48:51], v[182:185], v[190:193], v[48:51]
	v_mfma_f32_16x16x32_bf16 v[40:43], v[174:177], v[202:205], v[40:43]
	v_mfma_f32_16x16x32_bf16 v[32:35], v[182:185], v[202:205], v[32:35]
	v_mfma_f32_16x16x32_bf16 v[24:27], v[174:177], v[210:213], v[24:27]
	v_mfma_f32_16x16x32_bf16 v[16:19], v[182:185], v[210:213], v[16:19]
	v_mfma_f32_16x16x32_bf16 v[8:11], v[174:177], v[218:221], v[8:11]
	v_mfma_f32_16x16x32_bf16 v[0:3], v[182:185], v[218:221], v[0:3]
	s_setprio 0
	s_barrier
	s_add_i32 s61, 0, 0x18000
	v_add_u32_e32 v136, s61, v159
	s_add_i32 s62, 0, 0x1c000
	ds_read_b128 v[146:149], v136
	ds_read_b128 v[150:153], v136 offset:1024
	ds_read_b128 v[154:157], v136 offset:2048
	ds_read_b128 v[166:169], v136 offset:3072
	v_add_u32_e32 v136, s62, v159
	ds_read_b128 v[170:173], v136
	ds_read_b128 v[174:177], v136 offset:1024
	ds_read_b128 v[178:181], v136 offset:2048
	ds_read_b128 v[182:185], v136 offset:3072
	s_add_u32 s36, s36, 0x80000
	s_addc_u32 s37, s37, 0
	s_mov_b32 m0, s44
	v_lshl_add_u64 v[228:229], s[36:37], 0, v[134:135]
	ds_read_b128 v[186:189], v164 offset:32768
	ds_read_b128 v[190:193], v164 offset:33792
	ds_read_b128 v[198:201], v164 offset:34816
	ds_read_b128 v[202:205], v164 offset:35840
	ds_read_b128 v[206:209], v164 offset:36864
	ds_read_b128 v[210:213], v164 offset:37888
	ds_read_b128 v[214:217], v164 offset:38912
	ds_read_b128 v[218:221], v164 offset:39936
	global_load_lds_dwordx4 v[228:229], off
	v_lshl_add_u64 v[228:229], s[36:37], 0, v[130:131]
	s_mov_b32 m0, s45
	s_nop 0
	global_load_lds_dwordx4 v[228:229], off
	s_waitcnt vmcnt(8)
	s_waitcnt lgkmcnt(0)
	s_barrier
	s_setprio 1
	s_waitcnt lgkmcnt(0)
	v_mfma_f32_16x16x32_bf16 v[124:127], v[146:149], v[186:189], v[124:127]
	v_mfma_f32_16x16x32_bf16 v[116:119], v[154:157], v[186:189], v[116:119]
	v_mfma_f32_16x16x32_bf16 v[108:111], v[146:149], v[198:201], v[108:111]
	v_mfma_f32_16x16x32_bf16 v[100:103], v[154:157], v[198:201], v[100:103]
	v_mfma_f32_16x16x32_bf16 v[92:95], v[146:149], v[206:209], v[92:95]
	v_mfma_f32_16x16x32_bf16 v[84:87], v[154:157], v[206:209], v[84:87]
	v_mfma_f32_16x16x32_bf16 v[76:79], v[146:149], v[214:217], v[76:79]
	v_mfma_f32_16x16x32_bf16 v[68:71], v[154:157], v[214:217], v[68:71]
	v_mfma_f32_16x16x32_bf16 v[124:127], v[150:153], v[190:193], v[124:127]
	v_mfma_f32_16x16x32_bf16 v[116:119], v[166:169], v[190:193], v[116:119]
	v_mfma_f32_16x16x32_bf16 v[108:111], v[150:153], v[202:205], v[108:111]
	v_mfma_f32_16x16x32_bf16 v[100:103], v[166:169], v[202:205], v[100:103]
	v_mfma_f32_16x16x32_bf16 v[92:95], v[150:153], v[210:213], v[92:95]
	v_mfma_f32_16x16x32_bf16 v[84:87], v[166:169], v[210:213], v[84:87]
	v_mfma_f32_16x16x32_bf16 v[76:79], v[150:153], v[218:221], v[76:79]
	v_mfma_f32_16x16x32_bf16 v[68:71], v[166:169], v[218:221], v[68:71]
	v_mfma_f32_16x16x32_bf16 v[120:123], v[170:173], v[186:189], v[120:123]
	v_mfma_f32_16x16x32_bf16 v[112:115], v[178:181], v[186:189], v[112:115]
	v_mfma_f32_16x16x32_bf16 v[104:107], v[170:173], v[198:201], v[104:107]
	v_mfma_f32_16x16x32_bf16 v[96:99], v[178:181], v[198:201], v[96:99]
	v_mfma_f32_16x16x32_bf16 v[88:91], v[170:173], v[206:209], v[88:91]
	v_mfma_f32_16x16x32_bf16 v[80:83], v[178:181], v[206:209], v[80:83]
	v_mfma_f32_16x16x32_bf16 v[72:75], v[170:173], v[214:217], v[72:75]
	v_mfma_f32_16x16x32_bf16 v[64:67], v[178:181], v[214:217], v[64:67]
	v_mfma_f32_16x16x32_bf16 v[120:123], v[174:177], v[190:193], v[120:123]
	v_mfma_f32_16x16x32_bf16 v[112:115], v[182:185], v[190:193], v[112:115]
	v_mfma_f32_16x16x32_bf16 v[104:107], v[174:177], v[202:205], v[104:107]
	v_mfma_f32_16x16x32_bf16 v[96:99], v[182:185], v[202:205], v[96:99]
	v_mfma_f32_16x16x32_bf16 v[88:91], v[174:177], v[210:213], v[88:91]
	v_mfma_f32_16x16x32_bf16 v[80:83], v[182:185], v[210:213], v[80:83]
	v_mfma_f32_16x16x32_bf16 v[72:75], v[174:177], v[218:221], v[72:75]
	v_mfma_f32_16x16x32_bf16 v[64:67], v[182:185], v[218:221], v[64:67]
	s_setprio 0
	s_barrier
; #define PG8_STAGE(bufoff, gbase, voff) do { _Pragma("unroll") for (int _i = 0; _i < 2; ++_i) \
;         __builtin_amdgcn_global_load_lds((const unsigned*)((const char*)(gbase) + (voff)[_i]), (PG8_LAS unsigned*)(lds + (bufoff) + ldsw + _i * 8192), 16, 0, 0); } while (0)
; #define PG8_LDA(dst, b, h) do { _Pragma("unroll") for (int m = 0; m < 4; ++m) _Pragma("unroll") for (int k = 0; k < 2; ++k) dst[m][k] = *(const PG8_LAS bf16x8*)(lds + PG8_SA(b, h) + aoff + m * 2048 + k * 1024); } while (0)
; #define PG8_WAIT_V(n) asm volatile("s_waitcnt vmcnt(" #n ")" ::: "memory")
; template <class Epi, class Sched, bool ALIGN_EPI = false, bool SP2 = false>
; __device__ __forceinline__ void gemm_phase(PG8_LAS unsigned char* lds, const Gemm g, const Sched& S, const Epi& E) {
;     ...
;             PG8_LDA(At, 1, 1); PG8_STAGE(PG8_SB(1, 0), b3, voffB); PG8_STAGE(PG8_SB(1, 1), b3 + hstep, voffB); PG8_STAGE(PG8_SA(1, 0), a3, voffA);
;             PG8_WAIT_V(8); PG8_WAIT_L(0); PG8_BAR; PG8_MMA(1, 0, At, B0); PG8_MMA(1, 1, At, B1); PG8_BAR; PG8_SCHED;
;             } else {
;             PG8_LDB(B0, 0, 0); PG8_SCHED; PG8_LDA(At, 0, 0); PG8_STAGE(PG8_SA(1, 1), a1 + hstep, voffA);
;             PG8_WAIT_L(8); PG8_BAR; PG8_WAIT_L(0); PG8_MMA(0, 0, At, B0); PG8_BAR; PG8_SCHED;
;             PG8_LDB(B1, 0, 1); PG8_STAGE(PG8_SB(0, 0), b2, voffB);
;             PG8_BAR; PG8_WAIT_L(0); PG8_MMA(0, 1, At, B1); PG8_BAR;
;             PG8_LDA(At, 0, 1); PG8_STAGE(PG8_SA(0, 0), a2, voffA);
;             PG8_BAR; PG8_WAIT_L(0); PG8_MMA(1, 0, At, B0); PG8_BAR; PG8_SCHED;
;             PG8_STAGE(PG8_SB(0, 1), b2 + hstep, voffB);
;             PG8_WAIT_V(6); PG8_BAR; PG8_MMA(1, 1, At, B1); PG8_BAR;
;             PG8_LDB(B0, 1, 0); PG8_SCHED; PG8_LDA(At, 1, 0); PG8_STAGE(PG8_SA(0, 1), a2 + hstep, voffA);
;             PG8_WAIT_L(8); PG8_BAR; PG8_WAIT_L(0); PG8_MMA(0, 0, At, B0); PG8_BAR; PG8_SCHED;
;             PG8_LDB(B1, 1, 1); PG8_STAGE(PG8_SB(1, 0), b3, voffB);
;             PG8_BAR; PG8_WAIT_L(0); PG8_MMA(0, 1, At, B1); PG8_BAR;
;             PG8_LDA(At, 1, 1); PG8_STAGE(PG8_SA(1, 0), a3, voffA);
;             PG8_BAR; PG8_WAIT_L(0); PG8_MMA(1, 0, At, B0); PG8_BAR; PG8_SCHED;
;             PG8_STAGE(PG8_SB(1, 1), b3 + hstep, voffB);
;             PG8_WAIT_V(6); PG8_BAR; PG8_MMA(1, 1, At, B1); PG8_BAR;
;             }
;         }
;         if constexpr (ALIGN_EPI) { if (wr == 0) PG8_BAR; }
	s_add_i32 s36, s61, s39
	v_lshl_add_u64 v[194:195], v[194:195], 0, s[16:17]
	s_mov_b32 m0, s36
	ds_read_b128 v[186:189], v164 offset:49152
	ds_read_b128 v[190:193], v164 offset:50176
	ds_read_b128 v[198:201], v164 offset:51200
	ds_read_b128 v[202:205], v164 offset:52224
	ds_read_b128 v[206:209], v164 offset:53248
	ds_read_b128 v[210:213], v164 offset:54272
	ds_read_b128 v[214:217], v164 offset:55296
	ds_read_b128 v[218:221], v164 offset:56320
	global_load_lds_dwordx4 v[194:195], off
	s_add_i32 m0, s36, 0x2000
	s_add_u32 s34, s34, 0x80080
	v_lshl_add_u64 v[194:195], v[222:223], 0, s[16:17]
	s_addc_u32 s35, s35, 0
	s_add_i32 s36, s62, s39
	global_load_lds_dwordx4 v[194:195], off
	v_lshl_add_u64 v[194:195], s[34:35], 0, v[132:133]
	s_mov_b32 m0, s36
	s_nop 0
	global_load_lds_dwordx4 v[194:195], off
	v_lshl_add_u64 v[194:195], s[34:35], 0, v[128:129]
	s_add_i32 m0, s36, 0x2000
	s_nop 0
	global_load_lds_dwordx4 v[194:195], off
	v_lshl_add_u64 v[194:195], v[224:225], 0, s[16:17]
	s_mov_b32 m0, s47
	s_nop 0
	global_load_lds_dwordx4 v[194:195], off
	v_lshl_add_u64 v[194:195], v[226:227], 0, s[16:17]
	s_mov_b32 m0, s48
	s_nop 0
	global_load_lds_dwordx4 v[194:195], off
	s_waitcnt vmcnt(8)
	s_waitcnt lgkmcnt(0)
	s_barrier
	s_setprio 1
	s_waitcnt lgkmcnt(0)
	v_mfma_f32_16x16x32_bf16 v[60:63], v[146:149], v[186:189], v[60:63]
	v_mfma_f32_16x16x32_bf16 v[52:55], v[154:157], v[186:189], v[52:55]
	v_mfma_f32_16x16x32_bf16 v[44:47], v[146:149], v[198:201], v[44:47]
	v_mfma_f32_16x16x32_bf16 v[36:39], v[154:157], v[198:201], v[36:39]
	v_mfma_f32_16x16x32_bf16 v[28:31], v[146:149], v[206:209], v[28:31]
	v_mfma_f32_16x16x32_bf16 v[20:23], v[154:157], v[206:209], v[20:23]
	v_mfma_f32_16x16x32_bf16 v[12:15], v[146:149], v[214:217], v[12:15]
	v_mfma_f32_16x16x32_bf16 v[4:7], v[154:157], v[214:217], v[4:7]
	v_mfma_f32_16x16x32_bf16 v[60:63], v[150:153], v[190:193], v[60:63]
	v_mfma_f32_16x16x32_bf16 v[52:55], v[166:169], v[190:193], v[52:55]
	v_mfma_f32_16x16x32_bf16 v[44:47], v[150:153], v[202:205], v[44:47]
	v_mfma_f32_16x16x32_bf16 v[36:39], v[166:169], v[202:205], v[36:39]
	v_mfma_f32_16x16x32_bf16 v[28:31], v[150:153], v[210:213], v[28:31]
	v_mfma_f32_16x16x32_bf16 v[20:23], v[166:169], v[210:213], v[20:23]
	v_mfma_f32_16x16x32_bf16 v[12:15], v[150:153], v[218:221], v[12:15]
	v_mfma_f32_16x16x32_bf16 v[4:7], v[166:169], v[218:221], v[4:7]
	v_mfma_f32_16x16x32_bf16 v[56:59], v[170:173], v[186:189], v[56:59]
	v_mfma_f32_16x16x32_bf16 v[48:51], v[178:181], v[186:189], v[48:51]
	v_mfma_f32_16x16x32_bf16 v[40:43], v[170:173], v[198:201], v[40:43]
	v_mfma_f32_16x16x32_bf16 v[32:35], v[178:181], v[198:201], v[32:35]
	v_mfma_f32_16x16x32_bf16 v[24:27], v[170:173], v[206:209], v[24:27]
	v_mfma_f32_16x16x32_bf16 v[16:19], v[178:181], v[206:209], v[16:19]
	v_mfma_f32_16x16x32_bf16 v[8:11], v[170:173], v[214:217], v[8:11]
	v_mfma_f32_16x16x32_bf16 v[0:3], v[178:181], v[214:217], v[0:3]
	v_mfma_f32_16x16x32_bf16 v[56:59], v[174:177], v[190:193], v[56:59]
	v_mfma_f32_16x16x32_bf16 v[48:51], v[182:185], v[190:193], v[48:51]
	v_mfma_f32_16x16x32_bf16 v[40:43], v[174:177], v[202:205], v[40:43]
	v_mfma_f32_16x16x32_bf16 v[32:35], v[182:185], v[202:205], v[32:35]
	v_mfma_f32_16x16x32_bf16 v[24:27], v[174:177], v[210:213], v[24:27]
	v_mfma_f32_16x16x32_bf16 v[16:19], v[182:185], v[210:213], v[16:19]
	v_mfma_f32_16x16x32_bf16 v[8:11], v[174:177], v[218:221], v[8:11]
	v_mfma_f32_16x16x32_bf16 v[0:3], v[182:185], v[218:221], v[0:3]
	s_setprio 0
	s_barrier
	s_add_i32 s60, s60, 2
	s_add_u32 s58, s58, 0x100
	s_addc_u32 s59, s59, 0
	s_add_u32 s30, s30, 0x100
	s_addc_u32 s31, s31, 0
	s_cmp_gt_u32 s60, 29
	s_cbranch_scc0 .LBB0_482
	s_and_b64 vcc, exec, s[18:19]
	s_cbranch_vccz .LBB0_485
	s_barrier

; #define PG8_STAGE(bufoff, gbase, voff) do { _Pragma("unroll") for (int _i = 0; _i < 2; ++_i) \
;         __builtin_amdgcn_global_load_lds((const unsigned*)((const char*)(gbase) + (voff)[_i]), (PG8_LAS unsigned*)(lds + (bufoff) + ldsw + _i * 8192), 16, 0, 0); } while (0)
; #define PG8_LDA(dst, b, h) do { _Pragma("unroll") for (int m = 0; m < 4; ++m) _Pragma("unroll") for (int k = 0; k < 2; ++k) dst[m][k] = *(const PG8_LAS bf16x8*)(lds + PG8_SA(b, h) + aoff + m * 2048 + k * 1024); } while (0)
; #define PG8_LDB(dst, b, h) do { _Pragma("unroll") for (int n = 0; n < 2; ++n) _Pragma("unroll") for (int k = 0; k < 2; ++k) dst[n][k] = *(const PG8_LAS bf16x8*)(lds + PG8_SB(b, h) + boff + n * 2048 + k * 1024); } while (0)
; #define PG8_MMA(ai, bj, At, Bt) do { __builtin_amdgcn_s_setprio(1); _Pragma("unroll") for (int m = 0; m < 4; ++m) _Pragma("unroll") for (int n = 0; n < 2; ++n) _Pragma("unroll") for (int k = 0; k < 2; ++k) \
;         acc[ai][bj][m][n] = __builtin_amdgcn_mfma_f32_16x16x32_bf16(Bt[n][k], At[m][k], acc[ai][bj][m][n], 0, 0, 0); __builtin_amdgcn_s_setprio(0); } while (0)
; #define PG8_WAIT_V(n) asm volatile("s_waitcnt vmcnt(" #n ")" ::: "memory")
; #define PG8_BAR __builtin_amdgcn_s_barrier()
; template <class Epi, class Sched, bool ALIGN_EPI = false, bool SP2 = false>
; __device__ __forceinline__ void gemm_phase(PG8_LAS unsigned char* lds, const Gemm g, const Sched& S, const Epi& E) {
;     ...
;         for (int t = 0; t < nt; t += 2) {
;             const bool last = (t == nt - 2);
;             const char* a1 = cA + (size_t)(t + 1) * kstep;
;             const char* a2 = last ? nA : cA + (size_t)(t + 2) * kstep; const char* b2 = last ? nB : cB + (size_t)(t + 2) * kstep;
;             const char* a3 = a2 + kstep; const char* b3 = b2 + kstep;
;             if (last && has_next) S.a_ready(nxt);
;             if constexpr (SP2) {
;             PG8_LDB(B0, 0, 0); PG8_LDB(B1, 0, 1); PG8_SCHED; PG8_LDA(At, 0, 0); PG8_STAGE(PG8_SA(1, 1), a1 + hstep, voffA);
;             PG8_WAIT_V(8); PG8_WAIT_L(0); PG8_BAR; PG8_MMA(0, 0, At, B0); PG8_MMA(0, 1, At, B1); PG8_BAR; PG8_SCHED;
;             PG8_LDA(At, 0, 1); PG8_STAGE(PG8_SB(0, 0), b2, voffB); PG8_STAGE(PG8_SB(0, 1), b2 + hstep, voffB); PG8_STAGE(PG8_SA(0, 0), a2, voffA);
;             PG8_WAIT_V(8); PG8_WAIT_L(0); PG8_BAR; PG8_MMA(1, 0, At, B0); PG8_MMA(1, 1, At, B1); PG8_BAR; PG8_SCHED;
.LBB0_767:
	ds_read_b128 v[144:147], v152
	ds_read_b128 v[156:159], v152 offset:1024
	ds_read_b128 v[160:163], v152 offset:2048
	ds_read_b128 v[164:167], v152 offset:3072
	ds_read_b128 v[168:171], v153
	ds_read_b128 v[172:175], v153 offset:1024
	ds_read_b128 v[176:179], v153 offset:2048
	ds_read_b128 v[180:183], v153 offset:3072
	s_add_u32 s34, s30, 0xfff80080
	s_addc_u32 s35, s31, -1
	s_cmp_eq_u32 s63, 28
	s_cselect_b32 s37, s57, s35
	s_cselect_b32 s36, s58, s34
	s_cselect_b32 s35, s59, s62
	s_cselect_b32 s34, s60, s61
	s_mov_b32 m0, s52
	v_lshl_add_u64 v[148:149], s[30:31], 0, v[142:143]
	ds_read_b128 v[184:187], v154
	ds_read_b128 v[188:191], v154 offset:1024
	ds_read_b128 v[192:195], v154 offset:2048
	ds_read_b128 v[198:201], v154 offset:3072
	ds_read_b128 v[202:205], v154 offset:4096
	ds_read_b128 v[206:209], v154 offset:5120
	ds_read_b128 v[210:213], v154 offset:6144
	ds_read_b128 v[214:217], v154 offset:7168
	global_load_lds_dwordx4 v[148:149], off
	v_lshl_add_u64 v[148:149], s[30:31], 0, v[140:141]
	s_mov_b32 m0, s53
	s_nop 0
	global_load_lds_dwordx4 v[148:149], off
	s_waitcnt vmcnt(8)
	s_waitcnt lgkmcnt(0)
	s_barrier
	s_setprio 1
	s_waitcnt lgkmcnt(0)
	v_mfma_f32_16x16x32_bf16 v[124:127], v[144:147], v[184:187], v[124:127]
	v_mfma_f32_16x16x32_bf16 v[120:123], v[160:163], v[184:187], v[120:123]
	v_mfma_f32_16x16x32_bf16 v[108:111], v[144:147], v[192:195], v[108:111]
	v_mfma_f32_16x16x32_bf16 v[104:107], v[160:163], v[192:195], v[104:107]
	v_mfma_f32_16x16x32_bf16 v[92:95], v[144:147], v[202:205], v[92:95]
	v_mfma_f32_16x16x32_bf16 v[88:91], v[160:163], v[202:205], v[88:91]
	v_mfma_f32_16x16x32_bf16 v[76:79], v[144:147], v[210:213], v[76:79]
	v_mfma_f32_16x16x32_bf16 v[72:75], v[160:163], v[210:213], v[72:75]
	v_mfma_f32_16x16x32_bf16 v[124:127], v[156:159], v[188:191], v[124:127]
	v_mfma_f32_16x16x32_bf16 v[120:123], v[164:167], v[188:191], v[120:123]
	v_mfma_f32_16x16x32_bf16 v[108:111], v[156:159], v[198:201], v[108:111]
	v_mfma_f32_16x16x32_bf16 v[104:107], v[164:167], v[198:201], v[104:107]
	v_mfma_f32_16x16x32_bf16 v[92:95], v[156:159], v[206:209], v[92:95]
	v_mfma_f32_16x16x32_bf16 v[88:91], v[164:167], v[206:209], v[88:91]
	v_mfma_f32_16x16x32_bf16 v[76:79], v[156:159], v[214:217], v[76:79]
	v_mfma_f32_16x16x32_bf16 v[72:75], v[164:167], v[214:217], v[72:75]
	v_mfma_f32_16x16x32_bf16 v[116:119], v[168:171], v[184:187], v[116:119]
	v_mfma_f32_16x16x32_bf16 v[112:115], v[176:179], v[184:187], v[112:115]
	v_mfma_f32_16x16x32_bf16 v[100:103], v[168:171], v[192:195], v[100:103]
	v_mfma_f32_16x16x32_bf16 v[96:99], v[176:179], v[192:195], v[96:99]
	v_mfma_f32_16x16x32_bf16 v[84:87], v[168:171], v[202:205], v[84:87]
	v_mfma_f32_16x16x32_bf16 v[80:83], v[176:179], v[202:205], v[80:83]
	v_mfma_f32_16x16x32_bf16 v[68:71], v[168:171], v[210:213], v[68:71]
	v_mfma_f32_16x16x32_bf16 v[64:67], v[176:179], v[210:213], v[64:67]
	v_mfma_f32_16x16x32_bf16 v[116:119], v[172:175], v[188:191], v[116:119]
	v_mfma_f32_16x16x32_bf16 v[112:115], v[180:183], v[188:191], v[112:115]
	v_mfma_f32_16x16x32_bf16 v[100:103], v[172:175], v[198:201], v[100:103]
	v_mfma_f32_16x16x32_bf16 v[96:99], v[180:183], v[198:201], v[96:99]
	v_mfma_f32_16x16x32_bf16 v[84:87], v[172:175], v[206:209], v[84:87]
	v_mfma_f32_16x16x32_bf16 v[80:83], v[180:183], v[206:209], v[80:83]
	v_mfma_f32_16x16x32_bf16 v[68:71], v[172:175], v[214:217], v[68:71]
	v_mfma_f32_16x16x32_bf16 v[64:67], v[180:183], v[214:217], v[64:67]
	s_setprio 0
	s_barrier
	s_add_i32 s64, s50, s40
	v_lshl_add_u64 v[148:149], s[34:35], 0, v[132:133]
	s_mov_b32 m0, s64
	ds_read_b128 v[184:187], v154 offset:16384
	ds_read_b128 v[188:191], v154 offset:17408
	ds_read_b128 v[192:195], v154 offset:18432
	ds_read_b128 v[198:201], v154 offset:19456
	ds_read_b128 v[202:205], v154 offset:20480
	ds_read_b128 v[206:209], v154 offset:21504
	ds_read_b128 v[210:213], v154 offset:22528
	ds_read_b128 v[214:217], v154 offset:23552
	global_load_lds_dwordx4 v[148:149], off
	s_add_i32 m0, s64, 0x2000
	s_add_u32 s64, s34, 0x80000
	v_lshl_add_u64 v[218:219], s[34:35], 0, v[128:129]
	s_addc_u32 s65, s35, 0
	s_add_i32 s66, s51, s40
	global_load_lds_dwordx4 v[218:219], off
	v_lshl_add_u64 v[220:221], s[64:65], 0, v[132:133]
	s_mov_b32 m0, s66
	v_lshl_add_u64 v[222:223], s[36:37], 0, v[130:131]
	global_load_lds_dwordx4 v[220:221], off
	v_lshl_add_u64 v[220:221], s[64:65], 0, v[128:129]
	s_add_i32 m0, s66, 0x2000
	s_nop 0
	global_load_lds_dwordx4 v[220:221], off
	v_lshl_add_u64 v[220:221], s[36:37], 0, v[134:135]
	s_mov_b32 m0, s3
	s_nop 0
	global_load_lds_dwordx4 v[220:221], off
	s_mov_b32 m0, s9
	s_nop 0
	global_load_lds_dwordx4 v[222:223], off
	s_waitcnt vmcnt(8)
	s_waitcnt lgkmcnt(0)
	s_barrier
; #define PG8_STAGE(bufoff, gbase, voff) do { _Pragma("unroll") for (int _i = 0; _i < 2; ++_i) \
;         __builtin_amdgcn_global_load_lds((const unsigned*)((const char*)(gbase) + (voff)[_i]), (PG8_LAS unsigned*)(lds + (bufoff) + ldsw + _i * 8192), 16, 0, 0); } while (0)
; #define PG8_LDA(dst, b, h) do { _Pragma("unroll") for (int m = 0; m < 4; ++m) _Pragma("unroll") for (int k = 0; k < 2; ++k) dst[m][k] = *(const PG8_LAS bf16x8*)(lds + PG8_SA(b, h) + aoff + m * 2048 + k * 1024); } while (0)
; #define PG8_LDB(dst, b, h) do { _Pragma("unroll") for (int n = 0; n < 2; ++n) _Pragma("unroll") for (int k = 0; k < 2; ++k) dst[n][k] = *(const PG8_LAS bf16x8*)(lds + PG8_SB(b, h) + boff + n * 2048 + k * 1024); } while (0)
; #define PG8_MMA(ai, bj, At, Bt) do { __builtin_amdgcn_s_setprio(1); _Pragma("unroll") for (int m = 0; m < 4; ++m) _Pragma("unroll") for (int n = 0; n < 2; ++n) _Pragma("unroll") for (int k = 0; k < 2; ++k) \
;         acc[ai][bj][m][n] = __builtin_amdgcn_mfma_f32_16x16x32_bf16(Bt[n][k], At[m][k], acc[ai][bj][m][n], 0, 0, 0); __builtin_amdgcn_s_setprio(0); } while (0)
; #define PG8_WAIT_V(n) asm volatile("s_waitcnt vmcnt(" #n ")" ::: "memory")
; #define PG8_WAIT_L(n) asm volatile("s_waitcnt lgkmcnt(" #n ")" ::: "memory")
; #define PG8_BAR __builtin_amdgcn_s_barrier()
; #define PG8_SCHED __builtin_amdgcn_sched_barrier(0)
; template <class Epi, class Sched, bool ALIGN_EPI = false, bool SP2 = false>
; __device__ __forceinline__ void gemm_phase(PG8_LAS unsigned char* lds, const Gemm g, const Sched& S, const Epi& E) {
;     ...
;             PG8_WAIT_V(8); PG8_WAIT_L(0); PG8_BAR; PG8_MMA(1, 0, At, B0); PG8_MMA(1, 1, At, B1); PG8_BAR; PG8_SCHED;
;             PG8_LDB(B0, 1, 0); PG8_LDB(B1, 1, 1); PG8_SCHED; PG8_LDA(At, 1, 0); PG8_STAGE(PG8_SA(0, 1), a2 + hstep, voffA);
;             PG8_WAIT_V(8); PG8_WAIT_L(0); PG8_BAR; PG8_MMA(0, 0, At, B0); PG8_MMA(0, 1, At, B1); PG8_BAR; PG8_SCHED;
	s_setprio 1
	s_waitcnt lgkmcnt(0)
	v_mfma_f32_16x16x32_bf16 v[60:63], v[144:147], v[184:187], v[60:63]
	v_mfma_f32_16x16x32_bf16 v[56:59], v[160:163], v[184:187], v[56:59]
	v_mfma_f32_16x16x32_bf16 v[44:47], v[144:147], v[192:195], v[44:47]
	v_mfma_f32_16x16x32_bf16 v[40:43], v[160:163], v[192:195], v[40:43]
	v_mfma_f32_16x16x32_bf16 v[28:31], v[144:147], v[202:205], v[28:31]
	v_mfma_f32_16x16x32_bf16 v[24:27], v[160:163], v[202:205], v[24:27]
	v_mfma_f32_16x16x32_bf16 v[12:15], v[144:147], v[210:213], v[12:15]
	v_mfma_f32_16x16x32_bf16 v[8:11], v[160:163], v[210:213], v[8:11]
	v_mfma_f32_16x16x32_bf16 v[60:63], v[156:159], v[188:191], v[60:63]
	v_mfma_f32_16x16x32_bf16 v[56:59], v[164:167], v[188:191], v[56:59]
	v_mfma_f32_16x16x32_bf16 v[44:47], v[156:159], v[198:201], v[44:47]
	v_mfma_f32_16x16x32_bf16 v[40:43], v[164:167], v[198:201], v[40:43]
	v_mfma_f32_16x16x32_bf16 v[28:31], v[156:159], v[206:209], v[28:31]
	v_mfma_f32_16x16x32_bf16 v[24:27], v[164:167], v[206:209], v[24:27]
	v_mfma_f32_16x16x32_bf16 v[12:15], v[156:159], v[214:217], v[12:15]
	v_mfma_f32_16x16x32_bf16 v[8:11], v[164:167], v[214:217], v[8:11]
	v_mfma_f32_16x16x32_bf16 v[52:55], v[168:171], v[184:187], v[52:55]
	v_mfma_f32_16x16x32_bf16 v[48:51], v[176:179], v[184:187], v[48:51]
	v_mfma_f32_16x16x32_bf16 v[36:39], v[168:171], v[192:195], v[36:39]
	v_mfma_f32_16x16x32_bf16 v[32:35], v[176:179], v[192:195], v[32:35]
	v_mfma_f32_16x16x32_bf16 v[20:23], v[168:171], v[202:205], v[20:23]
	v_mfma_f32_16x16x32_bf16 v[16:19], v[176:179], v[202:205], v[16:19]
	v_mfma_f32_16x16x32_bf16 v[4:7], v[168:171], v[210:213], v[4:7]
	v_mfma_f32_16x16x32_bf16 v[0:3], v[176:179], v[210:213], v[0:3]
	v_mfma_f32_16x16x32_bf16 v[52:55], v[172:175], v[188:191], v[52:55]
	v_mfma_f32_16x16x32_bf16 v[48:51], v[180:183], v[188:191], v[48:51]
	v_mfma_f32_16x16x32_bf16 v[36:39], v[172:175], v[198:201], v[36:39]
	v_mfma_f32_16x16x32_bf16 v[32:35], v[180:183], v[198:201], v[32:35]
	v_mfma_f32_16x16x32_bf16 v[20:23], v[172:175], v[206:209], v[20:23]
	v_mfma_f32_16x16x32_bf16 v[16:19], v[180:183], v[206:209], v[16:19]
	v_mfma_f32_16x16x32_bf16 v[4:7], v[172:175], v[214:217], v[4:7]
	v_mfma_f32_16x16x32_bf16 v[0:3], v[180:183], v[214:217], v[0:3]
	s_setprio 0
	s_barrier
	s_add_i32 s64, 0, 0x18000
	v_add_u32_e32 v155, s64, v151
	s_add_i32 s65, 0, 0x1c000
	ds_read_b128 v[144:147], v155
	ds_read_b128 v[156:159], v155 offset:1024
	ds_read_b128 v[160:163], v155 offset:2048
	ds_read_b128 v[164:167], v155 offset:3072
	v_add_u32_e32 v155, s65, v151
	ds_read_b128 v[168:171], v155
	ds_read_b128 v[172:175], v155 offset:1024
	ds_read_b128 v[176:179], v155 offset:2048
	ds_read_b128 v[180:183], v155 offset:3072
	s_add_u32 s36, s36, 0x80000
	s_addc_u32 s37, s37, 0
	s_mov_b32 m0, s41
	v_lshl_add_u64 v[224:225], s[36:37], 0, v[134:135]
	ds_read_b128 v[184:187], v154 offset:32768
	ds_read_b128 v[188:191], v154 offset:33792
	ds_read_b128 v[192:195], v154 offset:34816
	ds_read_b128 v[198:201], v154 offset:35840
	ds_read_b128 v[202:205], v154 offset:36864
	ds_read_b128 v[206:209], v154 offset:37888
	ds_read_b128 v[210:213], v154 offset:38912
	ds_read_b128 v[214:217], v154 offset:39936
	global_load_lds_dwordx4 v[224:225], off
	v_lshl_add_u64 v[224:225], s[36:37], 0, v[130:131]
	s_mov_b32 m0, s42
	s_nop 0
	global_load_lds_dwordx4 v[224:225], off
	s_waitcnt vmcnt(8)
	s_waitcnt lgkmcnt(0)
	s_barrier
	s_setprio 1
	s_waitcnt lgkmcnt(0)
	v_mfma_f32_16x16x32_bf16 v[124:127], v[144:147], v[184:187], v[124:127]
	v_mfma_f32_16x16x32_bf16 v[120:123], v[160:163], v[184:187], v[120:123]
	v_mfma_f32_16x16x32_bf16 v[108:111], v[144:147], v[192:195], v[108:111]
	v_mfma_f32_16x16x32_bf16 v[104:107], v[160:163], v[192:195], v[104:107]
	v_mfma_f32_16x16x32_bf16 v[92:95], v[144:147], v[202:205], v[92:95]
	v_mfma_f32_16x16x32_bf16 v[88:91], v[160:163], v[202:205], v[88:91]
	v_mfma_f32_16x16x32_bf16 v[76:79], v[144:147], v[210:213], v[76:79]
	v_mfma_f32_16x16x32_bf16 v[72:75], v[160:163], v[210:213], v[72:75]
	v_mfma_f32_16x16x32_bf16 v[124:127], v[156:159], v[188:191], v[124:127]
	v_mfma_f32_16x16x32_bf16 v[120:123], v[164:167], v[188:191], v[120:123]
	v_mfma_f32_16x16x32_bf16 v[108:111], v[156:159], v[198:201], v[108:111]
	v_mfma_f32_16x16x32_bf16 v[104:107], v[164:167], v[198:201], v[104:107]
	v_mfma_f32_16x16x32_bf16 v[92:95], v[156:159], v[206:209], v[92:95]
	v_mfma_f32_16x16x32_bf16 v[88:91], v[164:167], v[206:209], v[88:91]
	v_mfma_f32_16x16x32_bf16 v[76:79], v[156:159], v[214:217], v[76:79]
	v_mfma_f32_16x16x32_bf16 v[72:75], v[164:167], v[214:217], v[72:75]
	v_mfma_f32_16x16x32_bf16 v[116:119], v[168:171], v[184:187], v[116:119]
	v_mfma_f32_16x16x32_bf16 v[112:115], v[176:179], v[184:187], v[112:115]
	v_mfma_f32_16x16x32_bf16 v[100:103], v[168:171], v[192:195], v[100:103]
	v_mfma_f32_16x16x32_bf16 v[96:99], v[176:179], v[192:195], v[96:99]
	v_mfma_f32_16x16x32_bf16 v[84:87], v[168:171], v[202:205], v[84:87]
	v_mfma_f32_16x16x32_bf16 v[80:83], v[176:179], v[202:205], v[80:83]
	v_mfma_f32_16x16x32_bf16 v[68:71], v[168:171], v[210:213], v[68:71]
	v_mfma_f32_16x16x32_bf16 v[64:67], v[176:179], v[210:213], v[64:67]
	v_mfma_f32_16x16x32_bf16 v[116:119], v[172:175], v[188:191], v[116:119]
	v_mfma_f32_16x16x32_bf16 v[112:115], v[180:183], v[188:191], v[112:115]
	v_mfma_f32_16x16x32_bf16 v[100:103], v[172:175], v[198:201], v[100:103]
	v_mfma_f32_16x16x32_bf16 v[96:99], v[180:183], v[198:201], v[96:99]
	v_mfma_f32_16x16x32_bf16 v[84:87], v[172:175], v[206:209], v[84:87]
	v_mfma_f32_16x16x32_bf16 v[80:83], v[180:183], v[206:209], v[80:83]
	v_mfma_f32_16x16x32_bf16 v[68:71], v[172:175], v[214:217], v[68:71]
	v_mfma_f32_16x16x32_bf16 v[64:67], v[180:183], v[214:217], v[64:67]
	s_setprio 0
	s_barrier
; #define PG8_STAGE(bufoff, gbase, voff) do { _Pragma("unroll") for (int _i = 0; _i < 2; ++_i) \
;         __builtin_amdgcn_global_load_lds((const unsigned*)((const char*)(gbase) + (voff)[_i]), (PG8_LAS unsigned*)(lds + (bufoff) + ldsw + _i * 8192), 16, 0, 0); } while (0)
; #define PG8_LDA(dst, b, h) do { _Pragma("unroll") for (int m = 0; m < 4; ++m) _Pragma("unroll") for (int k = 0; k < 2; ++k) dst[m][k] = *(const PG8_LAS bf16x8*)(lds + PG8_SA(b, h) + aoff + m * 2048 + k * 1024); } while (0)
; #define PG8_WAIT_V(n) asm volatile("s_waitcnt vmcnt(" #n ")" ::: "memory")
; template <class Epi, class Sched, bool ALIGN_EPI = false, bool SP2 = false>
; __device__ __forceinline__ void gemm_phase(PG8_LAS unsigned char* lds, const Gemm g, const Sched& S, const Epi& E) {
;     ...
;             PG8_LDA(At, 1, 1); PG8_STAGE(PG8_SB(1, 0), b3, voffB); PG8_STAGE(PG8_SB(1, 1), b3 + hstep, voffB); PG8_STAGE(PG8_SA(1, 0), a3, voffA);
;             PG8_WAIT_V(8); PG8_WAIT_L(0); PG8_BAR; PG8_MMA(1, 0, At, B0); PG8_MMA(1, 1, At, B1); PG8_BAR; PG8_SCHED;
;             } else {
;             PG8_LDB(B0, 0, 0); PG8_SCHED; PG8_LDA(At, 0, 0); PG8_STAGE(PG8_SA(1, 1), a1 + hstep, voffA);
;             PG8_WAIT_L(8); PG8_BAR; PG8_WAIT_L(0); PG8_MMA(0, 0, At, B0); PG8_BAR; PG8_SCHED;
;             PG8_LDB(B1, 0, 1); PG8_STAGE(PG8_SB(0, 0), b2, voffB);
;             PG8_BAR; PG8_WAIT_L(0); PG8_MMA(0, 1, At, B1); PG8_BAR;
;             PG8_LDA(At, 0, 1); PG8_STAGE(PG8_SA(0, 0), a2, voffA);
;             PG8_BAR; PG8_WAIT_L(0); PG8_MMA(1, 0, At, B0); PG8_BAR; PG8_SCHED;
;             PG8_STAGE(PG8_SB(0, 1), b2 + hstep, voffB);
;             PG8_WAIT_V(6); PG8_BAR; PG8_MMA(1, 1, At, B1); PG8_BAR;
;             PG8_LDB(B0, 1, 0); PG8_SCHED; PG8_LDA(At, 1, 0); PG8_STAGE(PG8_SA(0, 1), a2 + hstep, voffA);
;             PG8_WAIT_L(8); PG8_BAR; PG8_WAIT_L(0); PG8_MMA(0, 0, At, B0); PG8_BAR; PG8_SCHED;
;             PG8_LDB(B1, 1, 1); PG8_STAGE(PG8_SB(1, 0), b3, voffB);
;             PG8_BAR; PG8_WAIT_L(0); PG8_MMA(0, 1, At, B1); PG8_BAR;
;             PG8_LDA(At, 1, 1); PG8_STAGE(PG8_SA(1, 0), a3, voffA);
;             PG8_BAR; PG8_WAIT_L(0); PG8_MMA(1, 0, At, B0); PG8_BAR; PG8_SCHED;
;             PG8_STAGE(PG8_SB(1, 1), b3 + hstep, voffB);
;             PG8_WAIT_V(6); PG8_BAR; PG8_MMA(1, 1, At, B1); PG8_BAR;
;             }
;         }
;         if constexpr (ALIGN_EPI) { if (wr == 0) PG8_BAR; }
	s_add_i32 s36, s64, s40
	v_lshl_add_u64 v[148:149], v[148:149], 0, s[16:17]
	s_mov_b32 m0, s36
	ds_read_b128 v[184:187], v154 offset:49152
	ds_read_b128 v[188:191], v154 offset:50176
	ds_read_b128 v[192:195], v154 offset:51200
	ds_read_b128 v[198:201], v154 offset:52224
	ds_read_b128 v[202:205], v154 offset:53248
	ds_read_b128 v[206:209], v154 offset:54272
	ds_read_b128 v[210:213], v154 offset:55296
	ds_read_b128 v[214:217], v154 offset:56320
	global_load_lds_dwordx4 v[148:149], off
	s_add_i32 m0, s36, 0x2000
	s_add_u32 s34, s34, 0x80080
	v_lshl_add_u64 v[148:149], v[218:219], 0, s[16:17]
	s_addc_u32 s35, s35, 0
	s_add_i32 s36, s65, s40
	global_load_lds_dwordx4 v[148:149], off
	v_lshl_add_u64 v[148:149], s[34:35], 0, v[132:133]
	s_mov_b32 m0, s36
	s_nop 0
	global_load_lds_dwordx4 v[148:149], off
	v_lshl_add_u64 v[148:149], s[34:35], 0, v[128:129]
	s_add_i32 m0, s36, 0x2000
	s_nop 0
	global_load_lds_dwordx4 v[148:149], off
	v_lshl_add_u64 v[148:149], v[220:221], 0, s[16:17]
	s_mov_b32 m0, s48
	s_nop 0
	global_load_lds_dwordx4 v[148:149], off
	v_lshl_add_u64 v[148:149], v[222:223], 0, s[16:17]
	s_mov_b32 m0, s49
	s_nop 0
	global_load_lds_dwordx4 v[148:149], off
	s_waitcnt vmcnt(8)
	s_waitcnt lgkmcnt(0)
	s_barrier
	s_setprio 1
	s_waitcnt lgkmcnt(0)
	v_mfma_f32_16x16x32_bf16 v[60:63], v[144:147], v[184:187], v[60:63]
	v_mfma_f32_16x16x32_bf16 v[56:59], v[160:163], v[184:187], v[56:59]
	v_mfma_f32_16x16x32_bf16 v[44:47], v[144:147], v[192:195], v[44:47]
	v_mfma_f32_16x16x32_bf16 v[40:43], v[160:163], v[192:195], v[40:43]
	v_mfma_f32_16x16x32_bf16 v[28:31], v[144:147], v[202:205], v[28:31]
	v_mfma_f32_16x16x32_bf16 v[24:27], v[160:163], v[202:205], v[24:27]
	v_mfma_f32_16x16x32_bf16 v[12:15], v[144:147], v[210:213], v[12:15]
	v_mfma_f32_16x16x32_bf16 v[8:11], v[160:163], v[210:213], v[8:11]
	v_mfma_f32_16x16x32_bf16 v[60:63], v[156:159], v[188:191], v[60:63]
	v_mfma_f32_16x16x32_bf16 v[56:59], v[164:167], v[188:191], v[56:59]
	v_mfma_f32_16x16x32_bf16 v[44:47], v[156:159], v[198:201], v[44:47]
	v_mfma_f32_16x16x32_bf16 v[40:43], v[164:167], v[198:201], v[40:43]
	v_mfma_f32_16x16x32_bf16 v[28:31], v[156:159], v[206:209], v[28:31]
	v_mfma_f32_16x16x32_bf16 v[24:27], v[164:167], v[206:209], v[24:27]
	v_mfma_f32_16x16x32_bf16 v[12:15], v[156:159], v[214:217], v[12:15]
	v_mfma_f32_16x16x32_bf16 v[8:11], v[164:167], v[214:217], v[8:11]
	v_mfma_f32_16x16x32_bf16 v[52:55], v[168:171], v[184:187], v[52:55]
	v_mfma_f32_16x16x32_bf16 v[48:51], v[176:179], v[184:187], v[48:51]
	v_mfma_f32_16x16x32_bf16 v[36:39], v[168:171], v[192:195], v[36:39]
	v_mfma_f32_16x16x32_bf16 v[32:35], v[176:179], v[192:195], v[32:35]
	v_mfma_f32_16x16x32_bf16 v[20:23], v[168:171], v[202:205], v[20:23]
	v_mfma_f32_16x16x32_bf16 v[16:19], v[176:179], v[202:205], v[16:19]
	v_mfma_f32_16x16x32_bf16 v[4:7], v[168:171], v[210:213], v[4:7]
	v_mfma_f32_16x16x32_bf16 v[0:3], v[176:179], v[210:213], v[0:3]
	v_mfma_f32_16x16x32_bf16 v[52:55], v[172:175], v[188:191], v[52:55]
	v_mfma_f32_16x16x32_bf16 v[48:51], v[180:183], v[188:191], v[48:51]
	v_mfma_f32_16x16x32_bf16 v[36:39], v[172:175], v[198:201], v[36:39]
	v_mfma_f32_16x16x32_bf16 v[32:35], v[180:183], v[198:201], v[32:35]
	v_mfma_f32_16x16x32_bf16 v[20:23], v[172:175], v[206:209], v[20:23]
	v_mfma_f32_16x16x32_bf16 v[16:19], v[180:183], v[206:209], v[16:19]
	v_mfma_f32_16x16x32_bf16 v[4:7], v[172:175], v[214:217], v[4:7]
	v_mfma_f32_16x16x32_bf16 v[0:3], v[180:183], v[214:217], v[0:3]
	s_setprio 0
	s_barrier
	s_add_i32 s63, s63, 2
	s_add_u32 s61, s61, 0x100
	s_addc_u32 s62, s62, 0
	s_add_u32 s30, s30, 0x100
	s_addc_u32 s31, s31, 0
	s_cmp_gt_u32 s63, 29
	s_cbranch_scc0 .LBB0_767
	s_and_b64 vcc, exec, s[18:19]
	s_cbranch_vccz .LBB0_770
	s_barrier

; #define LAS __attribute__((address_space(3)))
; __device__ __forceinline__ f32x4 mfma16(bf16x8 a, bf16x8 b, f32x4 c) { return __builtin_amdgcn_mfma_f32_16x16x32_bf16(a, b, c, 0, 0, 0); }
; template <int MODE>
; __device__ __forceinline__ void nsa_soft(f32x4 (&st)[4], const float (&Bl)[16], float cl, bool fast, int keybase, int t, bool sel, float& m2, float& l, f32x4 (&o)[4], float lfin, LAS float* imp, int lane) {
;     ...
;     for (int tau = 0; tau < 4; ++tau)
; #pragma unroll
;         for (int r = 0; r < 4; ++r) st[tau][r] = __builtin_fmaf(st[tau][r], LOG2E, Bl[tau * 4 + r]);
;     if (!fast) {
; #pragma unroll
;         for (int tau = 0; tau < 4; ++tau)
; #pragma unroll
;             for (int r = 0; r < 4; ++r) { const int off = keybase + 32 * (tau >> 1) + 8 * kg + 4 * (tau & 1) + r;
;                 int dist; bool valid;
;                 if (MODE <= 1) { dist = t - (16 * off + 31); valid = dist >= 0; }
;                 else if (MODE == 2) { dist = t - off; valid = sel && dist >= 0; }
;                 else { dist = t - off; valid = dist >= 0 && dist < 512; }
;                 st[tau][r] = valid ? st[tau][r] : -INFINITY; }
; template <int MODE> ...
;     ...
;       for (int tau = 0; tau < 4; ++tau) { const LAS bf16* rp = kt + (16 * tau + rho) * KT_LD + dof;
;           const bf16x8 k0 = *(const LAS bf16x8*)(rp), k1 = *(const LAS bf16x8*)(rp + 32);
; #pragma unroll
;           for (int s = 0; s < 2; ++s) { st[s][tau] = (f32x4){0.f, 0.f, 0.f, 0.f}; st[s][tau] = mfma16(k0, qf[s][0], st[s][tau]); st[s][tau] = mfma16(k1, qf[s][1], st[s][tau]); } } }
.LBB0_907:
	s_bitcmp1_b32 s44, 0
	s_cselect_b32 s40, 0x4800, 0
	v_add_u32_e32 v53, s40, v215
	v_add_u32_e32 v62, v53, v204
	ds_read_b128 v[28:31], v62
	ds_read_b128 v[32:35], v62 offset:64
	v_add_u32_e32 v53, v53, v205
	s_cmp_gt_i32 s45, s4
	s_cselect_b64 s[40:41], -1, 0
	s_waitcnt lgkmcnt(0)
	v_mfma_f32_16x16x32_bf16 v[36:39], v[28:31], v[0:3], 0
	s_cmp_le_i32 s45, s4
	v_mfma_f32_16x16x32_bf16 v[28:31], v[28:31], v[8:11], 0
	v_mfma_f32_16x16x32_bf16 v[40:43], v[32:35], v[4:7], v[36:39]
	s_nop 4
	ds_read_b128 v[36:39], v62 offset:2304
	v_mfma_f32_16x16x32_bf16 v[28:31], v[32:35], v[12:15], v[28:31]
	ds_read_b128 v[32:35], v62 offset:2368
	ds_read_b128 v[58:61], v62 offset:4608
	ds_read_b128 v[62:65], v62 offset:4672
	ds_read_b128 v[70:73], v53
	ds_read_b128 v[74:77], v53 offset:64
	s_waitcnt lgkmcnt(5)
	v_mfma_f32_16x16x32_bf16 v[54:57], v[36:39], v[0:3], 0
	v_add_u32_e32 v53, s45, v210
	v_add_u32_e32 v66, 0xfffffbf1, v53
	v_or_b32_e32 v177, 47, v66
	v_mfma_f32_16x16x32_bf16 v[36:39], v[36:39], v[8:11], 0
	v_or_b32_e32 v180, 31, v66
	v_or_b32_e32 v176, 0x4f, v66
	v_or_b32_e32 v179, 63, v66
	s_waitcnt lgkmcnt(4)
	v_mfma_f32_16x16x32_bf16 v[54:57], v[32:35], v[4:7], v[54:57]
	v_or_b32_e32 v163, 0x6f, v66
	v_or_b32_e32 v178, 0x5f, v66
	v_or_b32_e32 v157, 0x22f, v66
	v_mfma_f32_16x16x32_bf16 v[32:35], v[32:35], v[12:15], v[36:39]
	v_or_b32_e32 v175, 0x21f, v66
	v_or_b32_e32 v156, 0x24f, v66
	v_or_b32_e32 v165, 0x23f, v66
	s_waitcnt lgkmcnt(3)
	v_mfma_f32_16x16x32_bf16 v[36:39], v[58:61], v[0:3], 0
	v_or_b32_e32 v149, 0x26f, v66
	v_or_b32_e32 v158, 0x25f, v66
	v_pk_fma_f32 v[68:69], v[40:41], s[22:23], v[80:81] op_sel_hi:[1,0,1]
	s_waitcnt lgkmcnt(2)
	v_mfma_f32_16x16x32_bf16 v[182:185], v[62:65], v[4:7], v[36:39]
	v_fma_f32 v66, v42, s22, v82
	v_fma_f32 v67, v43, s22, v83
	v_add_u32_e32 v174, 0xfffffc70, v53
	v_add_u32_e32 v159, 0xfffffc80, v53
	v_mfma_f32_16x16x32_bf16 v[36:39], v[58:61], v[8:11], 0
	v_add_u32_e32 v155, 0xfffffe70, v53
	v_add_u32_e32 v147, 0xfffffe80, v53
	s_waitcnt lgkmcnt(1)
	v_mfma_f32_16x16x32_bf16 v[58:61], v[70:73], v[0:3], 0
	v_mfma_f32_16x16x32_bf16 v[40:43], v[70:73], v[8:11], 0
	s_waitcnt lgkmcnt(0)
	v_mfma_f32_16x16x32_bf16 v[186:189], v[74:77], v[4:7], v[58:61]
	v_mfma_f32_16x16x32_bf16 v[36:39], v[62:65], v[12:15], v[36:39]
	v_fma_f32 v64, v54, s22, v84
	v_fma_f32 v65, v55, s22, v85
	v_pk_fma_f32 v[62:63], v[56:57], s[22:23], v[86:87] op_sel_hi:[1,0,1]
	s_nop 0
	v_pk_fma_f32 v[60:61], v[182:183], s[22:23], v[166:167] op_sel_hi:[1,0,1]
	v_mfma_f32_16x16x32_bf16 v[40:43], v[74:77], v[12:15], v[40:43]
	v_fma_f32 v58, v184, s22, v168
	v_fma_f32 v59, v185, s22, v169
	v_pk_fma_f32 v[56:57], v[186:187], s[22:23], v[170:171] op_sel_hi:[1,0,1]
	v_pk_fma_f32 v[54:55], v[188:189], s[22:23], v[172:173] op_sel_hi:[1,0,1]
	s_cbranch_scc1 .LBB0_909
	v_cmp_ge_i32_e32 vcc, v20, v180
	s_nop 1
	v_cndmask_b32_e32 v68, v225, v68, vcc
	v_cmp_ge_i32_e32 vcc, v21, v177
	s_nop 1
	v_cndmask_b32_e32 v69, v225, v69, vcc
	v_cmp_ge_i32_e32 vcc, v22, v179
	s_nop 1
	v_cndmask_b32_e32 v66, v225, v66, vcc
	v_cmp_ge_i32_e32 vcc, v23, v176
	s_nop 1
	v_cndmask_b32_e32 v67, v225, v67, vcc
	v_cmp_ge_i32_e32 vcc, v162, v178
	s_nop 1
	v_cndmask_b32_e32 v64, v225, v64, vcc
	v_cmp_ge_i32_e32 vcc, v51, v163
	s_nop 1
	v_cndmask_b32_e32 v65, v225, v65, vcc
	v_cmp_ge_i32_e32 vcc, v162, v174
	s_nop 1
	v_cndmask_b32_e32 v62, v225, v62, vcc
	v_cmp_ge_i32_e32 vcc, v162, v159
	s_nop 1
	v_cndmask_b32_e32 v63, v225, v63, vcc
	v_cmp_ge_i32_e32 vcc, v20, v175
	s_nop 1
	v_cndmask_b32_e32 v60, v225, v60, vcc
	v_cmp_ge_i32_e32 vcc, v21, v157
	s_nop 1
	v_cndmask_b32_e32 v61, v225, v61, vcc
	v_cmp_ge_i32_e32 vcc, v22, v165
	s_nop 1
	v_cndmask_b32_e32 v58, v225, v58, vcc
	v_cmp_ge_i32_e32 vcc, v23, v156
	s_nop 1
	v_cndmask_b32_e32 v59, v225, v59, vcc
	v_cmp_ge_i32_e32 vcc, v162, v158
	s_nop 1
	v_cndmask_b32_e32 v56, v225, v56, vcc
	v_cmp_ge_i32_e32 vcc, v51, v149
	s_nop 1
	v_cndmask_b32_e32 v57, v225, v57, vcc
	v_cmp_ge_i32_e32 vcc, v162, v155
	s_nop 1
	v_cndmask_b32_e32 v54, v225, v54, vcc
	v_cmp_ge_i32_e32 vcc, v162, v147
	s_nop 1
	v_cndmask_b32_e32 v55, v225, v55, vcc

; #define DB_GLOAD(SK, SV, kb_) do { SK = *(const v4u*)(kbase + (size_t)((kb_) + srow) * ldk + sch); if (MODE != 0) SV = *(const v4u*)(vbase + (size_t)srow * ldv + (kb_) + sch); } while (0)
; #define DB_LWRITE(SK, SV, buf_) do { LAS unsigned char* nb_ = lds + NSA_TILE0 + (buf_) * NSA_TILE_STRIDE; *(LAS v4u*)((LAS bf16*)nb_ + krow * KT_LD + sch) = SK; if (MODE != 0) *(LAS v4u*)((LAS bf16*)(nb_ + NSA_V_OFF) + srow * KT_LD + sch) = SV; } while (0)
; template <int MODE>
; __device__ __forceinline__ void nsa_soft(f32x4 (&st)[4], const float (&Bl)[16], float cl, bool fast, int keybase, int t, bool sel, float& m2, float& l, f32x4 (&o)[4], float lfin, LAS float* imp, int lane) {
;     ...
;         float mloc = fmaxf(fmaxf(fmaxf(st[0][0], st[0][1]), fmaxf(st[0][2], st[0][3])), fmaxf(fmaxf(st[1][0], st[1][1]), fmaxf(st[1][2], st[1][3])));
;         mloc = fmaxf(mloc, fmaxf(fmaxf(fmaxf(st[2][0], st[2][1]), fmaxf(st[2][2], st[2][3])), fmaxf(fmaxf(st[3][0], st[3][1]), fmaxf(st[3][2], st[3][3]))));
;         mloc = xrow16_max(mloc);
;         const float mnew = fmaxf(m2, mloc + cl); const float alpha = __builtin_amdgcn_exp2f(m2 - mnew); m2 = mnew;
; template <int MODE> ...
;     ...
;     for (int s = 0; s < nst; ++s) {
;         const int kb = kb0 + s * 64;
;         if (s + 1 < nst) DB_GLOAD(skA, svA, kb + 64);
;         DB_COMPUTE(kb, s & 1);
;         if (s + 1 < nst) DB_LWRITE(skA, svA, (s + 1) & 1);
.LBB0_911:
	v_max_f32_e32 v36, v75, v75
	v_max_f32_e32 v37, v74, v74
	v_max_f32_e32 v36, v37, v36
	v_max_f32_e32 v37, v71, v71
	v_max_f32_e32 v38, v70, v70
	v_max_f32_e32 v37, v38, v37
	v_max_f32_e32 v38, v35, v35
	v_max_f32_e32 v39, v34, v34
	v_max_f32_e32 v38, v39, v38
	v_max_f32_e32 v39, v33, v33
	v_max_f32_e32 v40, v32, v32
	v_max_f32_e32 v39, v40, v39
	v_max_f32_e32 v40, v29, v29
	v_max_f32_e32 v41, v28, v28
	v_max_f32_e32 v40, v41, v40
	v_max3_f32 v40, v30, v31, v40
	v_max3_f32 v36, v76, v77, v36
	v_max3_f32 v37, v72, v73, v37
	v_max3_f32 v38, v38, v39, v40
	v_max3_f32 v36, v36, v37, v38
	v_mov_b32_e32 v37, v36
	s_nop 1
	v_permlane16_swap_b32_e32 v36, v37
	v_max_f32_e32 v37, v37, v37
	v_max_f32_e32 v36, v36, v36
	v_max_f32_e32 v36, v36, v37
	v_mov_b32_e32 v37, v36
	s_add_i32 s44, s44, 1
	s_andn2_b64 vcc, exec, s[38:39]
	v_permlane32_swap_b32_e32 v36, v37
	s_cbranch_vccnz .LBB0_913
	s_bitcmp1_b32 s44, 0
	s_cselect_b32 s38, 0x4800, 0
	v_add_u32_e32 v38, s38, v202
	s_waitcnt vmcnt(0)
	ds_write_b128 v38, v[16:19]

; #define LAS __attribute__((address_space(3)))
; __device__ __forceinline__ f32x4 mfma16(bf16x8 a, bf16x8 b, f32x4 c) { return __builtin_amdgcn_mfma_f32_16x16x32_bf16(a, b, c, 0, 0, 0); }
; template <int MODE>
; __device__ __forceinline__ void nsa_soft(f32x4 (&st)[4], const float (&Bl)[16], float cl, bool fast, int keybase, int t, bool sel, float& m2, float& l, f32x4 (&o)[4], float lfin, LAS float* imp, int lane) {
;     ...
;     for (int tau = 0; tau < 4; ++tau)
; #pragma unroll
;         for (int r = 0; r < 4; ++r) st[tau][r] = __builtin_fmaf(st[tau][r], LOG2E, Bl[tau * 4 + r]);
;     if (!fast) {
; #pragma unroll
;         for (int tau = 0; tau < 4; ++tau)
; #pragma unroll
;             for (int r = 0; r < 4; ++r) { const int off = keybase + 32 * (tau >> 1) + 8 * kg + 4 * (tau & 1) + r;
;                 int dist; bool valid;
;                 if (MODE <= 1) { dist = t - (16 * off + 31); valid = dist >= 0; }
;                 else if (MODE == 2) { dist = t - off; valid = sel && dist >= 0; }
;                 else { dist = t - off; valid = dist >= 0 && dist < 512; }
;                 st[tau][r] = valid ? st[tau][r] : -INFINITY; }
; template <int MODE> ...
;     ...
;       for (int tau = 0; tau < 4; ++tau) { const LAS bf16* rp = kt + (16 * tau + rho) * KT_LD + dof;
;           const bf16x8 k0 = *(const LAS bf16x8*)(rp), k1 = *(const LAS bf16x8*)(rp + 32);
; #pragma unroll
;           for (int s = 0; s < 2; ++s) { st[s][tau] = (f32x4){0.f, 0.f, 0.f, 0.f}; st[s][tau] = mfma16(k0, qf[s][0], st[s][tau]); st[s][tau] = mfma16(k1, qf[s][1], st[s][tau]); } } }
.LBB0_923:
	s_bitcmp1_b32 s49, 0
	s_cselect_b32 s10, 0x4800, 0
	v_add_u32_e32 v190, s10, v215
	v_add_u32_e32 v195, v190, v204
	ds_read_b128 v[64:67], v195
	ds_read_b128 v[68:71], v195 offset:64
	v_add_u32_e32 v226, v190, v205
	s_cmp_gt_i32 s48, s4
	s_cselect_b64 s[40:41], -1, 0
	s_waitcnt lgkmcnt(0)
	v_mfma_f32_16x16x32_bf16 v[72:75], v[64:67], v[0:3], 0
	s_cmp_le_i32 s48, s4
	v_mfma_f32_16x16x32_bf16 v[64:67], v[64:67], v[8:11], 0
	v_mfma_f32_16x16x32_bf16 v[178:181], v[68:71], v[4:7], v[72:75]
	v_mfma_f32_16x16x32_bf16 v[64:67], v[68:71], v[12:15], v[64:67]
	ds_read_b128 v[68:71], v195 offset:2304
	s_nop 2
	ds_read_b128 v[72:75], v195 offset:2368
	s_waitcnt lgkmcnt(1)
	v_mfma_f32_16x16x32_bf16 v[76:79], v[68:71], v[0:3], 0
	v_mfma_f32_16x16x32_bf16 v[68:71], v[68:71], v[8:11], 0
	s_waitcnt lgkmcnt(0)
	v_mfma_f32_16x16x32_bf16 v[182:185], v[72:75], v[4:7], v[76:79]
	v_mfma_f32_16x16x32_bf16 v[68:71], v[72:75], v[12:15], v[68:71]
	ds_read_b128 v[72:75], v195 offset:4608
	s_nop 2
	ds_read_b128 v[76:79], v195 offset:4672
	s_waitcnt lgkmcnt(1)
	v_mfma_f32_16x16x32_bf16 v[186:189], v[72:75], v[0:3], 0
	v_mfma_f32_16x16x32_bf16 v[72:75], v[72:75], v[8:11], 0
	s_waitcnt lgkmcnt(0)
	v_mfma_f32_16x16x32_bf16 v[228:231], v[76:79], v[4:7], v[186:189]
	v_mfma_f32_16x16x32_bf16 v[72:75], v[76:79], v[12:15], v[72:75]
	ds_read_b128 v[76:79], v226
	s_nop 2
	ds_read_b128 v[186:189], v226 offset:64
	s_waitcnt lgkmcnt(1)
	v_mfma_f32_16x16x32_bf16 v[190:193], v[76:79], v[0:3], 0
	v_mfma_f32_16x16x32_bf16 v[76:79], v[76:79], v[8:11], 0
	s_waitcnt lgkmcnt(0)
	v_mfma_f32_16x16x32_bf16 v[248:251], v[186:189], v[4:7], v[190:193]
	v_mfma_f32_16x16x32_bf16 v[76:79], v[186:189], v[12:15], v[76:79]
	v_add_u32_e32 v186, s48, v210
	v_add_u32_e32 v187, 0xfffffbf1, v186
	v_or_b32_e32 v232, 47, v187
	v_or_b32_e32 v237, 31, v187
	v_or_b32_e32 v234, 0x4f, v187
	v_or_b32_e32 v240, 63, v187
	v_or_b32_e32 v233, 0x6f, v187
	v_or_b32_e32 v243, 0x5f, v187
	v_add_u32_e32 v235, 0xfffffc80, v186
	v_add_u32_e32 v241, 0xfffffc70, v186
	v_or_b32_e32 v238, 0x22f, v187
	v_or_b32_e32 v244, 0x21f, v187
	v_or_b32_e32 v236, 0x24f, v187
	v_or_b32_e32 v246, 0x23f, v187
	v_or_b32_e32 v239, 0x26f, v187
	v_or_b32_e32 v245, 0x25f, v187
	v_add_u32_e32 v242, 0xfffffe80, v186
	v_add_u32_e32 v247, 0xfffffe70, v186
	v_pk_fma_f32 v[190:191], v[178:179], s[22:23], v[80:81] op_sel_hi:[1,0,1]
	v_pk_fma_f32 v[192:193], v[180:181], s[22:23], v[82:83] op_sel_hi:[1,0,1]
	v_pk_fma_f32 v[188:189], v[182:183], s[22:23], v[84:85] op_sel_hi:[1,0,1]
	v_pk_fma_f32 v[186:187], v[184:185], s[22:23], v[86:87] op_sel_hi:[1,0,1]
	v_pk_fma_f32 v[184:185], v[228:229], s[22:23], v[166:167] op_sel_hi:[1,0,1]
	v_pk_fma_f32 v[182:183], v[230:231], s[22:23], v[168:169] op_sel_hi:[1,0,1]
	v_pk_fma_f32 v[180:181], v[248:249], s[22:23], v[170:171] op_sel_hi:[1,0,1]
	v_pk_fma_f32 v[178:179], v[250:251], s[22:23], v[172:173] op_sel_hi:[1,0,1]
	s_cbranch_scc1 .LBB0_925
	v_cmp_ge_i32_e32 vcc, v56, v237
	s_nop 1
	v_cndmask_b32_e32 v190, v225, v190, vcc
	v_cmp_ge_i32_e32 vcc, v57, v232
	s_nop 1
	v_cndmask_b32_e32 v191, v225, v191, vcc
	v_cmp_ge_i32_e32 vcc, v58, v240
	s_nop 1
	v_cndmask_b32_e32 v192, v225, v192, vcc
	v_cmp_ge_i32_e32 vcc, v59, v234
	s_nop 1
	v_cndmask_b32_e32 v193, v225, v193, vcc
	v_cmp_ge_i32_e32 vcc, v162, v243
	s_nop 1
	v_cndmask_b32_e32 v188, v225, v188, vcc
	v_cmp_ge_i32_e32 vcc, v147, v233
	s_nop 1
	v_cndmask_b32_e32 v189, v225, v189, vcc
	v_cmp_ge_i32_e32 vcc, v162, v241
	s_nop 1
	v_cndmask_b32_e32 v186, v225, v186, vcc
	v_cmp_ge_i32_e32 vcc, v147, v235
	s_nop 1
	v_cndmask_b32_e32 v187, v225, v187, vcc
	v_cmp_ge_i32_e32 vcc, v56, v244
	s_nop 1
	v_cndmask_b32_e32 v184, v225, v184, vcc
	v_cmp_ge_i32_e32 vcc, v57, v238
	s_nop 1
	v_cndmask_b32_e32 v185, v225, v185, vcc
	v_cmp_ge_i32_e32 vcc, v58, v246
	s_nop 1
	v_cndmask_b32_e32 v182, v225, v182, vcc
	v_cmp_ge_i32_e32 vcc, v59, v236
	s_nop 1
	v_cndmask_b32_e32 v183, v225, v183, vcc
	v_cmp_ge_i32_e32 vcc, v162, v245
	s_nop 1
	v_cndmask_b32_e32 v180, v225, v180, vcc
	v_cmp_ge_i32_e32 vcc, v147, v239
	s_nop 1
	v_cndmask_b32_e32 v181, v225, v181, vcc
	v_cmp_ge_i32_e32 vcc, v162, v247
	s_nop 1
	v_cndmask_b32_e32 v178, v225, v178, vcc
	v_cmp_ge_i32_e32 vcc, v147, v242
	s_nop 1
	v_cndmask_b32_e32 v179, v225, v179, vcc

; #define LAS __attribute__((address_space(3)))
; __device__ __forceinline__ f32x4 mfma16(bf16x8 a, bf16x8 b, f32x4 c) { return __builtin_amdgcn_mfma_f32_16x16x32_bf16(a, b, c, 0, 0, 0); }
; #define BAR_LDS() do { asm volatile("s_waitcnt lgkmcnt(0)" ::: "memory"); __builtin_amdgcn_s_barrier(); asm volatile("" ::: "memory"); } while (0)
; #define DB_GLOAD(SK, SV, kb_) do { SK = *(const v4u*)(kbase + (size_t)((kb_) + srow) * ldk + sch); if (MODE != 0) SV = *(const v4u*)(vbase + (size_t)srow * ldv + (kb_) + sch); } while (0)
; #define DB_LWRITE(SK, SV, buf_) do { LAS unsigned char* nb_ = lds + NSA_TILE0 + (buf_) * NSA_TILE_STRIDE; *(LAS v4u*)((LAS bf16*)nb_ + krow * KT_LD + sch) = SK; if (MODE != 0) *(LAS v4u*)((LAS bf16*)(nb_ + NSA_V_OFF) + srow * KT_LD + sch) = SV; } while (0)
; template <int MODE> ...
;     ...
;     if (MODE != 0) {
;         bf16x8 pb[2][2];
; #pragma unroll
;         for (int s = 0; s < 2; ++s) { pb[s][0] = pack_p(st[s][0], st[s][1]); pb[s][1] = pack_p(st[s][2], st[s][3]); }
; #pragma unroll
;         for (int dt = 0; dt < 4; ++dt) { const LAS bf16* vp = vt + (dt * 16 + (lane & 15)) * KT_LD + 8 * kg;
;             const bf16x8 v0 = *(const LAS bf16x8*)(vp), v1 = *(const LAS bf16x8*)(vp + 32);
; #pragma unroll
;             for (int s = 0; s < 2; ++s) { o[s][dt] = mfma16(v0, pb[s][0], o[s][dt]); o[s][dt] = mfma16(v1, pb[s][1], o[s][dt]); } }
;     }
; template <int MODE> ...
;     ...
;     for (int s = 0; s < nst; ++s) {
;         const int kb = kb0 + s * 64;
;         if (s + 1 < nst) DB_GLOAD(skA, svA, kb + 64);
;         DB_COMPUTE(kb, s & 1);
;         if (s + 1 < nst) DB_LWRITE(skA, svA, (s + 1) & 1);
;         BAR_LDS();
.LBB0_951:
	s_or_b64 exec, exec, s[10:11]
	v_cvt_pk_bf16_f32 v180, v190, v227
	v_cvt_pk_bf16_f32 v181, v191, v192
	v_cvt_pk_bf16_f32 v182, v188, v189
	v_cvt_pk_bf16_f32 v183, v186, v187
	v_cvt_pk_bf16_f32 v184, v228, v230
	v_cvt_pk_bf16_f32 v185, v229, v231
	v_cvt_pk_bf16_f32 v186, v248, v250
	v_cvt_pk_bf16_f32 v187, v249, v251
	v_cvt_pk_bf16_f32 v74, v73, v74
	v_cvt_pk_bf16_f32 v75, v72, v75
	v_cvt_pk_bf16_f32 v76, v76, v78
	v_cvt_pk_bf16_f32 v77, v77, v79
	v_cvt_pk_bf16_f32 v70, v70, v71
	v_cvt_pk_bf16_f32 v71, v68, v69
	v_cvt_pk_bf16_f32 v72, v64, v178
	v_cvt_pk_bf16_f32 v73, v65, v66
	ds_read_b128 v[64:67], v195 offset:9216
	ds_read_b128 v[188:191], v195 offset:9280
	s_waitcnt lgkmcnt(1)
	v_mfma_f32_16x16x32_bf16 v[44:47], v[64:67], v[180:183], v[44:47]
	s_add_i32 s49, s49, 1
	s_andn2_b64 vcc, exec, s[38:39]
	v_mfma_f32_16x16x32_bf16 v[40:43], v[64:67], v[74:77], v[40:43]
	ds_read_b128 v[64:67], v195 offset:11520
	s_waitcnt lgkmcnt(1)
	v_mfma_f32_16x16x32_bf16 v[44:47], v[188:191], v[184:187], v[44:47]
	v_mfma_f32_16x16x32_bf16 v[40:43], v[188:191], v[70:73], v[40:43]
	ds_read_b128 v[188:191], v195 offset:11584
	s_waitcnt lgkmcnt(1)
	v_mfma_f32_16x16x32_bf16 v[36:39], v[64:67], v[180:183], v[36:39]
	v_mfma_f32_16x16x32_bf16 v[28:31], v[64:67], v[74:77], v[28:31]
	ds_read_b128 v[64:67], v195 offset:13824
	s_waitcnt lgkmcnt(1)
	v_mfma_f32_16x16x32_bf16 v[36:39], v[188:191], v[184:187], v[36:39]
	v_mfma_f32_16x16x32_bf16 v[28:31], v[188:191], v[70:73], v[28:31]
	ds_read_b128 v[188:191], v195 offset:13888
	s_waitcnt lgkmcnt(1)
	v_mfma_f32_16x16x32_bf16 v[32:35], v[64:67], v[180:183], v[32:35]
	v_mfma_f32_16x16x32_bf16 v[20:23], v[64:67], v[74:77], v[20:23]
	ds_read_b128 v[64:67], v226 offset:9216
	s_waitcnt lgkmcnt(1)
	v_mfma_f32_16x16x32_bf16 v[32:35], v[188:191], v[184:187], v[32:35]
	v_mfma_f32_16x16x32_bf16 v[20:23], v[188:191], v[70:73], v[20:23]
	ds_read_b128 v[188:191], v226 offset:9280
	s_waitcnt lgkmcnt(1)
	v_mfma_f32_16x16x32_bf16 v[24:27], v[64:67], v[180:183], v[24:27]
	v_mfma_f32_16x16x32_bf16 v[16:19], v[64:67], v[74:77], v[16:19]
	s_waitcnt lgkmcnt(0)
	v_mfma_f32_16x16x32_bf16 v[24:27], v[188:191], v[184:187], v[24:27]
	v_mfma_f32_16x16x32_bf16 v[16:19], v[188:191], v[70:73], v[16:19]
	s_cbranch_vccnz .LBB0_920
	s_bitcmp1_b32 s49, 0
	s_cselect_b32 s10, 0x4800, 0
	s_add_i32 s10, s10, 0
	s_add_i32 s10, s10, 0x10800
	v_add3_u32 v65, s10, v201, v92
	v_add3_u32 v64, s10, v206, v92
	s_waitcnt vmcnt(0)
	ds_write_b128 v65, v[48:51]
	ds_write_b128 v64, v[52:55] offset:9216
	s_branch .LBB0_920

; #define PG8_STAGE(bufoff, gbase, voff) do { _Pragma("unroll") for (int _i = 0; _i < 2; ++_i) \
;         __builtin_amdgcn_global_load_lds((const unsigned*)((const char*)(gbase) + (voff)[_i]), (PG8_LAS unsigned*)(lds + (bufoff) + ldsw + _i * 8192), 16, 0, 0); } while (0)
; #define PG8_LDA(dst, b, h) do { _Pragma("unroll") for (int m = 0; m < 4; ++m) _Pragma("unroll") for (int k = 0; k < 2; ++k) dst[m][k] = *(const PG8_LAS bf16x8*)(lds + PG8_SA(b, h) + aoff + m * 2048 + k * 1024); } while (0)
; #define PG8_LDB(dst, b, h) do { _Pragma("unroll") for (int n = 0; n < 2; ++n) _Pragma("unroll") for (int k = 0; k < 2; ++k) dst[n][k] = *(const PG8_LAS bf16x8*)(lds + PG8_SB(b, h) + boff + n * 2048 + k * 1024); } while (0)
; #define PG8_MMA(ai, bj, At, Bt) do { __builtin_amdgcn_s_setprio(1); _Pragma("unroll") for (int m = 0; m < 4; ++m) _Pragma("unroll") for (int n = 0; n < 2; ++n) _Pragma("unroll") for (int k = 0; k < 2; ++k) \
;         acc[ai][bj][m][n] = __builtin_amdgcn_mfma_f32_16x16x32_bf16(Bt[n][k], At[m][k], acc[ai][bj][m][n], 0, 0, 0); __builtin_amdgcn_s_setprio(0); } while (0)
; #define PG8_WAIT_V(n) asm volatile("s_waitcnt vmcnt(" #n ")" ::: "memory")
; #define PG8_BAR __builtin_amdgcn_s_barrier()
; template <class Epi, class Sched, bool ALIGN_EPI = false, bool SP2 = false>
; __device__ __forceinline__ void gemm_phase(PG8_LAS unsigned char* lds, const Gemm g, const Sched& S, const Epi& E) {
;     ...
;         for (int t = 0; t < nt; t += 2) {
;             const bool last = (t == nt - 2);
;             const char* a1 = cA + (size_t)(t + 1) * kstep;
;             const char* a2 = last ? nA : cA + (size_t)(t + 2) * kstep; const char* b2 = last ? nB : cB + (size_t)(t + 2) * kstep;
;             const char* a3 = a2 + kstep; const char* b3 = b2 + kstep;
;             if (last && has_next) S.a_ready(nxt);
;             if constexpr (SP2) {
;             PG8_LDB(B0, 0, 0); PG8_LDB(B1, 0, 1); PG8_SCHED; PG8_LDA(At, 0, 0); PG8_STAGE(PG8_SA(1, 1), a1 + hstep, voffA);
;             PG8_WAIT_V(8); PG8_WAIT_L(0); PG8_BAR; PG8_MMA(0, 0, At, B0); PG8_MMA(0, 1, At, B1); PG8_BAR; PG8_SCHED;
;             PG8_LDA(At, 0, 1); PG8_STAGE(PG8_SB(0, 0), b2, voffB); PG8_STAGE(PG8_SB(0, 1), b2 + hstep, voffB); PG8_STAGE(PG8_SA(0, 0), a2, voffA);
;             PG8_WAIT_V(8); PG8_WAIT_L(0); PG8_BAR; PG8_MMA(1, 0, At, B0); PG8_MMA(1, 1, At, B1); PG8_BAR; PG8_SCHED;
.LBB0_1138:
	ds_read_b128 v[140:143], v147
	ds_read_b128 v[150:153], v147 offset:1024
	ds_read_b128 v[154:157], v147 offset:2048
	ds_read_b128 v[158:161], v147 offset:3072
	ds_read_b128 v[162:165], v148
	ds_read_b128 v[166:169], v148 offset:1024
	ds_read_b128 v[170:173], v148 offset:2048
	ds_read_b128 v[174:177], v148 offset:3072
	s_add_u32 s34, s30, 0xfff80080
	s_addc_u32 s35, s31, -1
	s_cmp_eq_u32 s55, 28
	s_cselect_b32 s37, s23, s35
	s_cselect_b32 s36, s51, s34
	s_cselect_b32 s35, s21, s54
	s_cselect_b32 s34, s52, s53
	v_lshl_add_u64 v[194:195], s[30:31], 0, v[134:135]
	s_add_i32 m0, s29, 0xc000
	ds_read_b128 v[178:181], v149
	ds_read_b128 v[182:185], v149 offset:1024
	ds_read_b128 v[186:189], v149 offset:2048
	ds_read_b128 v[190:193], v149 offset:3072
	ds_read_b128 v[198:201], v149 offset:4096
	ds_read_b128 v[202:205], v149 offset:5120
	ds_read_b128 v[206:209], v149 offset:6144
	ds_read_b128 v[210:213], v149 offset:7168
	global_load_lds_dwordx4 v[194:195], off
	v_lshl_add_u64 v[194:195], s[30:31], 0, v[132:133]
	s_add_i32 m0, s29, 0xe000
	s_nop 0
	global_load_lds_dwordx4 v[194:195], off
	s_waitcnt vmcnt(8)
	s_waitcnt lgkmcnt(0)
	s_barrier
	s_setprio 1
	s_waitcnt lgkmcnt(0)
	v_mfma_f32_16x16x32_bf16 v[124:127], v[140:143], v[178:181], v[124:127]
	v_mfma_f32_16x16x32_bf16 v[120:123], v[154:157], v[178:181], v[120:123]
	v_mfma_f32_16x16x32_bf16 v[112:115], v[140:143], v[186:189], v[112:115]
	v_mfma_f32_16x16x32_bf16 v[108:111], v[154:157], v[186:189], v[108:111]
	v_mfma_f32_16x16x32_bf16 v[96:99], v[140:143], v[198:201], v[96:99]
	v_mfma_f32_16x16x32_bf16 v[92:95], v[154:157], v[198:201], v[92:95]
	v_mfma_f32_16x16x32_bf16 v[80:83], v[140:143], v[206:209], v[80:83]
	v_mfma_f32_16x16x32_bf16 v[76:79], v[154:157], v[206:209], v[76:79]
	v_mfma_f32_16x16x32_bf16 v[124:127], v[150:153], v[182:185], v[124:127]
	v_mfma_f32_16x16x32_bf16 v[120:123], v[158:161], v[182:185], v[120:123]
	v_mfma_f32_16x16x32_bf16 v[112:115], v[150:153], v[190:193], v[112:115]
	v_mfma_f32_16x16x32_bf16 v[108:111], v[158:161], v[190:193], v[108:111]
	v_mfma_f32_16x16x32_bf16 v[96:99], v[150:153], v[202:205], v[96:99]
	v_mfma_f32_16x16x32_bf16 v[92:95], v[158:161], v[202:205], v[92:95]
	v_mfma_f32_16x16x32_bf16 v[80:83], v[150:153], v[210:213], v[80:83]
	v_mfma_f32_16x16x32_bf16 v[76:79], v[158:161], v[210:213], v[76:79]
	v_mfma_f32_16x16x32_bf16 v[116:119], v[162:165], v[178:181], v[116:119]
	v_mfma_f32_16x16x32_bf16 v[104:107], v[170:173], v[178:181], v[104:107]
	v_mfma_f32_16x16x32_bf16 v[100:103], v[162:165], v[186:189], v[100:103]
	v_mfma_f32_16x16x32_bf16 v[88:91], v[170:173], v[186:189], v[88:91]
	v_mfma_f32_16x16x32_bf16 v[84:87], v[162:165], v[198:201], v[84:87]
	v_mfma_f32_16x16x32_bf16 v[72:75], v[170:173], v[198:201], v[72:75]
	v_mfma_f32_16x16x32_bf16 v[68:71], v[162:165], v[206:209], v[68:71]
	v_mfma_f32_16x16x32_bf16 v[64:67], v[170:173], v[206:209], v[64:67]
	v_mfma_f32_16x16x32_bf16 v[116:119], v[166:169], v[182:185], v[116:119]
	v_mfma_f32_16x16x32_bf16 v[104:107], v[174:177], v[182:185], v[104:107]
	v_mfma_f32_16x16x32_bf16 v[100:103], v[166:169], v[190:193], v[100:103]
	v_mfma_f32_16x16x32_bf16 v[88:91], v[174:177], v[190:193], v[88:91]
	v_mfma_f32_16x16x32_bf16 v[84:87], v[166:169], v[202:205], v[84:87]
	v_mfma_f32_16x16x32_bf16 v[72:75], v[174:177], v[202:205], v[72:75]
	v_mfma_f32_16x16x32_bf16 v[68:71], v[166:169], v[210:213], v[68:71]
	v_mfma_f32_16x16x32_bf16 v[64:67], v[174:177], v[210:213], v[64:67]
	s_setprio 0
	s_barrier
	s_add_i32 s56, s48, s40
	v_lshl_add_u64 v[194:195], s[34:35], 0, v[128:129]
	s_mov_b32 m0, s56
	ds_read_b128 v[178:181], v149 offset:16384
	ds_read_b128 v[182:185], v149 offset:17408
	ds_read_b128 v[186:189], v149 offset:18432
	ds_read_b128 v[190:193], v149 offset:19456
	ds_read_b128 v[198:201], v149 offset:20480
	ds_read_b128 v[202:205], v149 offset:21504
	ds_read_b128 v[206:209], v149 offset:22528
	ds_read_b128 v[210:213], v149 offset:23552
	global_load_lds_dwordx4 v[194:195], off
	s_add_i32 m0, s56, 0x2000
	s_add_u32 s56, s34, 0x80000
	v_lshl_add_u64 v[214:215], s[34:35], 0, v[130:131]
	s_addc_u32 s57, s35, 0
	s_add_i32 s58, s49, s40
	global_load_lds_dwordx4 v[214:215], off
	v_lshl_add_u64 v[216:217], s[56:57], 0, v[128:129]
	s_mov_b32 m0, s58
	v_lshl_add_u64 v[218:219], s[36:37], 0, v[130:131]
	global_load_lds_dwordx4 v[216:217], off
	v_lshl_add_u64 v[216:217], s[56:57], 0, v[130:131]
	s_add_i32 m0, s58, 0x2000
	s_nop 0
	global_load_lds_dwordx4 v[216:217], off
	v_lshl_add_u64 v[216:217], s[36:37], 0, v[128:129]
	s_mov_b32 m0, s29
	s_nop 0
	global_load_lds_dwordx4 v[216:217], off
	s_mov_b32 m0, s41
	s_nop 0
	global_load_lds_dwordx4 v[218:219], off
	s_waitcnt vmcnt(8)
	s_waitcnt lgkmcnt(0)
	s_barrier
; #define PG8_STAGE(bufoff, gbase, voff) do { _Pragma("unroll") for (int _i = 0; _i < 2; ++_i) \
;         __builtin_amdgcn_global_load_lds((const unsigned*)((const char*)(gbase) + (voff)[_i]), (PG8_LAS unsigned*)(lds + (bufoff) + ldsw + _i * 8192), 16, 0, 0); } while (0)
; #define PG8_LDA(dst, b, h) do { _Pragma("unroll") for (int m = 0; m < 4; ++m) _Pragma("unroll") for (int k = 0; k < 2; ++k) dst[m][k] = *(const PG8_LAS bf16x8*)(lds + PG8_SA(b, h) + aoff + m * 2048 + k * 1024); } while (0)
; #define PG8_LDB(dst, b, h) do { _Pragma("unroll") for (int n = 0; n < 2; ++n) _Pragma("unroll") for (int k = 0; k < 2; ++k) dst[n][k] = *(const PG8_LAS bf16x8*)(lds + PG8_SB(b, h) + boff + n * 2048 + k * 1024); } while (0)
; #define PG8_MMA(ai, bj, At, Bt) do { __builtin_amdgcn_s_setprio(1); _Pragma("unroll") for (int m = 0; m < 4; ++m) _Pragma("unroll") for (int n = 0; n < 2; ++n) _Pragma("unroll") for (int k = 0; k < 2; ++k) \
;         acc[ai][bj][m][n] = __builtin_amdgcn_mfma_f32_16x16x32_bf16(Bt[n][k], At[m][k], acc[ai][bj][m][n], 0, 0, 0); __builtin_amdgcn_s_setprio(0); } while (0)
; #define PG8_WAIT_V(n) asm volatile("s_waitcnt vmcnt(" #n ")" ::: "memory")
; #define PG8_WAIT_L(n) asm volatile("s_waitcnt lgkmcnt(" #n ")" ::: "memory")
; #define PG8_BAR __builtin_amdgcn_s_barrier()
; #define PG8_SCHED __builtin_amdgcn_sched_barrier(0)
; template <class Epi, class Sched, bool ALIGN_EPI = false, bool SP2 = false>
; __device__ __forceinline__ void gemm_phase(PG8_LAS unsigned char* lds, const Gemm g, const Sched& S, const Epi& E) {
;     ...
;             PG8_WAIT_V(8); PG8_WAIT_L(0); PG8_BAR; PG8_MMA(1, 0, At, B0); PG8_MMA(1, 1, At, B1); PG8_BAR; PG8_SCHED;
;             PG8_LDB(B0, 1, 0); PG8_LDB(B1, 1, 1); PG8_SCHED; PG8_LDA(At, 1, 0); PG8_STAGE(PG8_SA(0, 1), a2 + hstep, voffA);
;             PG8_WAIT_V(8); PG8_WAIT_L(0); PG8_BAR; PG8_MMA(0, 0, At, B0); PG8_MMA(0, 1, At, B1); PG8_BAR; PG8_SCHED;
	s_setprio 1
	s_waitcnt lgkmcnt(0)
	v_mfma_f32_16x16x32_bf16 v[60:63], v[140:143], v[178:181], v[60:63]
	v_mfma_f32_16x16x32_bf16 v[56:59], v[154:157], v[178:181], v[56:59]
	v_mfma_f32_16x16x32_bf16 v[48:51], v[140:143], v[186:189], v[48:51]
	v_mfma_f32_16x16x32_bf16 v[44:47], v[154:157], v[186:189], v[44:47]
	v_mfma_f32_16x16x32_bf16 v[32:35], v[140:143], v[198:201], v[32:35]
	v_mfma_f32_16x16x32_bf16 v[28:31], v[154:157], v[198:201], v[28:31]
	v_mfma_f32_16x16x32_bf16 v[16:19], v[140:143], v[206:209], v[16:19]
	v_mfma_f32_16x16x32_bf16 v[12:15], v[154:157], v[206:209], v[12:15]
	v_mfma_f32_16x16x32_bf16 v[60:63], v[150:153], v[182:185], v[60:63]
	v_mfma_f32_16x16x32_bf16 v[56:59], v[158:161], v[182:185], v[56:59]
	v_mfma_f32_16x16x32_bf16 v[48:51], v[150:153], v[190:193], v[48:51]
	v_mfma_f32_16x16x32_bf16 v[44:47], v[158:161], v[190:193], v[44:47]
	v_mfma_f32_16x16x32_bf16 v[32:35], v[150:153], v[202:205], v[32:35]
	v_mfma_f32_16x16x32_bf16 v[28:31], v[158:161], v[202:205], v[28:31]
	v_mfma_f32_16x16x32_bf16 v[16:19], v[150:153], v[210:213], v[16:19]
	v_mfma_f32_16x16x32_bf16 v[12:15], v[158:161], v[210:213], v[12:15]
	v_mfma_f32_16x16x32_bf16 v[52:55], v[162:165], v[178:181], v[52:55]
	v_mfma_f32_16x16x32_bf16 v[40:43], v[170:173], v[178:181], v[40:43]
	v_mfma_f32_16x16x32_bf16 v[36:39], v[162:165], v[186:189], v[36:39]
	v_mfma_f32_16x16x32_bf16 v[24:27], v[170:173], v[186:189], v[24:27]
	v_mfma_f32_16x16x32_bf16 v[20:23], v[162:165], v[198:201], v[20:23]
	v_mfma_f32_16x16x32_bf16 v[8:11], v[170:173], v[198:201], v[8:11]
	v_mfma_f32_16x16x32_bf16 v[4:7], v[162:165], v[206:209], v[4:7]
	v_mfma_f32_16x16x32_bf16 v[0:3], v[170:173], v[206:209], v[0:3]
	v_mfma_f32_16x16x32_bf16 v[52:55], v[166:169], v[182:185], v[52:55]
	v_mfma_f32_16x16x32_bf16 v[40:43], v[174:177], v[182:185], v[40:43]
	v_mfma_f32_16x16x32_bf16 v[36:39], v[166:169], v[190:193], v[36:39]
	v_mfma_f32_16x16x32_bf16 v[24:27], v[174:177], v[190:193], v[24:27]
	v_mfma_f32_16x16x32_bf16 v[20:23], v[166:169], v[202:205], v[20:23]
	v_mfma_f32_16x16x32_bf16 v[8:11], v[174:177], v[202:205], v[8:11]
	v_mfma_f32_16x16x32_bf16 v[4:7], v[166:169], v[210:213], v[4:7]
	v_mfma_f32_16x16x32_bf16 v[0:3], v[174:177], v[210:213], v[0:3]
	s_setprio 0
	s_barrier
	s_add_i32 s56, 0, 0x18000
	s_add_i32 s57, 0, 0x1c000
	v_add_u32_e32 v158, s56, v145
	v_add_u32_e32 v174, s57, v145
	ds_read_b128 v[140:143], v158
	ds_read_b128 v[150:153], v158 offset:1024
	ds_read_b128 v[154:157], v158 offset:2048
	ds_read_b128 v[158:161], v158 offset:3072
	ds_read_b128 v[162:165], v174
	ds_read_b128 v[166:169], v174 offset:1024
	ds_read_b128 v[170:173], v174 offset:2048
	ds_read_b128 v[174:177], v174 offset:3072
	s_add_u32 s36, s36, 0x80000
	s_addc_u32 s37, s37, 0
	s_mov_b32 m0, s42
	v_lshl_add_u64 v[220:221], s[36:37], 0, v[128:129]
	ds_read_b128 v[178:181], v149 offset:32768
	ds_read_b128 v[182:185], v149 offset:33792
	ds_read_b128 v[186:189], v149 offset:34816
	ds_read_b128 v[190:193], v149 offset:35840
	ds_read_b128 v[198:201], v149 offset:36864
	ds_read_b128 v[202:205], v149 offset:37888
	ds_read_b128 v[206:209], v149 offset:38912
	ds_read_b128 v[210:213], v149 offset:39936
	global_load_lds_dwordx4 v[220:221], off
	v_lshl_add_u64 v[220:221], s[36:37], 0, v[130:131]
	s_mov_b32 m0, s43
	s_nop 0
	global_load_lds_dwordx4 v[220:221], off
	s_waitcnt vmcnt(8)
	s_waitcnt lgkmcnt(0)
	s_barrier
	s_setprio 1
	s_waitcnt lgkmcnt(0)
	v_mfma_f32_16x16x32_bf16 v[124:127], v[140:143], v[178:181], v[124:127]
	v_mfma_f32_16x16x32_bf16 v[120:123], v[154:157], v[178:181], v[120:123]
	v_mfma_f32_16x16x32_bf16 v[112:115], v[140:143], v[186:189], v[112:115]
	v_mfma_f32_16x16x32_bf16 v[108:111], v[154:157], v[186:189], v[108:111]
	v_mfma_f32_16x16x32_bf16 v[96:99], v[140:143], v[198:201], v[96:99]
	v_mfma_f32_16x16x32_bf16 v[92:95], v[154:157], v[198:201], v[92:95]
	v_mfma_f32_16x16x32_bf16 v[80:83], v[140:143], v[206:209], v[80:83]
	v_mfma_f32_16x16x32_bf16 v[76:79], v[154:157], v[206:209], v[76:79]
	v_mfma_f32_16x16x32_bf16 v[124:127], v[150:153], v[182:185], v[124:127]
	v_mfma_f32_16x16x32_bf16 v[120:123], v[158:161], v[182:185], v[120:123]
	v_mfma_f32_16x16x32_bf16 v[112:115], v[150:153], v[190:193], v[112:115]
	v_mfma_f32_16x16x32_bf16 v[108:111], v[158:161], v[190:193], v[108:111]
	v_mfma_f32_16x16x32_bf16 v[96:99], v[150:153], v[202:205], v[96:99]
	v_mfma_f32_16x16x32_bf16 v[92:95], v[158:161], v[202:205], v[92:95]
	v_mfma_f32_16x16x32_bf16 v[80:83], v[150:153], v[210:213], v[80:83]
	v_mfma_f32_16x16x32_bf16 v[76:79], v[158:161], v[210:213], v[76:79]
	v_mfma_f32_16x16x32_bf16 v[116:119], v[162:165], v[178:181], v[116:119]
	v_mfma_f32_16x16x32_bf16 v[104:107], v[170:173], v[178:181], v[104:107]
	v_mfma_f32_16x16x32_bf16 v[100:103], v[162:165], v[186:189], v[100:103]
	v_mfma_f32_16x16x32_bf16 v[88:91], v[170:173], v[186:189], v[88:91]
	v_mfma_f32_16x16x32_bf16 v[84:87], v[162:165], v[198:201], v[84:87]
	v_mfma_f32_16x16x32_bf16 v[72:75], v[170:173], v[198:201], v[72:75]
	v_mfma_f32_16x16x32_bf16 v[68:71], v[162:165], v[206:209], v[68:71]
	v_mfma_f32_16x16x32_bf16 v[64:67], v[170:173], v[206:209], v[64:67]
	v_mfma_f32_16x16x32_bf16 v[116:119], v[166:169], v[182:185], v[116:119]
	v_mfma_f32_16x16x32_bf16 v[104:107], v[174:177], v[182:185], v[104:107]
	v_mfma_f32_16x16x32_bf16 v[100:103], v[166:169], v[190:193], v[100:103]
	v_mfma_f32_16x16x32_bf16 v[88:91], v[174:177], v[190:193], v[88:91]
	v_mfma_f32_16x16x32_bf16 v[84:87], v[166:169], v[202:205], v[84:87]
	v_mfma_f32_16x16x32_bf16 v[72:75], v[174:177], v[202:205], v[72:75]
	v_mfma_f32_16x16x32_bf16 v[68:71], v[166:169], v[210:213], v[68:71]
	v_mfma_f32_16x16x32_bf16 v[64:67], v[174:177], v[210:213], v[64:67]
	s_setprio 0
	s_barrier
; #define PG8_STAGE(bufoff, gbase, voff) do { _Pragma("unroll") for (int _i = 0; _i < 2; ++_i) \
;         __builtin_amdgcn_global_load_lds((const unsigned*)((const char*)(gbase) + (voff)[_i]), (PG8_LAS unsigned*)(lds + (bufoff) + ldsw + _i * 8192), 16, 0, 0); } while (0)
; #define PG8_LDA(dst, b, h) do { _Pragma("unroll") for (int m = 0; m < 4; ++m) _Pragma("unroll") for (int k = 0; k < 2; ++k) dst[m][k] = *(const PG8_LAS bf16x8*)(lds + PG8_SA(b, h) + aoff + m * 2048 + k * 1024); } while (0)
; #define PG8_WAIT_V(n) asm volatile("s_waitcnt vmcnt(" #n ")" ::: "memory")
; template <class Epi, class Sched, bool ALIGN_EPI = false, bool SP2 = false>
; __device__ __forceinline__ void gemm_phase(PG8_LAS unsigned char* lds, const Gemm g, const Sched& S, const Epi& E) {
;     ...
;             PG8_LDA(At, 1, 1); PG8_STAGE(PG8_SB(1, 0), b3, voffB); PG8_STAGE(PG8_SB(1, 1), b3 + hstep, voffB); PG8_STAGE(PG8_SA(1, 0), a3, voffA);
;             PG8_WAIT_V(8); PG8_WAIT_L(0); PG8_BAR; PG8_MMA(1, 0, At, B0); PG8_MMA(1, 1, At, B1); PG8_BAR; PG8_SCHED;
;             } else {
;             PG8_LDB(B0, 0, 0); PG8_SCHED; PG8_LDA(At, 0, 0); PG8_STAGE(PG8_SA(1, 1), a1 + hstep, voffA);
;             PG8_WAIT_L(8); PG8_BAR; PG8_WAIT_L(0); PG8_MMA(0, 0, At, B0); PG8_BAR; PG8_SCHED;
;             PG8_LDB(B1, 0, 1); PG8_STAGE(PG8_SB(0, 0), b2, voffB);
;             PG8_BAR; PG8_WAIT_L(0); PG8_MMA(0, 1, At, B1); PG8_BAR;
;             PG8_LDA(At, 0, 1); PG8_STAGE(PG8_SA(0, 0), a2, voffA);
;             PG8_BAR; PG8_WAIT_L(0); PG8_MMA(1, 0, At, B0); PG8_BAR; PG8_SCHED;
;             PG8_STAGE(PG8_SB(0, 1), b2 + hstep, voffB);
;             PG8_WAIT_V(6); PG8_BAR; PG8_MMA(1, 1, At, B1); PG8_BAR;
;             PG8_LDB(B0, 1, 0); PG8_SCHED; PG8_LDA(At, 1, 0); PG8_STAGE(PG8_SA(0, 1), a2 + hstep, voffA);
;             PG8_WAIT_L(8); PG8_BAR; PG8_WAIT_L(0); PG8_MMA(0, 0, At, B0); PG8_BAR; PG8_SCHED;
;             PG8_LDB(B1, 1, 1); PG8_STAGE(PG8_SB(1, 0), b3, voffB);
;             PG8_BAR; PG8_WAIT_L(0); PG8_MMA(0, 1, At, B1); PG8_BAR;
;             PG8_LDA(At, 1, 1); PG8_STAGE(PG8_SA(1, 0), a3, voffA);
;             PG8_BAR; PG8_WAIT_L(0); PG8_MMA(1, 0, At, B0); PG8_BAR; PG8_SCHED;
;             PG8_STAGE(PG8_SB(1, 1), b3 + hstep, voffB);
;             PG8_WAIT_V(6); PG8_BAR; PG8_MMA(1, 1, At, B1); PG8_BAR;
;             }
;         }
;         if constexpr (ALIGN_EPI) { if (wr == 0) PG8_BAR; }
	s_add_i32 s36, s56, s40
	v_lshl_add_u64 v[194:195], v[194:195], 0, s[16:17]
	s_mov_b32 m0, s36
	ds_read_b128 v[178:181], v149 offset:49152
	ds_read_b128 v[182:185], v149 offset:50176
	ds_read_b128 v[186:189], v149 offset:51200
	ds_read_b128 v[190:193], v149 offset:52224
	ds_read_b128 v[198:201], v149 offset:53248
	ds_read_b128 v[202:205], v149 offset:54272
	ds_read_b128 v[206:209], v149 offset:55296
	ds_read_b128 v[210:213], v149 offset:56320
	global_load_lds_dwordx4 v[194:195], off
	s_add_i32 m0, s36, 0x2000
	s_add_u32 s34, s34, 0x80080
	v_lshl_add_u64 v[194:195], v[214:215], 0, s[16:17]
	s_addc_u32 s35, s35, 0
	s_add_i32 s36, s57, s40
	global_load_lds_dwordx4 v[194:195], off
	v_lshl_add_u64 v[194:195], s[34:35], 0, v[128:129]
	s_mov_b32 m0, s36
	s_nop 0
	global_load_lds_dwordx4 v[194:195], off
	v_lshl_add_u64 v[194:195], s[34:35], 0, v[130:131]
	s_add_i32 m0, s36, 0x2000
	s_nop 0
	global_load_lds_dwordx4 v[194:195], off
	v_lshl_add_u64 v[194:195], v[216:217], 0, s[16:17]
	s_mov_b32 m0, s45
	s_nop 0
	global_load_lds_dwordx4 v[194:195], off
	v_lshl_add_u64 v[194:195], v[218:219], 0, s[16:17]
	s_mov_b32 m0, s46
	s_nop 0
	global_load_lds_dwordx4 v[194:195], off
	s_waitcnt vmcnt(8)
	s_waitcnt lgkmcnt(0)
	s_barrier
	s_setprio 1
	s_waitcnt lgkmcnt(0)
	v_mfma_f32_16x16x32_bf16 v[60:63], v[140:143], v[178:181], v[60:63]
	v_mfma_f32_16x16x32_bf16 v[56:59], v[154:157], v[178:181], v[56:59]
	v_mfma_f32_16x16x32_bf16 v[48:51], v[140:143], v[186:189], v[48:51]
	v_mfma_f32_16x16x32_bf16 v[44:47], v[154:157], v[186:189], v[44:47]
	v_mfma_f32_16x16x32_bf16 v[32:35], v[140:143], v[198:201], v[32:35]
	v_mfma_f32_16x16x32_bf16 v[28:31], v[154:157], v[198:201], v[28:31]
	v_mfma_f32_16x16x32_bf16 v[16:19], v[140:143], v[206:209], v[16:19]
	v_mfma_f32_16x16x32_bf16 v[12:15], v[154:157], v[206:209], v[12:15]
	v_mfma_f32_16x16x32_bf16 v[60:63], v[150:153], v[182:185], v[60:63]
	v_mfma_f32_16x16x32_bf16 v[56:59], v[158:161], v[182:185], v[56:59]
	v_mfma_f32_16x16x32_bf16 v[48:51], v[150:153], v[190:193], v[48:51]
	v_mfma_f32_16x16x32_bf16 v[44:47], v[158:161], v[190:193], v[44:47]
	v_mfma_f32_16x16x32_bf16 v[32:35], v[150:153], v[202:205], v[32:35]
	v_mfma_f32_16x16x32_bf16 v[28:31], v[158:161], v[202:205], v[28:31]
	v_mfma_f32_16x16x32_bf16 v[16:19], v[150:153], v[210:213], v[16:19]
	v_mfma_f32_16x16x32_bf16 v[12:15], v[158:161], v[210:213], v[12:15]
	v_mfma_f32_16x16x32_bf16 v[52:55], v[162:165], v[178:181], v[52:55]
	v_mfma_f32_16x16x32_bf16 v[40:43], v[170:173], v[178:181], v[40:43]
	v_mfma_f32_16x16x32_bf16 v[36:39], v[162:165], v[186:189], v[36:39]
	v_mfma_f32_16x16x32_bf16 v[24:27], v[170:173], v[186:189], v[24:27]
	v_mfma_f32_16x16x32_bf16 v[20:23], v[162:165], v[198:201], v[20:23]
	v_mfma_f32_16x16x32_bf16 v[8:11], v[170:173], v[198:201], v[8:11]
	v_mfma_f32_16x16x32_bf16 v[4:7], v[162:165], v[206:209], v[4:7]
	v_mfma_f32_16x16x32_bf16 v[0:3], v[170:173], v[206:209], v[0:3]
	v_mfma_f32_16x16x32_bf16 v[52:55], v[166:169], v[182:185], v[52:55]
	v_mfma_f32_16x16x32_bf16 v[40:43], v[174:177], v[182:185], v[40:43]
	v_mfma_f32_16x16x32_bf16 v[36:39], v[166:169], v[190:193], v[36:39]
	v_mfma_f32_16x16x32_bf16 v[24:27], v[174:177], v[190:193], v[24:27]
	v_mfma_f32_16x16x32_bf16 v[20:23], v[166:169], v[202:205], v[20:23]
	v_mfma_f32_16x16x32_bf16 v[8:11], v[174:177], v[202:205], v[8:11]
	v_mfma_f32_16x16x32_bf16 v[4:7], v[166:169], v[210:213], v[4:7]
	v_mfma_f32_16x16x32_bf16 v[0:3], v[174:177], v[210:213], v[0:3]
	s_setprio 0
	s_barrier
	s_add_i32 s55, s55, 2
	s_add_u32 s53, s53, 0x100
	s_addc_u32 s54, s54, 0
	s_add_u32 s30, s30, 0x100
	s_addc_u32 s31, s31, 0
	s_cmp_gt_u32 s55, 29
	s_cbranch_scc0 .LBB0_1138
	s_and_b64 vcc, exec, s[18:19]
	s_cbranch_vccz .LBB0_1141
	s_barrier

; #define PG8_STAGE(bufoff, gbase, voff) do { _Pragma("unroll") for (int _i = 0; _i < 2; ++_i) \
;         __builtin_amdgcn_global_load_lds((const unsigned*)((const char*)(gbase) + (voff)[_i]), (PG8_LAS unsigned*)(lds + (bufoff) + ldsw + _i * 8192), 16, 0, 0); } while (0)
; #define PG8_LDA(dst, b, h) do { _Pragma("unroll") for (int m = 0; m < 4; ++m) _Pragma("unroll") for (int k = 0; k < 2; ++k) dst[m][k] = *(const PG8_LAS bf16x8*)(lds + PG8_SA(b, h) + aoff + m * 2048 + k * 1024); } while (0)
; #define PG8_LDB(dst, b, h) do { _Pragma("unroll") for (int n = 0; n < 2; ++n) _Pragma("unroll") for (int k = 0; k < 2; ++k) dst[n][k] = *(const PG8_LAS bf16x8*)(lds + PG8_SB(b, h) + boff + n * 2048 + k * 1024); } while (0)
; #define PG8_MMA(ai, bj, At, Bt) do { __builtin_amdgcn_s_setprio(1); _Pragma("unroll") for (int m = 0; m < 4; ++m) _Pragma("unroll") for (int n = 0; n < 2; ++n) _Pragma("unroll") for (int k = 0; k < 2; ++k) \
;         acc[ai][bj][m][n] = __builtin_amdgcn_mfma_f32_16x16x32_bf16(Bt[n][k], At[m][k], acc[ai][bj][m][n], 0, 0, 0); __builtin_amdgcn_s_setprio(0); } while (0)
; #define PG8_WAIT_V(n) asm volatile("s_waitcnt vmcnt(" #n ")" ::: "memory")
; #define PG8_BAR __builtin_amdgcn_s_barrier()
; template <class Epi, class Sched, bool ALIGN_EPI = false, bool SP2 = false>
; __device__ __forceinline__ void gemm_phase(PG8_LAS unsigned char* lds, const Gemm g, const Sched& S, const Epi& E) {
;     ...
;         for (int t = 0; t < nt; t += 2) {
;             const bool last = (t == nt - 2);
;             const char* a1 = cA + (size_t)(t + 1) * kstep;
;             const char* a2 = last ? nA : cA + (size_t)(t + 2) * kstep; const char* b2 = last ? nB : cB + (size_t)(t + 2) * kstep;
;             const char* a3 = a2 + kstep; const char* b3 = b2 + kstep;
;             if (last && has_next) S.a_ready(nxt);
;             if constexpr (SP2) {
;             PG8_LDB(B0, 0, 0); PG8_LDB(B1, 0, 1); PG8_SCHED; PG8_LDA(At, 0, 0); PG8_STAGE(PG8_SA(1, 1), a1 + hstep, voffA);
;             PG8_WAIT_V(8); PG8_WAIT_L(0); PG8_BAR; PG8_MMA(0, 0, At, B0); PG8_MMA(0, 1, At, B1); PG8_BAR; PG8_SCHED;
;             PG8_LDA(At, 0, 1); PG8_STAGE(PG8_SB(0, 0), b2, voffB); PG8_STAGE(PG8_SB(0, 1), b2 + hstep, voffB); PG8_STAGE(PG8_SA(0, 0), a2, voffA);
;             PG8_WAIT_V(8); PG8_WAIT_L(0); PG8_BAR; PG8_MMA(1, 0, At, B0); PG8_MMA(1, 1, At, B1); PG8_BAR; PG8_SCHED;
.LBB0_1267:
	ds_read_b128 v[152:155], v149
	ds_read_b128 v[156:159], v149 offset:1024
	ds_read_b128 v[160:163], v149 offset:2048
	ds_read_b128 v[164:167], v149 offset:3072
	ds_read_b128 v[168:171], v150
	ds_read_b128 v[172:175], v150 offset:1024
	ds_read_b128 v[176:179], v150 offset:2048
	ds_read_b128 v[180:183], v150 offset:3072
	s_add_u32 s30, s28, 0xfff80080
	s_addc_u32 s31, s29, -1
	s_cmp_eq_u32 s55, 28
	s_cselect_b32 s35, s21, s31
	s_cselect_b32 s34, s51, s30
	s_cselect_b32 s31, s19, s54
	s_cselect_b32 s30, s52, s53
	v_lshl_add_u64 v[144:145], s[28:29], 0, v[138:139]
	s_add_i32 m0, s27, 0xc000
	ds_read_b128 v[184:187], v151
	ds_read_b128 v[188:191], v151 offset:1024
	ds_read_b128 v[192:195], v151 offset:2048
	ds_read_b128 v[198:201], v151 offset:3072
	ds_read_b128 v[202:205], v151 offset:4096
	ds_read_b128 v[206:209], v151 offset:5120
	ds_read_b128 v[210:213], v151 offset:6144
	ds_read_b128 v[214:217], v151 offset:7168
	global_load_lds_dwordx4 v[144:145], off
	v_lshl_add_u64 v[144:145], s[28:29], 0, v[136:137]
	s_add_i32 m0, s27, 0xe000
	s_nop 0
	global_load_lds_dwordx4 v[144:145], off
	s_waitcnt vmcnt(8)
	s_waitcnt lgkmcnt(0)
	s_barrier
	s_setprio 1
	s_waitcnt lgkmcnt(0)
	v_mfma_f32_16x16x32_bf16 v[124:127], v[152:155], v[184:187], v[124:127]
	v_mfma_f32_16x16x32_bf16 v[120:123], v[160:163], v[184:187], v[120:123]
	v_mfma_f32_16x16x32_bf16 v[108:111], v[152:155], v[192:195], v[108:111]
	v_mfma_f32_16x16x32_bf16 v[104:107], v[160:163], v[192:195], v[104:107]
	v_mfma_f32_16x16x32_bf16 v[92:95], v[152:155], v[202:205], v[92:95]
	v_mfma_f32_16x16x32_bf16 v[88:91], v[160:163], v[202:205], v[88:91]
	v_mfma_f32_16x16x32_bf16 v[76:79], v[152:155], v[210:213], v[76:79]
	v_mfma_f32_16x16x32_bf16 v[72:75], v[160:163], v[210:213], v[72:75]
	v_mfma_f32_16x16x32_bf16 v[124:127], v[156:159], v[188:191], v[124:127]
	v_mfma_f32_16x16x32_bf16 v[120:123], v[164:167], v[188:191], v[120:123]
	v_mfma_f32_16x16x32_bf16 v[108:111], v[156:159], v[198:201], v[108:111]
	v_mfma_f32_16x16x32_bf16 v[104:107], v[164:167], v[198:201], v[104:107]
	v_mfma_f32_16x16x32_bf16 v[92:95], v[156:159], v[206:209], v[92:95]
	v_mfma_f32_16x16x32_bf16 v[88:91], v[164:167], v[206:209], v[88:91]
	v_mfma_f32_16x16x32_bf16 v[76:79], v[156:159], v[214:217], v[76:79]
	v_mfma_f32_16x16x32_bf16 v[72:75], v[164:167], v[214:217], v[72:75]
	v_mfma_f32_16x16x32_bf16 v[116:119], v[168:171], v[184:187], v[116:119]
	v_mfma_f32_16x16x32_bf16 v[112:115], v[176:179], v[184:187], v[112:115]
	v_mfma_f32_16x16x32_bf16 v[100:103], v[168:171], v[192:195], v[100:103]
	v_mfma_f32_16x16x32_bf16 v[96:99], v[176:179], v[192:195], v[96:99]
	v_mfma_f32_16x16x32_bf16 v[84:87], v[168:171], v[202:205], v[84:87]
	v_mfma_f32_16x16x32_bf16 v[80:83], v[176:179], v[202:205], v[80:83]
	v_mfma_f32_16x16x32_bf16 v[68:71], v[168:171], v[210:213], v[68:71]
	v_mfma_f32_16x16x32_bf16 v[64:67], v[176:179], v[210:213], v[64:67]
	v_mfma_f32_16x16x32_bf16 v[116:119], v[172:175], v[188:191], v[116:119]
	v_mfma_f32_16x16x32_bf16 v[112:115], v[180:183], v[188:191], v[112:115]
	v_mfma_f32_16x16x32_bf16 v[100:103], v[172:175], v[198:201], v[100:103]
	v_mfma_f32_16x16x32_bf16 v[96:99], v[180:183], v[198:201], v[96:99]
	v_mfma_f32_16x16x32_bf16 v[84:87], v[172:175], v[206:209], v[84:87]
	v_mfma_f32_16x16x32_bf16 v[80:83], v[180:183], v[206:209], v[80:83]
	v_mfma_f32_16x16x32_bf16 v[68:71], v[172:175], v[214:217], v[68:71]
	v_mfma_f32_16x16x32_bf16 v[64:67], v[180:183], v[214:217], v[64:67]
	s_setprio 0
	s_barrier
	s_add_i32 s56, s47, s37
	v_lshl_add_u64 v[144:145], s[30:31], 0, v[132:133]
	s_mov_b32 m0, s56
	ds_read_b128 v[184:187], v151 offset:16384
	ds_read_b128 v[188:191], v151 offset:17408
	ds_read_b128 v[192:195], v151 offset:18432
	ds_read_b128 v[198:201], v151 offset:19456
	ds_read_b128 v[202:205], v151 offset:20480
	ds_read_b128 v[206:209], v151 offset:21504
	ds_read_b128 v[210:213], v151 offset:22528
	ds_read_b128 v[214:217], v151 offset:23552
	global_load_lds_dwordx4 v[144:145], off
	s_add_i32 m0, s56, 0x2000
	s_add_u32 s56, s30, 0x80000
	v_lshl_add_u64 v[218:219], s[30:31], 0, v[128:129]
	s_addc_u32 s57, s31, 0
	s_add_i32 s58, s48, s37
	global_load_lds_dwordx4 v[218:219], off
	v_lshl_add_u64 v[220:221], s[56:57], 0, v[132:133]
	s_mov_b32 m0, s58
	v_lshl_add_u64 v[222:223], s[34:35], 0, v[130:131]
	global_load_lds_dwordx4 v[220:221], off
	v_lshl_add_u64 v[220:221], s[56:57], 0, v[128:129]
	s_add_i32 m0, s58, 0x2000
	s_nop 0
	global_load_lds_dwordx4 v[220:221], off
	v_lshl_add_u64 v[220:221], s[34:35], 0, v[134:135]
	s_mov_b32 m0, s27
	s_nop 0
	global_load_lds_dwordx4 v[220:221], off
	s_mov_b32 m0, s40
	s_nop 0
	global_load_lds_dwordx4 v[222:223], off
	s_waitcnt vmcnt(8)
	s_waitcnt lgkmcnt(0)
	s_barrier
; #define PG8_STAGE(bufoff, gbase, voff) do { _Pragma("unroll") for (int _i = 0; _i < 2; ++_i) \
;         __builtin_amdgcn_global_load_lds((const unsigned*)((const char*)(gbase) + (voff)[_i]), (PG8_LAS unsigned*)(lds + (bufoff) + ldsw + _i * 8192), 16, 0, 0); } while (0)
; #define PG8_LDA(dst, b, h) do { _Pragma("unroll") for (int m = 0; m < 4; ++m) _Pragma("unroll") for (int k = 0; k < 2; ++k) dst[m][k] = *(const PG8_LAS bf16x8*)(lds + PG8_SA(b, h) + aoff + m * 2048 + k * 1024); } while (0)
; #define PG8_LDB(dst, b, h) do { _Pragma("unroll") for (int n = 0; n < 2; ++n) _Pragma("unroll") for (int k = 0; k < 2; ++k) dst[n][k] = *(const PG8_LAS bf16x8*)(lds + PG8_SB(b, h) + boff + n * 2048 + k * 1024); } while (0)
; #define PG8_MMA(ai, bj, At, Bt) do { __builtin_amdgcn_s_setprio(1); _Pragma("unroll") for (int m = 0; m < 4; ++m) _Pragma("unroll") for (int n = 0; n < 2; ++n) _Pragma("unroll") for (int k = 0; k < 2; ++k) \
;         acc[ai][bj][m][n] = __builtin_amdgcn_mfma_f32_16x16x32_bf16(Bt[n][k], At[m][k], acc[ai][bj][m][n], 0, 0, 0); __builtin_amdgcn_s_setprio(0); } while (0)
; #define PG8_WAIT_V(n) asm volatile("s_waitcnt vmcnt(" #n ")" ::: "memory")
; #define PG8_WAIT_L(n) asm volatile("s_waitcnt lgkmcnt(" #n ")" ::: "memory")
; #define PG8_BAR __builtin_amdgcn_s_barrier()
; #define PG8_SCHED __builtin_amdgcn_sched_barrier(0)
; template <class Epi, class Sched, bool ALIGN_EPI = false, bool SP2 = false>
; __device__ __forceinline__ void gemm_phase(PG8_LAS unsigned char* lds, const Gemm g, const Sched& S, const Epi& E) {
;     ...
;             PG8_WAIT_V(8); PG8_WAIT_L(0); PG8_BAR; PG8_MMA(1, 0, At, B0); PG8_MMA(1, 1, At, B1); PG8_BAR; PG8_SCHED;
;             PG8_LDB(B0, 1, 0); PG8_LDB(B1, 1, 1); PG8_SCHED; PG8_LDA(At, 1, 0); PG8_STAGE(PG8_SA(0, 1), a2 + hstep, voffA);
;             PG8_WAIT_V(8); PG8_WAIT_L(0); PG8_BAR; PG8_MMA(0, 0, At, B0); PG8_MMA(0, 1, At, B1); PG8_BAR; PG8_SCHED;
	s_setprio 1
	s_waitcnt lgkmcnt(0)
	v_mfma_f32_16x16x32_bf16 v[60:63], v[152:155], v[184:187], v[60:63]
	v_mfma_f32_16x16x32_bf16 v[56:59], v[160:163], v[184:187], v[56:59]
	v_mfma_f32_16x16x32_bf16 v[44:47], v[152:155], v[192:195], v[44:47]
	v_mfma_f32_16x16x32_bf16 v[40:43], v[160:163], v[192:195], v[40:43]
	v_mfma_f32_16x16x32_bf16 v[28:31], v[152:155], v[202:205], v[28:31]
	v_mfma_f32_16x16x32_bf16 v[24:27], v[160:163], v[202:205], v[24:27]
	v_mfma_f32_16x16x32_bf16 v[12:15], v[152:155], v[210:213], v[12:15]
	v_mfma_f32_16x16x32_bf16 v[8:11], v[160:163], v[210:213], v[8:11]
	v_mfma_f32_16x16x32_bf16 v[60:63], v[156:159], v[188:191], v[60:63]
	v_mfma_f32_16x16x32_bf16 v[56:59], v[164:167], v[188:191], v[56:59]
	v_mfma_f32_16x16x32_bf16 v[44:47], v[156:159], v[198:201], v[44:47]
	v_mfma_f32_16x16x32_bf16 v[40:43], v[164:167], v[198:201], v[40:43]
	v_mfma_f32_16x16x32_bf16 v[28:31], v[156:159], v[206:209], v[28:31]
	v_mfma_f32_16x16x32_bf16 v[24:27], v[164:167], v[206:209], v[24:27]
	v_mfma_f32_16x16x32_bf16 v[12:15], v[156:159], v[214:217], v[12:15]
	v_mfma_f32_16x16x32_bf16 v[8:11], v[164:167], v[214:217], v[8:11]
	v_mfma_f32_16x16x32_bf16 v[52:55], v[168:171], v[184:187], v[52:55]
	v_mfma_f32_16x16x32_bf16 v[48:51], v[176:179], v[184:187], v[48:51]
	v_mfma_f32_16x16x32_bf16 v[36:39], v[168:171], v[192:195], v[36:39]
	v_mfma_f32_16x16x32_bf16 v[32:35], v[176:179], v[192:195], v[32:35]
	v_mfma_f32_16x16x32_bf16 v[20:23], v[168:171], v[202:205], v[20:23]
	v_mfma_f32_16x16x32_bf16 v[16:19], v[176:179], v[202:205], v[16:19]
	v_mfma_f32_16x16x32_bf16 v[4:7], v[168:171], v[210:213], v[4:7]
	v_mfma_f32_16x16x32_bf16 v[0:3], v[176:179], v[210:213], v[0:3]
	v_mfma_f32_16x16x32_bf16 v[52:55], v[172:175], v[188:191], v[52:55]
	v_mfma_f32_16x16x32_bf16 v[48:51], v[180:183], v[188:191], v[48:51]
	v_mfma_f32_16x16x32_bf16 v[36:39], v[172:175], v[198:201], v[36:39]
	v_mfma_f32_16x16x32_bf16 v[32:35], v[180:183], v[198:201], v[32:35]
	v_mfma_f32_16x16x32_bf16 v[20:23], v[172:175], v[206:209], v[20:23]
	v_mfma_f32_16x16x32_bf16 v[16:19], v[180:183], v[206:209], v[16:19]
	v_mfma_f32_16x16x32_bf16 v[4:7], v[172:175], v[214:217], v[4:7]
	v_mfma_f32_16x16x32_bf16 v[0:3], v[180:183], v[214:217], v[0:3]
	s_setprio 0
	s_barrier
	s_add_i32 s56, 0, 0x18000
	s_add_i32 s57, 0, 0x1c000
	v_add_u32_e32 v164, s56, v147
	v_add_u32_e32 v180, s57, v147
	ds_read_b128 v[152:155], v164
	ds_read_b128 v[156:159], v164 offset:1024
	ds_read_b128 v[160:163], v164 offset:2048
	ds_read_b128 v[164:167], v164 offset:3072
	ds_read_b128 v[168:171], v180
	ds_read_b128 v[172:175], v180 offset:1024
	ds_read_b128 v[176:179], v180 offset:2048
	ds_read_b128 v[180:183], v180 offset:3072
	s_add_u32 s34, s34, 0x80000
	s_addc_u32 s35, s35, 0
	s_mov_b32 m0, s41
	v_lshl_add_u64 v[224:225], s[34:35], 0, v[134:135]
	ds_read_b128 v[184:187], v151 offset:32768
	ds_read_b128 v[188:191], v151 offset:33792
	ds_read_b128 v[192:195], v151 offset:34816
	ds_read_b128 v[198:201], v151 offset:35840
	ds_read_b128 v[202:205], v151 offset:36864
	ds_read_b128 v[206:209], v151 offset:37888
	ds_read_b128 v[210:213], v151 offset:38912
	ds_read_b128 v[214:217], v151 offset:39936
	global_load_lds_dwordx4 v[224:225], off
	v_lshl_add_u64 v[224:225], s[34:35], 0, v[130:131]
	s_mov_b32 m0, s42
	s_nop 0
	global_load_lds_dwordx4 v[224:225], off
	s_waitcnt vmcnt(8)
	s_waitcnt lgkmcnt(0)
	s_barrier
	s_setprio 1
	s_waitcnt lgkmcnt(0)
	v_mfma_f32_16x16x32_bf16 v[124:127], v[152:155], v[184:187], v[124:127]
	v_mfma_f32_16x16x32_bf16 v[120:123], v[160:163], v[184:187], v[120:123]
	v_mfma_f32_16x16x32_bf16 v[108:111], v[152:155], v[192:195], v[108:111]
	v_mfma_f32_16x16x32_bf16 v[104:107], v[160:163], v[192:195], v[104:107]
	v_mfma_f32_16x16x32_bf16 v[92:95], v[152:155], v[202:205], v[92:95]
	v_mfma_f32_16x16x32_bf16 v[88:91], v[160:163], v[202:205], v[88:91]
	v_mfma_f32_16x16x32_bf16 v[76:79], v[152:155], v[210:213], v[76:79]
	v_mfma_f32_16x16x32_bf16 v[72:75], v[160:163], v[210:213], v[72:75]
	v_mfma_f32_16x16x32_bf16 v[124:127], v[156:159], v[188:191], v[124:127]
	v_mfma_f32_16x16x32_bf16 v[120:123], v[164:167], v[188:191], v[120:123]
	v_mfma_f32_16x16x32_bf16 v[108:111], v[156:159], v[198:201], v[108:111]
	v_mfma_f32_16x16x32_bf16 v[104:107], v[164:167], v[198:201], v[104:107]
	v_mfma_f32_16x16x32_bf16 v[92:95], v[156:159], v[206:209], v[92:95]
	v_mfma_f32_16x16x32_bf16 v[88:91], v[164:167], v[206:209], v[88:91]
	v_mfma_f32_16x16x32_bf16 v[76:79], v[156:159], v[214:217], v[76:79]
	v_mfma_f32_16x16x32_bf16 v[72:75], v[164:167], v[214:217], v[72:75]
	v_mfma_f32_16x16x32_bf16 v[116:119], v[168:171], v[184:187], v[116:119]
	v_mfma_f32_16x16x32_bf16 v[112:115], v[176:179], v[184:187], v[112:115]
	v_mfma_f32_16x16x32_bf16 v[100:103], v[168:171], v[192:195], v[100:103]
	v_mfma_f32_16x16x32_bf16 v[96:99], v[176:179], v[192:195], v[96:99]
	v_mfma_f32_16x16x32_bf16 v[84:87], v[168:171], v[202:205], v[84:87]
	v_mfma_f32_16x16x32_bf16 v[80:83], v[176:179], v[202:205], v[80:83]
	v_mfma_f32_16x16x32_bf16 v[68:71], v[168:171], v[210:213], v[68:71]
	v_mfma_f32_16x16x32_bf16 v[64:67], v[176:179], v[210:213], v[64:67]
	v_mfma_f32_16x16x32_bf16 v[116:119], v[172:175], v[188:191], v[116:119]
	v_mfma_f32_16x16x32_bf16 v[112:115], v[180:183], v[188:191], v[112:115]
	v_mfma_f32_16x16x32_bf16 v[100:103], v[172:175], v[198:201], v[100:103]
	v_mfma_f32_16x16x32_bf16 v[96:99], v[180:183], v[198:201], v[96:99]
	v_mfma_f32_16x16x32_bf16 v[84:87], v[172:175], v[206:209], v[84:87]
	v_mfma_f32_16x16x32_bf16 v[80:83], v[180:183], v[206:209], v[80:83]
	v_mfma_f32_16x16x32_bf16 v[68:71], v[172:175], v[214:217], v[68:71]
	v_mfma_f32_16x16x32_bf16 v[64:67], v[180:183], v[214:217], v[64:67]
	s_setprio 0
	s_barrier
; #define PG8_STAGE(bufoff, gbase, voff) do { _Pragma("unroll") for (int _i = 0; _i < 2; ++_i) \
;         __builtin_amdgcn_global_load_lds((const unsigned*)((const char*)(gbase) + (voff)[_i]), (PG8_LAS unsigned*)(lds + (bufoff) + ldsw + _i * 8192), 16, 0, 0); } while (0)
; #define PG8_LDA(dst, b, h) do { _Pragma("unroll") for (int m = 0; m < 4; ++m) _Pragma("unroll") for (int k = 0; k < 2; ++k) dst[m][k] = *(const PG8_LAS bf16x8*)(lds + PG8_SA(b, h) + aoff + m * 2048 + k * 1024); } while (0)
; #define PG8_WAIT_V(n) asm volatile("s_waitcnt vmcnt(" #n ")" ::: "memory")
; template <class Epi, class Sched, bool ALIGN_EPI = false, bool SP2 = false>
; __device__ __forceinline__ void gemm_phase(PG8_LAS unsigned char* lds, const Gemm g, const Sched& S, const Epi& E) {
;     ...
;             PG8_LDA(At, 1, 1); PG8_STAGE(PG8_SB(1, 0), b3, voffB); PG8_STAGE(PG8_SB(1, 1), b3 + hstep, voffB); PG8_STAGE(PG8_SA(1, 0), a3, voffA);
;             PG8_WAIT_V(8); PG8_WAIT_L(0); PG8_BAR; PG8_MMA(1, 0, At, B0); PG8_MMA(1, 1, At, B1); PG8_BAR; PG8_SCHED;
;             } else {
;             PG8_LDB(B0, 0, 0); PG8_SCHED; PG8_LDA(At, 0, 0); PG8_STAGE(PG8_SA(1, 1), a1 + hstep, voffA);
;             PG8_WAIT_L(8); PG8_BAR; PG8_WAIT_L(0); PG8_MMA(0, 0, At, B0); PG8_BAR; PG8_SCHED;
;             PG8_LDB(B1, 0, 1); PG8_STAGE(PG8_SB(0, 0), b2, voffB);
;             PG8_BAR; PG8_WAIT_L(0); PG8_MMA(0, 1, At, B1); PG8_BAR;
;             PG8_LDA(At, 0, 1); PG8_STAGE(PG8_SA(0, 0), a2, voffA);
;             PG8_BAR; PG8_WAIT_L(0); PG8_MMA(1, 0, At, B0); PG8_BAR; PG8_SCHED;
;             PG8_STAGE(PG8_SB(0, 1), b2 + hstep, voffB);
;             PG8_WAIT_V(6); PG8_BAR; PG8_MMA(1, 1, At, B1); PG8_BAR;
;             PG8_LDB(B0, 1, 0); PG8_SCHED; PG8_LDA(At, 1, 0); PG8_STAGE(PG8_SA(0, 1), a2 + hstep, voffA);
;             PG8_WAIT_L(8); PG8_BAR; PG8_WAIT_L(0); PG8_MMA(0, 0, At, B0); PG8_BAR; PG8_SCHED;
;             PG8_LDB(B1, 1, 1); PG8_STAGE(PG8_SB(1, 0), b3, voffB);
;             PG8_BAR; PG8_WAIT_L(0); PG8_MMA(0, 1, At, B1); PG8_BAR;
;             PG8_LDA(At, 1, 1); PG8_STAGE(PG8_SA(1, 0), a3, voffA);
;             PG8_BAR; PG8_WAIT_L(0); PG8_MMA(1, 0, At, B0); PG8_BAR; PG8_SCHED;
;             PG8_STAGE(PG8_SB(1, 1), b3 + hstep, voffB);
;             PG8_WAIT_V(6); PG8_BAR; PG8_MMA(1, 1, At, B1); PG8_BAR;
;             }
;         }
;         if constexpr (ALIGN_EPI) { if (wr == 0) PG8_BAR; }
	s_add_i32 s34, s56, s37
	v_lshl_add_u64 v[144:145], v[144:145], 0, s[14:15]
	s_mov_b32 m0, s34
	ds_read_b128 v[184:187], v151 offset:49152
	ds_read_b128 v[188:191], v151 offset:50176
	ds_read_b128 v[192:195], v151 offset:51200
	ds_read_b128 v[198:201], v151 offset:52224
	ds_read_b128 v[202:205], v151 offset:53248
	ds_read_b128 v[206:209], v151 offset:54272
	ds_read_b128 v[210:213], v151 offset:55296
	ds_read_b128 v[214:217], v151 offset:56320
	global_load_lds_dwordx4 v[144:145], off
	s_add_i32 m0, s34, 0x2000
	s_add_u32 s30, s30, 0x80080
	v_lshl_add_u64 v[144:145], v[218:219], 0, s[14:15]
	s_addc_u32 s31, s31, 0
	s_add_i32 s34, s57, s37
	global_load_lds_dwordx4 v[144:145], off
	v_lshl_add_u64 v[144:145], s[30:31], 0, v[132:133]
	s_mov_b32 m0, s34
	s_nop 0
	global_load_lds_dwordx4 v[144:145], off
	v_lshl_add_u64 v[144:145], s[30:31], 0, v[128:129]
	s_add_i32 m0, s34, 0x2000
	s_nop 0
	global_load_lds_dwordx4 v[144:145], off
	v_lshl_add_u64 v[144:145], v[220:221], 0, s[14:15]
	s_mov_b32 m0, s44
	s_nop 0
	global_load_lds_dwordx4 v[144:145], off
	v_lshl_add_u64 v[144:145], v[222:223], 0, s[14:15]
	s_mov_b32 m0, s45
	s_nop 0
	global_load_lds_dwordx4 v[144:145], off
	s_waitcnt vmcnt(8)
	s_waitcnt lgkmcnt(0)
	s_barrier
	s_setprio 1
	s_waitcnt lgkmcnt(0)
	v_mfma_f32_16x16x32_bf16 v[60:63], v[152:155], v[184:187], v[60:63]
	v_mfma_f32_16x16x32_bf16 v[56:59], v[160:163], v[184:187], v[56:59]
	v_mfma_f32_16x16x32_bf16 v[44:47], v[152:155], v[192:195], v[44:47]
	v_mfma_f32_16x16x32_bf16 v[40:43], v[160:163], v[192:195], v[40:43]
	v_mfma_f32_16x16x32_bf16 v[28:31], v[152:155], v[202:205], v[28:31]
	v_mfma_f32_16x16x32_bf16 v[24:27], v[160:163], v[202:205], v[24:27]
	v_mfma_f32_16x16x32_bf16 v[12:15], v[152:155], v[210:213], v[12:15]
	v_mfma_f32_16x16x32_bf16 v[8:11], v[160:163], v[210:213], v[8:11]
	v_mfma_f32_16x16x32_bf16 v[60:63], v[156:159], v[188:191], v[60:63]
	v_mfma_f32_16x16x32_bf16 v[56:59], v[164:167], v[188:191], v[56:59]
	v_mfma_f32_16x16x32_bf16 v[44:47], v[156:159], v[198:201], v[44:47]
	v_mfma_f32_16x16x32_bf16 v[40:43], v[164:167], v[198:201], v[40:43]
	v_mfma_f32_16x16x32_bf16 v[28:31], v[156:159], v[206:209], v[28:31]
	v_mfma_f32_16x16x32_bf16 v[24:27], v[164:167], v[206:209], v[24:27]
	v_mfma_f32_16x16x32_bf16 v[12:15], v[156:159], v[214:217], v[12:15]
	v_mfma_f32_16x16x32_bf16 v[8:11], v[164:167], v[214:217], v[8:11]
	v_mfma_f32_16x16x32_bf16 v[52:55], v[168:171], v[184:187], v[52:55]
	v_mfma_f32_16x16x32_bf16 v[48:51], v[176:179], v[184:187], v[48:51]
	v_mfma_f32_16x16x32_bf16 v[36:39], v[168:171], v[192:195], v[36:39]
	v_mfma_f32_16x16x32_bf16 v[32:35], v[176:179], v[192:195], v[32:35]
	v_mfma_f32_16x16x32_bf16 v[20:23], v[168:171], v[202:205], v[20:23]
	v_mfma_f32_16x16x32_bf16 v[16:19], v[176:179], v[202:205], v[16:19]
	v_mfma_f32_16x16x32_bf16 v[4:7], v[168:171], v[210:213], v[4:7]
	v_mfma_f32_16x16x32_bf16 v[0:3], v[176:179], v[210:213], v[0:3]
	v_mfma_f32_16x16x32_bf16 v[52:55], v[172:175], v[188:191], v[52:55]
	v_mfma_f32_16x16x32_bf16 v[48:51], v[180:183], v[188:191], v[48:51]
	v_mfma_f32_16x16x32_bf16 v[36:39], v[172:175], v[198:201], v[36:39]
	v_mfma_f32_16x16x32_bf16 v[32:35], v[180:183], v[198:201], v[32:35]
	v_mfma_f32_16x16x32_bf16 v[20:23], v[172:175], v[206:209], v[20:23]
	v_mfma_f32_16x16x32_bf16 v[16:19], v[180:183], v[206:209], v[16:19]
	v_mfma_f32_16x16x32_bf16 v[4:7], v[172:175], v[214:217], v[4:7]
	v_mfma_f32_16x16x32_bf16 v[0:3], v[180:183], v[214:217], v[0:3]
	s_setprio 0
	s_barrier
	s_add_i32 s55, s55, 2
	s_add_u32 s53, s53, 0x100
	s_addc_u32 s54, s54, 0
	s_add_u32 s28, s28, 0x100
	s_addc_u32 s29, s29, 0
	s_cmp_gt_u32 s55, 29
	s_cbranch_scc0 .LBB0_1267
	s_and_b64 vcc, exec, s[16:17]
	s_cbranch_vccz .LBB0_1270
	s_barrier

; #define PG8_STAGE(bufoff, gbase, voff) do { _Pragma("unroll") for (int _i = 0; _i < 2; ++_i) \
;         __builtin_amdgcn_global_load_lds((const unsigned*)((const char*)(gbase) + (voff)[_i]), (PG8_LAS unsigned*)(lds + (bufoff) + ldsw + _i * 8192), 16, 0, 0); } while (0)
; #define PG8_LDA(dst, b, h) do { _Pragma("unroll") for (int m = 0; m < 4; ++m) _Pragma("unroll") for (int k = 0; k < 2; ++k) dst[m][k] = *(const PG8_LAS bf16x8*)(lds + PG8_SA(b, h) + aoff + m * 2048 + k * 1024); } while (0)
; #define PG8_LDB(dst, b, h) do { _Pragma("unroll") for (int n = 0; n < 2; ++n) _Pragma("unroll") for (int k = 0; k < 2; ++k) dst[n][k] = *(const PG8_LAS bf16x8*)(lds + PG8_SB(b, h) + boff + n * 2048 + k * 1024); } while (0)
; #define PG8_MMA(ai, bj, At, Bt) do { __builtin_amdgcn_s_setprio(1); _Pragma("unroll") for (int m = 0; m < 4; ++m) _Pragma("unroll") for (int n = 0; n < 2; ++n) _Pragma("unroll") for (int k = 0; k < 2; ++k) \
;         acc[ai][bj][m][n] = __builtin_amdgcn_mfma_f32_16x16x32_bf16(Bt[n][k], At[m][k], acc[ai][bj][m][n], 0, 0, 0); __builtin_amdgcn_s_setprio(0); } while (0)
; #define PG8_WAIT_V(n) asm volatile("s_waitcnt vmcnt(" #n ")" ::: "memory")
; #define PG8_BAR __builtin_amdgcn_s_barrier()
; template <class Epi, class Sched, bool ALIGN_EPI = false, bool SP2 = false>
; __device__ __forceinline__ void gemm_phase(PG8_LAS unsigned char* lds, const Gemm g, const Sched& S, const Epi& E) {
;     ...
;         for (int t = 0; t < nt; t += 2) {
;             const bool last = (t == nt - 2);
;             const char* a1 = cA + (size_t)(t + 1) * kstep;
;             const char* a2 = last ? nA : cA + (size_t)(t + 2) * kstep; const char* b2 = last ? nB : cB + (size_t)(t + 2) * kstep;
;             const char* a3 = a2 + kstep; const char* b3 = b2 + kstep;
;             if (last && has_next) S.a_ready(nxt);
;             if constexpr (SP2) {
;             PG8_LDB(B0, 0, 0); PG8_LDB(B1, 0, 1); PG8_SCHED; PG8_LDA(At, 0, 0); PG8_STAGE(PG8_SA(1, 1), a1 + hstep, voffA);
;             PG8_WAIT_V(8); PG8_WAIT_L(0); PG8_BAR; PG8_MMA(0, 0, At, B0); PG8_MMA(0, 1, At, B1); PG8_BAR; PG8_SCHED;
;             PG8_LDA(At, 0, 1); PG8_STAGE(PG8_SB(0, 0), b2, voffB); PG8_STAGE(PG8_SB(0, 1), b2 + hstep, voffB); PG8_STAGE(PG8_SA(0, 0), a2, voffA);
;             PG8_WAIT_V(8); PG8_WAIT_L(0); PG8_BAR; PG8_MMA(1, 0, At, B0); PG8_MMA(1, 1, At, B1); PG8_BAR; PG8_SCHED;
.LBB0_1350:
	ds_read_b128 v[140:143], v147
	ds_read_b128 v[150:153], v147 offset:1024
	ds_read_b128 v[154:157], v147 offset:2048
	ds_read_b128 v[158:161], v147 offset:3072
	ds_read_b128 v[162:165], v148
	ds_read_b128 v[166:169], v148 offset:1024
	ds_read_b128 v[170:173], v148 offset:2048
	ds_read_b128 v[174:177], v148 offset:3072
	s_add_u32 s24, s22, 0xffea0080
	s_addc_u32 s25, s23, -1
	s_cmpk_eq_i32 s49, 0x54
	s_cselect_b32 s27, s9, s25
	s_cselect_b32 s26, s8, s24
	s_cselect_b32 s25, s21, s48
	s_cselect_b32 s24, s20, s47
	v_lshl_add_u64 v[194:195], s[22:23], 0, v[134:135]
	s_add_i32 m0, s33, 0xc000
	ds_read_b128 v[178:181], v149
	ds_read_b128 v[182:185], v149 offset:1024
	ds_read_b128 v[186:189], v149 offset:2048
	ds_read_b128 v[190:193], v149 offset:3072
	ds_read_b128 v[198:201], v149 offset:4096
	ds_read_b128 v[202:205], v149 offset:5120
	ds_read_b128 v[206:209], v149 offset:6144
	ds_read_b128 v[210:213], v149 offset:7168
	global_load_lds_dwordx4 v[194:195], off
	v_lshl_add_u64 v[194:195], s[22:23], 0, v[132:133]
	s_add_i32 m0, s33, 0xe000
	s_nop 0
	global_load_lds_dwordx4 v[194:195], off
	s_waitcnt vmcnt(8)
	s_waitcnt lgkmcnt(0)
	s_barrier
	s_setprio 1
	s_waitcnt lgkmcnt(0)
	v_mfma_f32_16x16x32_bf16 v[124:127], v[140:143], v[178:181], v[124:127]
	v_mfma_f32_16x16x32_bf16 v[120:123], v[154:157], v[178:181], v[120:123]
	v_mfma_f32_16x16x32_bf16 v[112:115], v[140:143], v[186:189], v[112:115]
	v_mfma_f32_16x16x32_bf16 v[104:107], v[154:157], v[186:189], v[104:107]
	v_mfma_f32_16x16x32_bf16 v[92:95], v[140:143], v[198:201], v[92:95]
	v_mfma_f32_16x16x32_bf16 v[88:91], v[154:157], v[198:201], v[88:91]
	v_mfma_f32_16x16x32_bf16 v[76:79], v[140:143], v[206:209], v[76:79]
	v_mfma_f32_16x16x32_bf16 v[72:75], v[154:157], v[206:209], v[72:75]
	v_mfma_f32_16x16x32_bf16 v[124:127], v[150:153], v[182:185], v[124:127]
	v_mfma_f32_16x16x32_bf16 v[120:123], v[158:161], v[182:185], v[120:123]
	v_mfma_f32_16x16x32_bf16 v[112:115], v[150:153], v[190:193], v[112:115]
	v_mfma_f32_16x16x32_bf16 v[104:107], v[158:161], v[190:193], v[104:107]
	v_mfma_f32_16x16x32_bf16 v[92:95], v[150:153], v[202:205], v[92:95]
	v_mfma_f32_16x16x32_bf16 v[88:91], v[158:161], v[202:205], v[88:91]
	v_mfma_f32_16x16x32_bf16 v[76:79], v[150:153], v[210:213], v[76:79]
	v_mfma_f32_16x16x32_bf16 v[72:75], v[158:161], v[210:213], v[72:75]
	v_mfma_f32_16x16x32_bf16 v[116:119], v[162:165], v[178:181], v[116:119]
	v_mfma_f32_16x16x32_bf16 v[108:111], v[170:173], v[178:181], v[108:111]
	v_mfma_f32_16x16x32_bf16 v[100:103], v[162:165], v[186:189], v[100:103]
	v_mfma_f32_16x16x32_bf16 v[96:99], v[170:173], v[186:189], v[96:99]
	v_mfma_f32_16x16x32_bf16 v[84:87], v[162:165], v[198:201], v[84:87]
	v_mfma_f32_16x16x32_bf16 v[80:83], v[170:173], v[198:201], v[80:83]
	v_mfma_f32_16x16x32_bf16 v[68:71], v[162:165], v[206:209], v[68:71]
	v_mfma_f32_16x16x32_bf16 v[64:67], v[170:173], v[206:209], v[64:67]
	v_mfma_f32_16x16x32_bf16 v[116:119], v[166:169], v[182:185], v[116:119]
	v_mfma_f32_16x16x32_bf16 v[108:111], v[174:177], v[182:185], v[108:111]
	v_mfma_f32_16x16x32_bf16 v[100:103], v[166:169], v[190:193], v[100:103]
	v_mfma_f32_16x16x32_bf16 v[96:99], v[174:177], v[190:193], v[96:99]
	v_mfma_f32_16x16x32_bf16 v[84:87], v[166:169], v[202:205], v[84:87]
	v_mfma_f32_16x16x32_bf16 v[80:83], v[174:177], v[202:205], v[80:83]
	v_mfma_f32_16x16x32_bf16 v[68:71], v[166:169], v[210:213], v[68:71]
	v_mfma_f32_16x16x32_bf16 v[64:67], v[174:177], v[210:213], v[64:67]
	s_setprio 0
	s_barrier
	s_add_i32 s50, s41, s31
	v_lshl_add_u64 v[194:195], s[24:25], 0, v[128:129]
	s_mov_b32 m0, s50
	ds_read_b128 v[178:181], v149 offset:16384
	ds_read_b128 v[182:185], v149 offset:17408
	ds_read_b128 v[186:189], v149 offset:18432
	ds_read_b128 v[190:193], v149 offset:19456
	ds_read_b128 v[198:201], v149 offset:20480
	ds_read_b128 v[202:205], v149 offset:21504
	ds_read_b128 v[206:209], v149 offset:22528
	ds_read_b128 v[210:213], v149 offset:23552
	global_load_lds_dwordx4 v[194:195], off
	s_add_i32 m0, s50, 0x2000
	s_add_u32 s50, s24, 0x160000
	v_lshl_add_u64 v[214:215], s[24:25], 0, v[130:131]
	s_addc_u32 s51, s25, 0
	s_add_i32 s52, s42, s31
	global_load_lds_dwordx4 v[214:215], off
	v_lshl_add_u64 v[216:217], s[50:51], 0, v[128:129]
	s_mov_b32 m0, s52
	v_lshl_add_u64 v[218:219], s[26:27], 0, v[130:131]
	global_load_lds_dwordx4 v[216:217], off
	v_lshl_add_u64 v[216:217], s[50:51], 0, v[130:131]
	s_add_i32 m0, s52, 0x2000
	s_nop 0
	global_load_lds_dwordx4 v[216:217], off
	v_lshl_add_u64 v[216:217], s[26:27], 0, v[128:129]
	s_mov_b32 m0, s33
	s_nop 0
	global_load_lds_dwordx4 v[216:217], off
	s_mov_b32 m0, s34
	s_nop 0
	global_load_lds_dwordx4 v[218:219], off
	s_waitcnt vmcnt(8)
	s_waitcnt lgkmcnt(0)
	s_barrier
; #define PG8_STAGE(bufoff, gbase, voff) do { _Pragma("unroll") for (int _i = 0; _i < 2; ++_i) \
;         __builtin_amdgcn_global_load_lds((const unsigned*)((const char*)(gbase) + (voff)[_i]), (PG8_LAS unsigned*)(lds + (bufoff) + ldsw + _i * 8192), 16, 0, 0); } while (0)
; #define PG8_LDA(dst, b, h) do { _Pragma("unroll") for (int m = 0; m < 4; ++m) _Pragma("unroll") for (int k = 0; k < 2; ++k) dst[m][k] = *(const PG8_LAS bf16x8*)(lds + PG8_SA(b, h) + aoff + m * 2048 + k * 1024); } while (0)
; #define PG8_LDB(dst, b, h) do { _Pragma("unroll") for (int n = 0; n < 2; ++n) _Pragma("unroll") for (int k = 0; k < 2; ++k) dst[n][k] = *(const PG8_LAS bf16x8*)(lds + PG8_SB(b, h) + boff + n * 2048 + k * 1024); } while (0)
; #define PG8_MMA(ai, bj, At, Bt) do { __builtin_amdgcn_s_setprio(1); _Pragma("unroll") for (int m = 0; m < 4; ++m) _Pragma("unroll") for (int n = 0; n < 2; ++n) _Pragma("unroll") for (int k = 0; k < 2; ++k) \
;         acc[ai][bj][m][n] = __builtin_amdgcn_mfma_f32_16x16x32_bf16(Bt[n][k], At[m][k], acc[ai][bj][m][n], 0, 0, 0); __builtin_amdgcn_s_setprio(0); } while (0)
; #define PG8_WAIT_V(n) asm volatile("s_waitcnt vmcnt(" #n ")" ::: "memory")
; #define PG8_WAIT_L(n) asm volatile("s_waitcnt lgkmcnt(" #n ")" ::: "memory")
; #define PG8_BAR __builtin_amdgcn_s_barrier()
; #define PG8_SCHED __builtin_amdgcn_sched_barrier(0)
; template <class Epi, class Sched, bool ALIGN_EPI = false, bool SP2 = false>
; __device__ __forceinline__ void gemm_phase(PG8_LAS unsigned char* lds, const Gemm g, const Sched& S, const Epi& E) {
;     ...
;             PG8_WAIT_V(8); PG8_WAIT_L(0); PG8_BAR; PG8_MMA(1, 0, At, B0); PG8_MMA(1, 1, At, B1); PG8_BAR; PG8_SCHED;
;             PG8_LDB(B0, 1, 0); PG8_LDB(B1, 1, 1); PG8_SCHED; PG8_LDA(At, 1, 0); PG8_STAGE(PG8_SA(0, 1), a2 + hstep, voffA);
;             PG8_WAIT_V(8); PG8_WAIT_L(0); PG8_BAR; PG8_MMA(0, 0, At, B0); PG8_MMA(0, 1, At, B1); PG8_BAR; PG8_SCHED;
	s_setprio 1
	s_waitcnt lgkmcnt(0)
	v_mfma_f32_16x16x32_bf16 v[60:63], v[140:143], v[178:181], v[60:63]
	v_mfma_f32_16x16x32_bf16 v[56:59], v[154:157], v[178:181], v[56:59]
	v_mfma_f32_16x16x32_bf16 v[44:47], v[140:143], v[186:189], v[44:47]
	v_mfma_f32_16x16x32_bf16 v[40:43], v[154:157], v[186:189], v[40:43]
	v_mfma_f32_16x16x32_bf16 v[28:31], v[140:143], v[198:201], v[28:31]
	v_mfma_f32_16x16x32_bf16 v[24:27], v[154:157], v[198:201], v[24:27]
	v_mfma_f32_16x16x32_bf16 v[12:15], v[140:143], v[206:209], v[12:15]
	v_mfma_f32_16x16x32_bf16 v[8:11], v[154:157], v[206:209], v[8:11]
	v_mfma_f32_16x16x32_bf16 v[60:63], v[150:153], v[182:185], v[60:63]
	v_mfma_f32_16x16x32_bf16 v[56:59], v[158:161], v[182:185], v[56:59]
	v_mfma_f32_16x16x32_bf16 v[44:47], v[150:153], v[190:193], v[44:47]
	v_mfma_f32_16x16x32_bf16 v[40:43], v[158:161], v[190:193], v[40:43]
	v_mfma_f32_16x16x32_bf16 v[28:31], v[150:153], v[202:205], v[28:31]
	v_mfma_f32_16x16x32_bf16 v[24:27], v[158:161], v[202:205], v[24:27]
	v_mfma_f32_16x16x32_bf16 v[12:15], v[150:153], v[210:213], v[12:15]
	v_mfma_f32_16x16x32_bf16 v[8:11], v[158:161], v[210:213], v[8:11]
	v_mfma_f32_16x16x32_bf16 v[52:55], v[162:165], v[178:181], v[52:55]
	v_mfma_f32_16x16x32_bf16 v[48:51], v[170:173], v[178:181], v[48:51]
	v_mfma_f32_16x16x32_bf16 v[36:39], v[162:165], v[186:189], v[36:39]
	v_mfma_f32_16x16x32_bf16 v[32:35], v[170:173], v[186:189], v[32:35]
	v_mfma_f32_16x16x32_bf16 v[20:23], v[162:165], v[198:201], v[20:23]
	v_mfma_f32_16x16x32_bf16 v[16:19], v[170:173], v[198:201], v[16:19]
	v_mfma_f32_16x16x32_bf16 v[4:7], v[162:165], v[206:209], v[4:7]
	v_mfma_f32_16x16x32_bf16 v[0:3], v[170:173], v[206:209], v[0:3]
	v_mfma_f32_16x16x32_bf16 v[52:55], v[166:169], v[182:185], v[52:55]
	v_mfma_f32_16x16x32_bf16 v[48:51], v[174:177], v[182:185], v[48:51]
	v_mfma_f32_16x16x32_bf16 v[36:39], v[166:169], v[190:193], v[36:39]
	v_mfma_f32_16x16x32_bf16 v[32:35], v[174:177], v[190:193], v[32:35]
	v_mfma_f32_16x16x32_bf16 v[20:23], v[166:169], v[202:205], v[20:23]
	v_mfma_f32_16x16x32_bf16 v[16:19], v[174:177], v[202:205], v[16:19]
	v_mfma_f32_16x16x32_bf16 v[4:7], v[166:169], v[210:213], v[4:7]
	v_mfma_f32_16x16x32_bf16 v[0:3], v[174:177], v[210:213], v[0:3]
	s_setprio 0
	s_barrier
	s_add_i32 s50, 0, 0x18000
	s_add_i32 s51, 0, 0x1c000
	v_add_u32_e32 v158, s50, v145
	v_add_u32_e32 v174, s51, v145
	ds_read_b128 v[140:143], v158
	ds_read_b128 v[150:153], v158 offset:1024
	ds_read_b128 v[154:157], v158 offset:2048
	ds_read_b128 v[158:161], v158 offset:3072
	ds_read_b128 v[162:165], v174
	ds_read_b128 v[166:169], v174 offset:1024
	ds_read_b128 v[170:173], v174 offset:2048
	ds_read_b128 v[174:177], v174 offset:3072
	s_add_u32 s26, s26, 0x160000
	s_addc_u32 s27, s27, 0
	s_mov_b32 m0, s35
	v_lshl_add_u64 v[220:221], s[26:27], 0, v[128:129]
	ds_read_b128 v[178:181], v149 offset:32768
	ds_read_b128 v[182:185], v149 offset:33792
	ds_read_b128 v[186:189], v149 offset:34816
	ds_read_b128 v[190:193], v149 offset:35840
	ds_read_b128 v[198:201], v149 offset:36864
	ds_read_b128 v[202:205], v149 offset:37888
	ds_read_b128 v[206:209], v149 offset:38912
	ds_read_b128 v[210:213], v149 offset:39936
	global_load_lds_dwordx4 v[220:221], off
	v_lshl_add_u64 v[220:221], s[26:27], 0, v[130:131]
	s_mov_b32 m0, s36
	s_nop 0
	global_load_lds_dwordx4 v[220:221], off
	s_waitcnt vmcnt(8)
	s_waitcnt lgkmcnt(0)
	s_barrier
	s_setprio 1
	s_waitcnt lgkmcnt(0)
	v_mfma_f32_16x16x32_bf16 v[124:127], v[140:143], v[178:181], v[124:127]
	v_mfma_f32_16x16x32_bf16 v[120:123], v[154:157], v[178:181], v[120:123]
	v_mfma_f32_16x16x32_bf16 v[112:115], v[140:143], v[186:189], v[112:115]
	v_mfma_f32_16x16x32_bf16 v[104:107], v[154:157], v[186:189], v[104:107]
	v_mfma_f32_16x16x32_bf16 v[92:95], v[140:143], v[198:201], v[92:95]
	v_mfma_f32_16x16x32_bf16 v[88:91], v[154:157], v[198:201], v[88:91]
	v_mfma_f32_16x16x32_bf16 v[76:79], v[140:143], v[206:209], v[76:79]
	v_mfma_f32_16x16x32_bf16 v[72:75], v[154:157], v[206:209], v[72:75]
	v_mfma_f32_16x16x32_bf16 v[124:127], v[150:153], v[182:185], v[124:127]
	v_mfma_f32_16x16x32_bf16 v[120:123], v[158:161], v[182:185], v[120:123]
	v_mfma_f32_16x16x32_bf16 v[112:115], v[150:153], v[190:193], v[112:115]
	v_mfma_f32_16x16x32_bf16 v[104:107], v[158:161], v[190:193], v[104:107]
	v_mfma_f32_16x16x32_bf16 v[92:95], v[150:153], v[202:205], v[92:95]
	v_mfma_f32_16x16x32_bf16 v[88:91], v[158:161], v[202:205], v[88:91]
	v_mfma_f32_16x16x32_bf16 v[76:79], v[150:153], v[210:213], v[76:79]
	v_mfma_f32_16x16x32_bf16 v[72:75], v[158:161], v[210:213], v[72:75]
	v_mfma_f32_16x16x32_bf16 v[116:119], v[162:165], v[178:181], v[116:119]
	v_mfma_f32_16x16x32_bf16 v[108:111], v[170:173], v[178:181], v[108:111]
	v_mfma_f32_16x16x32_bf16 v[100:103], v[162:165], v[186:189], v[100:103]
	v_mfma_f32_16x16x32_bf16 v[96:99], v[170:173], v[186:189], v[96:99]
	v_mfma_f32_16x16x32_bf16 v[84:87], v[162:165], v[198:201], v[84:87]
	v_mfma_f32_16x16x32_bf16 v[80:83], v[170:173], v[198:201], v[80:83]
	v_mfma_f32_16x16x32_bf16 v[68:71], v[162:165], v[206:209], v[68:71]
	v_mfma_f32_16x16x32_bf16 v[64:67], v[170:173], v[206:209], v[64:67]
	v_mfma_f32_16x16x32_bf16 v[116:119], v[166:169], v[182:185], v[116:119]
	v_mfma_f32_16x16x32_bf16 v[108:111], v[174:177], v[182:185], v[108:111]
	v_mfma_f32_16x16x32_bf16 v[100:103], v[166:169], v[190:193], v[100:103]
	v_mfma_f32_16x16x32_bf16 v[96:99], v[174:177], v[190:193], v[96:99]
	v_mfma_f32_16x16x32_bf16 v[84:87], v[166:169], v[202:205], v[84:87]
	v_mfma_f32_16x16x32_bf16 v[80:83], v[174:177], v[202:205], v[80:83]
	v_mfma_f32_16x16x32_bf16 v[68:71], v[166:169], v[210:213], v[68:71]
	v_mfma_f32_16x16x32_bf16 v[64:67], v[174:177], v[210:213], v[64:67]
	s_setprio 0
	s_barrier
; #define PG8_STAGE(bufoff, gbase, voff) do { _Pragma("unroll") for (int _i = 0; _i < 2; ++_i) \
;         __builtin_amdgcn_global_load_lds((const unsigned*)((const char*)(gbase) + (voff)[_i]), (PG8_LAS unsigned*)(lds + (bufoff) + ldsw + _i * 8192), 16, 0, 0); } while (0)
; #define PG8_LDA(dst, b, h) do { _Pragma("unroll") for (int m = 0; m < 4; ++m) _Pragma("unroll") for (int k = 0; k < 2; ++k) dst[m][k] = *(const PG8_LAS bf16x8*)(lds + PG8_SA(b, h) + aoff + m * 2048 + k * 1024); } while (0)
; #define PG8_WAIT_V(n) asm volatile("s_waitcnt vmcnt(" #n ")" ::: "memory")
; template <class Epi, class Sched, bool ALIGN_EPI = false, bool SP2 = false>
; __device__ __forceinline__ void gemm_phase(PG8_LAS unsigned char* lds, const Gemm g, const Sched& S, const Epi& E) {
;     ...
;             PG8_LDA(At, 1, 1); PG8_STAGE(PG8_SB(1, 0), b3, voffB); PG8_STAGE(PG8_SB(1, 1), b3 + hstep, voffB); PG8_STAGE(PG8_SA(1, 0), a3, voffA);
;             PG8_WAIT_V(8); PG8_WAIT_L(0); PG8_BAR; PG8_MMA(1, 0, At, B0); PG8_MMA(1, 1, At, B1); PG8_BAR; PG8_SCHED;
;             } else {
;             PG8_LDB(B0, 0, 0); PG8_SCHED; PG8_LDA(At, 0, 0); PG8_STAGE(PG8_SA(1, 1), a1 + hstep, voffA);
;             PG8_WAIT_L(8); PG8_BAR; PG8_WAIT_L(0); PG8_MMA(0, 0, At, B0); PG8_BAR; PG8_SCHED;
;             PG8_LDB(B1, 0, 1); PG8_STAGE(PG8_SB(0, 0), b2, voffB);
;             PG8_BAR; PG8_WAIT_L(0); PG8_MMA(0, 1, At, B1); PG8_BAR;
;             PG8_LDA(At, 0, 1); PG8_STAGE(PG8_SA(0, 0), a2, voffA);
;             PG8_BAR; PG8_WAIT_L(0); PG8_MMA(1, 0, At, B0); PG8_BAR; PG8_SCHED;
;             PG8_STAGE(PG8_SB(0, 1), b2 + hstep, voffB);
;             PG8_WAIT_V(6); PG8_BAR; PG8_MMA(1, 1, At, B1); PG8_BAR;
;             PG8_LDB(B0, 1, 0); PG8_SCHED; PG8_LDA(At, 1, 0); PG8_STAGE(PG8_SA(0, 1), a2 + hstep, voffA);
;             PG8_WAIT_L(8); PG8_BAR; PG8_WAIT_L(0); PG8_MMA(0, 0, At, B0); PG8_BAR; PG8_SCHED;
;             PG8_LDB(B1, 1, 1); PG8_STAGE(PG8_SB(1, 0), b3, voffB);
;             PG8_BAR; PG8_WAIT_L(0); PG8_MMA(0, 1, At, B1); PG8_BAR;
;             PG8_LDA(At, 1, 1); PG8_STAGE(PG8_SA(1, 0), a3, voffA);
;             PG8_BAR; PG8_WAIT_L(0); PG8_MMA(1, 0, At, B0); PG8_BAR; PG8_SCHED;
;             PG8_STAGE(PG8_SB(1, 1), b3 + hstep, voffB);
;             PG8_WAIT_V(6); PG8_BAR; PG8_MMA(1, 1, At, B1); PG8_BAR;
;             }
;         }
;         if constexpr (ALIGN_EPI) { if (wr == 0) PG8_BAR; }
	s_add_i32 s26, s50, s31
	v_lshl_add_u64 v[194:195], v[194:195], 0, s[16:17]
	s_mov_b32 m0, s26
	ds_read_b128 v[178:181], v149 offset:49152
	ds_read_b128 v[182:185], v149 offset:50176
	ds_read_b128 v[186:189], v149 offset:51200
	ds_read_b128 v[190:193], v149 offset:52224
	ds_read_b128 v[198:201], v149 offset:53248
	ds_read_b128 v[202:205], v149 offset:54272
	ds_read_b128 v[206:209], v149 offset:55296
	ds_read_b128 v[210:213], v149 offset:56320
	global_load_lds_dwordx4 v[194:195], off
	s_add_i32 m0, s26, 0x2000
	s_add_u32 s24, s24, 0x160080
	v_lshl_add_u64 v[194:195], v[214:215], 0, s[16:17]
	s_addc_u32 s25, s25, 0
	s_add_i32 s26, s51, s31
	global_load_lds_dwordx4 v[194:195], off
	v_lshl_add_u64 v[194:195], s[24:25], 0, v[128:129]
	s_mov_b32 m0, s26
	s_nop 0
	global_load_lds_dwordx4 v[194:195], off
	v_lshl_add_u64 v[194:195], s[24:25], 0, v[130:131]
	s_add_i32 m0, s26, 0x2000
	s_nop 0
	global_load_lds_dwordx4 v[194:195], off
	v_lshl_add_u64 v[194:195], v[216:217], 0, s[16:17]
	s_mov_b32 m0, s38
	s_nop 0
	global_load_lds_dwordx4 v[194:195], off
	v_lshl_add_u64 v[194:195], v[218:219], 0, s[16:17]
	s_mov_b32 m0, s39
	s_nop 0
	global_load_lds_dwordx4 v[194:195], off
	s_waitcnt vmcnt(8)
	s_waitcnt lgkmcnt(0)
	s_barrier
	s_setprio 1
	s_waitcnt lgkmcnt(0)
	v_mfma_f32_16x16x32_bf16 v[60:63], v[140:143], v[178:181], v[60:63]
	v_mfma_f32_16x16x32_bf16 v[56:59], v[154:157], v[178:181], v[56:59]
	v_mfma_f32_16x16x32_bf16 v[44:47], v[140:143], v[186:189], v[44:47]
	v_mfma_f32_16x16x32_bf16 v[40:43], v[154:157], v[186:189], v[40:43]
	v_mfma_f32_16x16x32_bf16 v[28:31], v[140:143], v[198:201], v[28:31]
	v_mfma_f32_16x16x32_bf16 v[24:27], v[154:157], v[198:201], v[24:27]
	v_mfma_f32_16x16x32_bf16 v[12:15], v[140:143], v[206:209], v[12:15]
	v_mfma_f32_16x16x32_bf16 v[8:11], v[154:157], v[206:209], v[8:11]
	v_mfma_f32_16x16x32_bf16 v[60:63], v[150:153], v[182:185], v[60:63]
	v_mfma_f32_16x16x32_bf16 v[56:59], v[158:161], v[182:185], v[56:59]
	v_mfma_f32_16x16x32_bf16 v[44:47], v[150:153], v[190:193], v[44:47]
	v_mfma_f32_16x16x32_bf16 v[40:43], v[158:161], v[190:193], v[40:43]
	v_mfma_f32_16x16x32_bf16 v[28:31], v[150:153], v[202:205], v[28:31]
	v_mfma_f32_16x16x32_bf16 v[24:27], v[158:161], v[202:205], v[24:27]
	v_mfma_f32_16x16x32_bf16 v[12:15], v[150:153], v[210:213], v[12:15]
	v_mfma_f32_16x16x32_bf16 v[8:11], v[158:161], v[210:213], v[8:11]
	v_mfma_f32_16x16x32_bf16 v[52:55], v[162:165], v[178:181], v[52:55]
	v_mfma_f32_16x16x32_bf16 v[48:51], v[170:173], v[178:181], v[48:51]
	v_mfma_f32_16x16x32_bf16 v[36:39], v[162:165], v[186:189], v[36:39]
	v_mfma_f32_16x16x32_bf16 v[32:35], v[170:173], v[186:189], v[32:35]
	v_mfma_f32_16x16x32_bf16 v[20:23], v[162:165], v[198:201], v[20:23]
	v_mfma_f32_16x16x32_bf16 v[16:19], v[170:173], v[198:201], v[16:19]
	v_mfma_f32_16x16x32_bf16 v[4:7], v[162:165], v[206:209], v[4:7]
	v_mfma_f32_16x16x32_bf16 v[0:3], v[170:173], v[206:209], v[0:3]
	v_mfma_f32_16x16x32_bf16 v[52:55], v[166:169], v[182:185], v[52:55]
	v_mfma_f32_16x16x32_bf16 v[48:51], v[174:177], v[182:185], v[48:51]
	v_mfma_f32_16x16x32_bf16 v[36:39], v[166:169], v[190:193], v[36:39]
	v_mfma_f32_16x16x32_bf16 v[32:35], v[174:177], v[190:193], v[32:35]
	v_mfma_f32_16x16x32_bf16 v[20:23], v[166:169], v[202:205], v[20:23]
	v_mfma_f32_16x16x32_bf16 v[16:19], v[174:177], v[202:205], v[16:19]
	v_mfma_f32_16x16x32_bf16 v[4:7], v[166:169], v[210:213], v[4:7]
	v_mfma_f32_16x16x32_bf16 v[0:3], v[174:177], v[210:213], v[0:3]
	s_setprio 0
	s_barrier
	s_add_i32 s49, s49, 2
	s_add_u32 s47, s47, 0x100
	s_addc_u32 s48, s48, 0
	s_add_u32 s22, s22, 0x100
	s_addc_u32 s23, s23, 0
	s_cmpk_gt_u32 s49, 0x55
	s_cbranch_scc0 .LBB0_1350
	s_and_b64 vcc, exec, s[18:19]
	s_cbranch_vccz .LBB0_1353
	s_barrier

; #define PG8_STAGE(bufoff, gbase, voff) do { _Pragma("unroll") for (int _i = 0; _i < 2; ++_i) \
;         __builtin_amdgcn_global_load_lds((const unsigned*)((const char*)(gbase) + (voff)[_i]), (PG8_LAS unsigned*)(lds + (bufoff) + ldsw + _i * 8192), 16, 0, 0); } while (0)
; #define PG8_LDA(dst, b, h) do { _Pragma("unroll") for (int m = 0; m < 4; ++m) _Pragma("unroll") for (int k = 0; k < 2; ++k) dst[m][k] = *(const PG8_LAS bf16x8*)(lds + PG8_SA(b, h) + aoff + m * 2048 + k * 1024); } while (0)
; #define PG8_LDB(dst, b, h) do { _Pragma("unroll") for (int n = 0; n < 2; ++n) _Pragma("unroll") for (int k = 0; k < 2; ++k) dst[n][k] = *(const PG8_LAS bf16x8*)(lds + PG8_SB(b, h) + boff + n * 2048 + k * 1024); } while (0)
; #define PG8_MMA(ai, bj, At, Bt) do { __builtin_amdgcn_s_setprio(1); _Pragma("unroll") for (int m = 0; m < 4; ++m) _Pragma("unroll") for (int n = 0; n < 2; ++n) _Pragma("unroll") for (int k = 0; k < 2; ++k) \
;         acc[ai][bj][m][n] = __builtin_amdgcn_mfma_f32_16x16x32_bf16(Bt[n][k], At[m][k], acc[ai][bj][m][n], 0, 0, 0); __builtin_amdgcn_s_setprio(0); } while (0)
; #define PG8_WAIT_V(n) asm volatile("s_waitcnt vmcnt(" #n ")" ::: "memory")
; #define PG8_BAR __builtin_amdgcn_s_barrier()
; template <class Epi, class Sched, bool ALIGN_EPI = false, bool SP2 = false>
; __device__ __forceinline__ void gemm_phase(PG8_LAS unsigned char* lds, const Gemm g, const Sched& S, const Epi& E) {
;     ...
;         for (int t = 0; t < nt; t += 2) {
;             const bool last = (t == nt - 2);
;             const char* a1 = cA + (size_t)(t + 1) * kstep;
;             const char* a2 = last ? nA : cA + (size_t)(t + 2) * kstep; const char* b2 = last ? nB : cB + (size_t)(t + 2) * kstep;
;             const char* a3 = a2 + kstep; const char* b3 = b2 + kstep;
;             if (last && has_next) S.a_ready(nxt);
;             if constexpr (SP2) {
;             PG8_LDB(B0, 0, 0); PG8_LDB(B1, 0, 1); PG8_SCHED; PG8_LDA(At, 0, 0); PG8_STAGE(PG8_SA(1, 1), a1 + hstep, voffA);
;             PG8_WAIT_V(8); PG8_WAIT_L(0); PG8_BAR; PG8_MMA(0, 0, At, B0); PG8_MMA(0, 1, At, B1); PG8_BAR; PG8_SCHED;
;             PG8_LDA(At, 0, 1); PG8_STAGE(PG8_SB(0, 0), b2, voffB); PG8_STAGE(PG8_SB(0, 1), b2 + hstep, voffB); PG8_STAGE(PG8_SA(0, 0), a2, voffA);
;             PG8_WAIT_V(8); PG8_WAIT_L(0); PG8_BAR; PG8_MMA(1, 0, At, B0); PG8_MMA(1, 1, At, B1); PG8_BAR; PG8_SCHED;
.LBB0_1487:
	ds_read_b128 v[152:155], v149
	ds_read_b128 v[156:159], v149 offset:1024
	ds_read_b128 v[160:163], v149 offset:2048
	ds_read_b128 v[164:167], v149 offset:3072
	ds_read_b128 v[168:171], v150
	ds_read_b128 v[172:175], v150 offset:1024
	ds_read_b128 v[176:179], v150 offset:2048
	ds_read_b128 v[180:183], v150 offset:3072
	s_add_u32 s40, s38, 0xfff80080
	s_addc_u32 s41, s39, -1
	s_cmp_eq_u32 s65, 28
	s_cselect_b32 s45, s29, s41
	s_cselect_b32 s44, s61, s40
	s_cselect_b32 s41, s27, s64
	s_cselect_b32 s40, s62, s63
	v_lshl_add_u64 v[144:145], s[38:39], 0, v[138:139]
	s_add_i32 m0, s37, 0xc000
	ds_read_b128 v[184:187], v151
	ds_read_b128 v[188:191], v151 offset:1024
	ds_read_b128 v[192:195], v151 offset:2048
	ds_read_b128 v[198:201], v151 offset:3072
	ds_read_b128 v[202:205], v151 offset:4096
	ds_read_b128 v[206:209], v151 offset:5120
	ds_read_b128 v[210:213], v151 offset:6144
	ds_read_b128 v[214:217], v151 offset:7168
	global_load_lds_dwordx4 v[144:145], off
	v_lshl_add_u64 v[144:145], s[38:39], 0, v[136:137]
	s_add_i32 m0, s37, 0xe000
	s_nop 0
	global_load_lds_dwordx4 v[144:145], off
	s_waitcnt vmcnt(8)
	s_waitcnt lgkmcnt(0)
	s_barrier
	s_setprio 1
	s_waitcnt lgkmcnt(0)
	v_mfma_f32_16x16x32_bf16 v[124:127], v[152:155], v[184:187], v[124:127]
	v_mfma_f32_16x16x32_bf16 v[120:123], v[160:163], v[184:187], v[120:123]
	v_mfma_f32_16x16x32_bf16 v[116:119], v[152:155], v[192:195], v[116:119]
	v_mfma_f32_16x16x32_bf16 v[108:111], v[160:163], v[192:195], v[108:111]
	v_mfma_f32_16x16x32_bf16 v[100:103], v[152:155], v[202:205], v[100:103]
	v_mfma_f32_16x16x32_bf16 v[92:95], v[160:163], v[202:205], v[92:95]
	v_mfma_f32_16x16x32_bf16 v[84:87], v[152:155], v[210:213], v[84:87]
	v_mfma_f32_16x16x32_bf16 v[76:79], v[160:163], v[210:213], v[76:79]
	v_mfma_f32_16x16x32_bf16 v[124:127], v[156:159], v[188:191], v[124:127]
	v_mfma_f32_16x16x32_bf16 v[120:123], v[164:167], v[188:191], v[120:123]
	v_mfma_f32_16x16x32_bf16 v[116:119], v[156:159], v[198:201], v[116:119]
	v_mfma_f32_16x16x32_bf16 v[108:111], v[164:167], v[198:201], v[108:111]
	v_mfma_f32_16x16x32_bf16 v[100:103], v[156:159], v[206:209], v[100:103]
	v_mfma_f32_16x16x32_bf16 v[92:95], v[164:167], v[206:209], v[92:95]
	v_mfma_f32_16x16x32_bf16 v[84:87], v[156:159], v[214:217], v[84:87]
	v_mfma_f32_16x16x32_bf16 v[76:79], v[164:167], v[214:217], v[76:79]
	v_mfma_f32_16x16x32_bf16 v[112:115], v[168:171], v[184:187], v[112:115]
	v_mfma_f32_16x16x32_bf16 v[104:107], v[176:179], v[184:187], v[104:107]
	v_mfma_f32_16x16x32_bf16 v[96:99], v[168:171], v[192:195], v[96:99]
	v_mfma_f32_16x16x32_bf16 v[88:91], v[176:179], v[192:195], v[88:91]
	v_mfma_f32_16x16x32_bf16 v[80:83], v[168:171], v[202:205], v[80:83]
	v_mfma_f32_16x16x32_bf16 v[72:75], v[176:179], v[202:205], v[72:75]
	v_mfma_f32_16x16x32_bf16 v[68:71], v[168:171], v[210:213], v[68:71]
	v_mfma_f32_16x16x32_bf16 v[64:67], v[176:179], v[210:213], v[64:67]
	v_mfma_f32_16x16x32_bf16 v[112:115], v[172:175], v[188:191], v[112:115]
	v_mfma_f32_16x16x32_bf16 v[104:107], v[180:183], v[188:191], v[104:107]
	v_mfma_f32_16x16x32_bf16 v[96:99], v[172:175], v[198:201], v[96:99]
	v_mfma_f32_16x16x32_bf16 v[88:91], v[180:183], v[198:201], v[88:91]
	v_mfma_f32_16x16x32_bf16 v[80:83], v[172:175], v[206:209], v[80:83]
	v_mfma_f32_16x16x32_bf16 v[72:75], v[180:183], v[206:209], v[72:75]
	v_mfma_f32_16x16x32_bf16 v[68:71], v[172:175], v[214:217], v[68:71]
	v_mfma_f32_16x16x32_bf16 v[64:67], v[180:183], v[214:217], v[64:67]
	s_setprio 0
	s_barrier
	s_add_i32 s66, s54, s46
	v_lshl_add_u64 v[144:145], s[40:41], 0, v[130:131]
	s_mov_b32 m0, s66
	ds_read_b128 v[184:187], v151 offset:16384
	ds_read_b128 v[188:191], v151 offset:17408
	ds_read_b128 v[192:195], v151 offset:18432
	ds_read_b128 v[198:201], v151 offset:19456
	ds_read_b128 v[202:205], v151 offset:20480
	ds_read_b128 v[206:209], v151 offset:21504
	ds_read_b128 v[210:213], v151 offset:22528
	ds_read_b128 v[214:217], v151 offset:23552
	global_load_lds_dwordx4 v[144:145], off
	s_add_i32 m0, s66, 0x2000
	s_add_u32 s66, s40, 0x80000
	v_lshl_add_u64 v[218:219], s[40:41], 0, v[134:135]
	s_addc_u32 s67, s41, 0
	s_add_i32 s68, s55, s46
	global_load_lds_dwordx4 v[218:219], off
	v_lshl_add_u64 v[220:221], s[66:67], 0, v[130:131]
	s_mov_b32 m0, s68
	v_lshl_add_u64 v[222:223], s[44:45], 0, v[132:133]
	global_load_lds_dwordx4 v[220:221], off
	v_lshl_add_u64 v[220:221], s[66:67], 0, v[134:135]
	s_add_i32 m0, s68, 0x2000
	s_nop 0
	global_load_lds_dwordx4 v[220:221], off
	v_lshl_add_u64 v[220:221], s[44:45], 0, v[128:129]
	s_mov_b32 m0, s37
	s_nop 0
	global_load_lds_dwordx4 v[220:221], off
	s_mov_b32 m0, s47
	s_nop 0
	global_load_lds_dwordx4 v[222:223], off
	s_waitcnt vmcnt(8)
	s_waitcnt lgkmcnt(0)
	s_barrier
; #define PG8_STAGE(bufoff, gbase, voff) do { _Pragma("unroll") for (int _i = 0; _i < 2; ++_i) \
;         __builtin_amdgcn_global_load_lds((const unsigned*)((const char*)(gbase) + (voff)[_i]), (PG8_LAS unsigned*)(lds + (bufoff) + ldsw + _i * 8192), 16, 0, 0); } while (0)
; #define PG8_LDA(dst, b, h) do { _Pragma("unroll") for (int m = 0; m < 4; ++m) _Pragma("unroll") for (int k = 0; k < 2; ++k) dst[m][k] = *(const PG8_LAS bf16x8*)(lds + PG8_SA(b, h) + aoff + m * 2048 + k * 1024); } while (0)
; #define PG8_LDB(dst, b, h) do { _Pragma("unroll") for (int n = 0; n < 2; ++n) _Pragma("unroll") for (int k = 0; k < 2; ++k) dst[n][k] = *(const PG8_LAS bf16x8*)(lds + PG8_SB(b, h) + boff + n * 2048 + k * 1024); } while (0)
; #define PG8_MMA(ai, bj, At, Bt) do { __builtin_amdgcn_s_setprio(1); _Pragma("unroll") for (int m = 0; m < 4; ++m) _Pragma("unroll") for (int n = 0; n < 2; ++n) _Pragma("unroll") for (int k = 0; k < 2; ++k) \
;         acc[ai][bj][m][n] = __builtin_amdgcn_mfma_f32_16x16x32_bf16(Bt[n][k], At[m][k], acc[ai][bj][m][n], 0, 0, 0); __builtin_amdgcn_s_setprio(0); } while (0)
; #define PG8_WAIT_V(n) asm volatile("s_waitcnt vmcnt(" #n ")" ::: "memory")
; #define PG8_WAIT_L(n) asm volatile("s_waitcnt lgkmcnt(" #n ")" ::: "memory")
; #define PG8_BAR __builtin_amdgcn_s_barrier()
; #define PG8_SCHED __builtin_amdgcn_sched_barrier(0)
; template <class Epi, class Sched, bool ALIGN_EPI = false, bool SP2 = false>
; __device__ __forceinline__ void gemm_phase(PG8_LAS unsigned char* lds, const Gemm g, const Sched& S, const Epi& E) {
;     ...
;             PG8_WAIT_V(8); PG8_WAIT_L(0); PG8_BAR; PG8_MMA(1, 0, At, B0); PG8_MMA(1, 1, At, B1); PG8_BAR; PG8_SCHED;
;             PG8_LDB(B0, 1, 0); PG8_LDB(B1, 1, 1); PG8_SCHED; PG8_LDA(At, 1, 0); PG8_STAGE(PG8_SA(0, 1), a2 + hstep, voffA);
;             PG8_WAIT_V(8); PG8_WAIT_L(0); PG8_BAR; PG8_MMA(0, 0, At, B0); PG8_MMA(0, 1, At, B1); PG8_BAR; PG8_SCHED;
	s_setprio 1
	s_waitcnt lgkmcnt(0)
	v_mfma_f32_16x16x32_bf16 v[60:63], v[152:155], v[184:187], v[60:63]
	v_mfma_f32_16x16x32_bf16 v[56:59], v[160:163], v[184:187], v[56:59]
	v_mfma_f32_16x16x32_bf16 v[52:55], v[152:155], v[192:195], v[52:55]
	v_mfma_f32_16x16x32_bf16 v[44:47], v[160:163], v[192:195], v[44:47]
	v_mfma_f32_16x16x32_bf16 v[36:39], v[152:155], v[202:205], v[36:39]
	v_mfma_f32_16x16x32_bf16 v[28:31], v[160:163], v[202:205], v[28:31]
	v_mfma_f32_16x16x32_bf16 v[20:23], v[152:155], v[210:213], v[20:23]
	v_mfma_f32_16x16x32_bf16 v[12:15], v[160:163], v[210:213], v[12:15]
	v_mfma_f32_16x16x32_bf16 v[60:63], v[156:159], v[188:191], v[60:63]
	v_mfma_f32_16x16x32_bf16 v[56:59], v[164:167], v[188:191], v[56:59]
	v_mfma_f32_16x16x32_bf16 v[52:55], v[156:159], v[198:201], v[52:55]
	v_mfma_f32_16x16x32_bf16 v[44:47], v[164:167], v[198:201], v[44:47]
	v_mfma_f32_16x16x32_bf16 v[36:39], v[156:159], v[206:209], v[36:39]
	v_mfma_f32_16x16x32_bf16 v[28:31], v[164:167], v[206:209], v[28:31]
	v_mfma_f32_16x16x32_bf16 v[20:23], v[156:159], v[214:217], v[20:23]
	v_mfma_f32_16x16x32_bf16 v[12:15], v[164:167], v[214:217], v[12:15]
	v_mfma_f32_16x16x32_bf16 v[48:51], v[168:171], v[184:187], v[48:51]
	v_mfma_f32_16x16x32_bf16 v[40:43], v[176:179], v[184:187], v[40:43]
	v_mfma_f32_16x16x32_bf16 v[32:35], v[168:171], v[192:195], v[32:35]
	v_mfma_f32_16x16x32_bf16 v[24:27], v[176:179], v[192:195], v[24:27]
	v_mfma_f32_16x16x32_bf16 v[16:19], v[168:171], v[202:205], v[16:19]
	v_mfma_f32_16x16x32_bf16 v[8:11], v[176:179], v[202:205], v[8:11]
	v_mfma_f32_16x16x32_bf16 v[4:7], v[168:171], v[210:213], v[4:7]
	v_mfma_f32_16x16x32_bf16 v[0:3], v[176:179], v[210:213], v[0:3]
	v_mfma_f32_16x16x32_bf16 v[48:51], v[172:175], v[188:191], v[48:51]
	v_mfma_f32_16x16x32_bf16 v[40:43], v[180:183], v[188:191], v[40:43]
	v_mfma_f32_16x16x32_bf16 v[32:35], v[172:175], v[198:201], v[32:35]
	v_mfma_f32_16x16x32_bf16 v[24:27], v[180:183], v[198:201], v[24:27]
	v_mfma_f32_16x16x32_bf16 v[16:19], v[172:175], v[206:209], v[16:19]
	v_mfma_f32_16x16x32_bf16 v[8:11], v[180:183], v[206:209], v[8:11]
	v_mfma_f32_16x16x32_bf16 v[4:7], v[172:175], v[214:217], v[4:7]
	v_mfma_f32_16x16x32_bf16 v[0:3], v[180:183], v[214:217], v[0:3]
	s_setprio 0
	s_barrier
	s_add_i32 s66, 0, 0x18000
	s_add_i32 s67, 0, 0x1c000
	v_add_u32_e32 v164, s66, v147
	v_add_u32_e32 v180, s67, v147
	ds_read_b128 v[152:155], v164
	ds_read_b128 v[156:159], v164 offset:1024
	ds_read_b128 v[160:163], v164 offset:2048
	ds_read_b128 v[164:167], v164 offset:3072
	ds_read_b128 v[168:171], v180
	ds_read_b128 v[172:175], v180 offset:1024
	ds_read_b128 v[176:179], v180 offset:2048
	ds_read_b128 v[180:183], v180 offset:3072
	s_add_u32 s44, s44, 0x80000
	s_addc_u32 s45, s45, 0
	s_mov_b32 m0, s48
	v_lshl_add_u64 v[224:225], s[44:45], 0, v[128:129]
	ds_read_b128 v[184:187], v151 offset:32768
	ds_read_b128 v[188:191], v151 offset:33792
	ds_read_b128 v[192:195], v151 offset:34816
	ds_read_b128 v[198:201], v151 offset:35840
	ds_read_b128 v[202:205], v151 offset:36864
	ds_read_b128 v[206:209], v151 offset:37888
	ds_read_b128 v[210:213], v151 offset:38912
	ds_read_b128 v[214:217], v151 offset:39936
	global_load_lds_dwordx4 v[224:225], off
	v_lshl_add_u64 v[224:225], s[44:45], 0, v[132:133]
	s_mov_b32 m0, s49
	s_nop 0
	global_load_lds_dwordx4 v[224:225], off
	s_waitcnt vmcnt(8)
	s_waitcnt lgkmcnt(0)
	s_barrier
	s_setprio 1
	s_waitcnt lgkmcnt(0)
	v_mfma_f32_16x16x32_bf16 v[124:127], v[152:155], v[184:187], v[124:127]
	v_mfma_f32_16x16x32_bf16 v[120:123], v[160:163], v[184:187], v[120:123]
	v_mfma_f32_16x16x32_bf16 v[116:119], v[152:155], v[192:195], v[116:119]
	v_mfma_f32_16x16x32_bf16 v[108:111], v[160:163], v[192:195], v[108:111]
	v_mfma_f32_16x16x32_bf16 v[100:103], v[152:155], v[202:205], v[100:103]
	v_mfma_f32_16x16x32_bf16 v[92:95], v[160:163], v[202:205], v[92:95]
	v_mfma_f32_16x16x32_bf16 v[84:87], v[152:155], v[210:213], v[84:87]
	v_mfma_f32_16x16x32_bf16 v[76:79], v[160:163], v[210:213], v[76:79]
	v_mfma_f32_16x16x32_bf16 v[124:127], v[156:159], v[188:191], v[124:127]
	v_mfma_f32_16x16x32_bf16 v[120:123], v[164:167], v[188:191], v[120:123]
	v_mfma_f32_16x16x32_bf16 v[116:119], v[156:159], v[198:201], v[116:119]
	v_mfma_f32_16x16x32_bf16 v[108:111], v[164:167], v[198:201], v[108:111]
	v_mfma_f32_16x16x32_bf16 v[100:103], v[156:159], v[206:209], v[100:103]
	v_mfma_f32_16x16x32_bf16 v[92:95], v[164:167], v[206:209], v[92:95]
	v_mfma_f32_16x16x32_bf16 v[84:87], v[156:159], v[214:217], v[84:87]
	v_mfma_f32_16x16x32_bf16 v[76:79], v[164:167], v[214:217], v[76:79]
	v_mfma_f32_16x16x32_bf16 v[112:115], v[168:171], v[184:187], v[112:115]
	v_mfma_f32_16x16x32_bf16 v[104:107], v[176:179], v[184:187], v[104:107]
	v_mfma_f32_16x16x32_bf16 v[96:99], v[168:171], v[192:195], v[96:99]
	v_mfma_f32_16x16x32_bf16 v[88:91], v[176:179], v[192:195], v[88:91]
	v_mfma_f32_16x16x32_bf16 v[80:83], v[168:171], v[202:205], v[80:83]
	v_mfma_f32_16x16x32_bf16 v[72:75], v[176:179], v[202:205], v[72:75]
	v_mfma_f32_16x16x32_bf16 v[68:71], v[168:171], v[210:213], v[68:71]
	v_mfma_f32_16x16x32_bf16 v[64:67], v[176:179], v[210:213], v[64:67]
	v_mfma_f32_16x16x32_bf16 v[112:115], v[172:175], v[188:191], v[112:115]
	v_mfma_f32_16x16x32_bf16 v[104:107], v[180:183], v[188:191], v[104:107]
	v_mfma_f32_16x16x32_bf16 v[96:99], v[172:175], v[198:201], v[96:99]
	v_mfma_f32_16x16x32_bf16 v[88:91], v[180:183], v[198:201], v[88:91]
	v_mfma_f32_16x16x32_bf16 v[80:83], v[172:175], v[206:209], v[80:83]
	v_mfma_f32_16x16x32_bf16 v[72:75], v[180:183], v[206:209], v[72:75]
	v_mfma_f32_16x16x32_bf16 v[68:71], v[172:175], v[214:217], v[68:71]
	v_mfma_f32_16x16x32_bf16 v[64:67], v[180:183], v[214:217], v[64:67]
	s_setprio 0
	s_barrier
; #define PG8_STAGE(bufoff, gbase, voff) do { _Pragma("unroll") for (int _i = 0; _i < 2; ++_i) \
;         __builtin_amdgcn_global_load_lds((const unsigned*)((const char*)(gbase) + (voff)[_i]), (PG8_LAS unsigned*)(lds + (bufoff) + ldsw + _i * 8192), 16, 0, 0); } while (0)
; #define PG8_LDA(dst, b, h) do { _Pragma("unroll") for (int m = 0; m < 4; ++m) _Pragma("unroll") for (int k = 0; k < 2; ++k) dst[m][k] = *(const PG8_LAS bf16x8*)(lds + PG8_SA(b, h) + aoff + m * 2048 + k * 1024); } while (0)
; #define PG8_WAIT_V(n) asm volatile("s_waitcnt vmcnt(" #n ")" ::: "memory")
; template <class Epi, class Sched, bool ALIGN_EPI = false, bool SP2 = false>
; __device__ __forceinline__ void gemm_phase(PG8_LAS unsigned char* lds, const Gemm g, const Sched& S, const Epi& E) {
;     ...
;             PG8_LDA(At, 1, 1); PG8_STAGE(PG8_SB(1, 0), b3, voffB); PG8_STAGE(PG8_SB(1, 1), b3 + hstep, voffB); PG8_STAGE(PG8_SA(1, 0), a3, voffA);
;             PG8_WAIT_V(8); PG8_WAIT_L(0); PG8_BAR; PG8_MMA(1, 0, At, B0); PG8_MMA(1, 1, At, B1); PG8_BAR; PG8_SCHED;
;             } else {
;             PG8_LDB(B0, 0, 0); PG8_SCHED; PG8_LDA(At, 0, 0); PG8_STAGE(PG8_SA(1, 1), a1 + hstep, voffA);
;             PG8_WAIT_L(8); PG8_BAR; PG8_WAIT_L(0); PG8_MMA(0, 0, At, B0); PG8_BAR; PG8_SCHED;
;             PG8_LDB(B1, 0, 1); PG8_STAGE(PG8_SB(0, 0), b2, voffB);
;             PG8_BAR; PG8_WAIT_L(0); PG8_MMA(0, 1, At, B1); PG8_BAR;
;             PG8_LDA(At, 0, 1); PG8_STAGE(PG8_SA(0, 0), a2, voffA);
;             PG8_BAR; PG8_WAIT_L(0); PG8_MMA(1, 0, At, B0); PG8_BAR; PG8_SCHED;
;             PG8_STAGE(PG8_SB(0, 1), b2 + hstep, voffB);
;             PG8_WAIT_V(6); PG8_BAR; PG8_MMA(1, 1, At, B1); PG8_BAR;
;             PG8_LDB(B0, 1, 0); PG8_SCHED; PG8_LDA(At, 1, 0); PG8_STAGE(PG8_SA(0, 1), a2 + hstep, voffA);
;             PG8_WAIT_L(8); PG8_BAR; PG8_WAIT_L(0); PG8_MMA(0, 0, At, B0); PG8_BAR; PG8_SCHED;
;             PG8_LDB(B1, 1, 1); PG8_STAGE(PG8_SB(1, 0), b3, voffB);
;             PG8_BAR; PG8_WAIT_L(0); PG8_MMA(0, 1, At, B1); PG8_BAR;
;             PG8_LDA(At, 1, 1); PG8_STAGE(PG8_SA(1, 0), a3, voffA);
;             PG8_BAR; PG8_WAIT_L(0); PG8_MMA(1, 0, At, B0); PG8_BAR; PG8_SCHED;
;             PG8_STAGE(PG8_SB(1, 1), b3 + hstep, voffB);
;             PG8_WAIT_V(6); PG8_BAR; PG8_MMA(1, 1, At, B1); PG8_BAR;
;             }
;         }
;         if constexpr (ALIGN_EPI) { if (wr == 0) PG8_BAR; }
	s_add_i32 s44, s66, s46
	v_lshl_add_u64 v[144:145], v[144:145], 0, s[14:15]
	s_mov_b32 m0, s44
	ds_read_b128 v[184:187], v151 offset:49152
	ds_read_b128 v[188:191], v151 offset:50176
	ds_read_b128 v[192:195], v151 offset:51200
	ds_read_b128 v[198:201], v151 offset:52224
	ds_read_b128 v[202:205], v151 offset:53248
	ds_read_b128 v[206:209], v151 offset:54272
	ds_read_b128 v[210:213], v151 offset:55296
	ds_read_b128 v[214:217], v151 offset:56320
	global_load_lds_dwordx4 v[144:145], off
	s_add_i32 m0, s44, 0x2000
	s_add_u32 s40, s40, 0x80080
	v_lshl_add_u64 v[144:145], v[218:219], 0, s[14:15]
	s_addc_u32 s41, s41, 0
	s_add_i32 s44, s67, s46
	global_load_lds_dwordx4 v[144:145], off
	v_lshl_add_u64 v[144:145], s[40:41], 0, v[130:131]
	s_mov_b32 m0, s44
	s_nop 0
	global_load_lds_dwordx4 v[144:145], off
	v_lshl_add_u64 v[144:145], s[40:41], 0, v[134:135]
	s_add_i32 m0, s44, 0x2000
	s_nop 0
	global_load_lds_dwordx4 v[144:145], off
	v_lshl_add_u64 v[144:145], v[220:221], 0, s[14:15]
	s_mov_b32 m0, s51
	s_nop 0
	global_load_lds_dwordx4 v[144:145], off
	v_lshl_add_u64 v[144:145], v[222:223], 0, s[14:15]
	s_mov_b32 m0, s52
	s_nop 0
	global_load_lds_dwordx4 v[144:145], off
	s_waitcnt vmcnt(8)
	s_waitcnt lgkmcnt(0)
	s_barrier
	s_setprio 1
	s_waitcnt lgkmcnt(0)
	v_mfma_f32_16x16x32_bf16 v[60:63], v[152:155], v[184:187], v[60:63]
	v_mfma_f32_16x16x32_bf16 v[56:59], v[160:163], v[184:187], v[56:59]
	v_mfma_f32_16x16x32_bf16 v[52:55], v[152:155], v[192:195], v[52:55]
	v_mfma_f32_16x16x32_bf16 v[44:47], v[160:163], v[192:195], v[44:47]
	v_mfma_f32_16x16x32_bf16 v[36:39], v[152:155], v[202:205], v[36:39]
	v_mfma_f32_16x16x32_bf16 v[28:31], v[160:163], v[202:205], v[28:31]
	v_mfma_f32_16x16x32_bf16 v[20:23], v[152:155], v[210:213], v[20:23]
	v_mfma_f32_16x16x32_bf16 v[12:15], v[160:163], v[210:213], v[12:15]
	v_mfma_f32_16x16x32_bf16 v[60:63], v[156:159], v[188:191], v[60:63]
	v_mfma_f32_16x16x32_bf16 v[56:59], v[164:167], v[188:191], v[56:59]
	v_mfma_f32_16x16x32_bf16 v[52:55], v[156:159], v[198:201], v[52:55]
	v_mfma_f32_16x16x32_bf16 v[44:47], v[164:167], v[198:201], v[44:47]
	v_mfma_f32_16x16x32_bf16 v[36:39], v[156:159], v[206:209], v[36:39]
	v_mfma_f32_16x16x32_bf16 v[28:31], v[164:167], v[206:209], v[28:31]
	v_mfma_f32_16x16x32_bf16 v[20:23], v[156:159], v[214:217], v[20:23]
	v_mfma_f32_16x16x32_bf16 v[12:15], v[164:167], v[214:217], v[12:15]
	v_mfma_f32_16x16x32_bf16 v[48:51], v[168:171], v[184:187], v[48:51]
	v_mfma_f32_16x16x32_bf16 v[40:43], v[176:179], v[184:187], v[40:43]
	v_mfma_f32_16x16x32_bf16 v[32:35], v[168:171], v[192:195], v[32:35]
	v_mfma_f32_16x16x32_bf16 v[24:27], v[176:179], v[192:195], v[24:27]
	v_mfma_f32_16x16x32_bf16 v[16:19], v[168:171], v[202:205], v[16:19]
	v_mfma_f32_16x16x32_bf16 v[8:11], v[176:179], v[202:205], v[8:11]
	v_mfma_f32_16x16x32_bf16 v[4:7], v[168:171], v[210:213], v[4:7]
	v_mfma_f32_16x16x32_bf16 v[0:3], v[176:179], v[210:213], v[0:3]
	v_mfma_f32_16x16x32_bf16 v[48:51], v[172:175], v[188:191], v[48:51]
	v_mfma_f32_16x16x32_bf16 v[40:43], v[180:183], v[188:191], v[40:43]
	v_mfma_f32_16x16x32_bf16 v[32:35], v[172:175], v[198:201], v[32:35]
	v_mfma_f32_16x16x32_bf16 v[24:27], v[180:183], v[198:201], v[24:27]
	v_mfma_f32_16x16x32_bf16 v[16:19], v[172:175], v[206:209], v[16:19]
	v_mfma_f32_16x16x32_bf16 v[8:11], v[180:183], v[206:209], v[8:11]
	v_mfma_f32_16x16x32_bf16 v[4:7], v[172:175], v[214:217], v[4:7]
	v_mfma_f32_16x16x32_bf16 v[0:3], v[180:183], v[214:217], v[0:3]
	s_setprio 0
	s_barrier
	s_add_i32 s65, s65, 2
	s_add_u32 s63, s63, 0x100
	s_addc_u32 s64, s64, 0
	s_add_u32 s38, s38, 0x100
	s_addc_u32 s39, s39, 0
	s_cmp_gt_u32 s65, 29
	s_cbranch_scc0 .LBB0_1487
	s_and_b64 vcc, exec, s[16:17]
	s_cbranch_vccz .LBB0_1490
	s_barrier

; #define PG8_STAGE(bufoff, gbase, voff) do { _Pragma("unroll") for (int _i = 0; _i < 2; ++_i) \
;         __builtin_amdgcn_global_load_lds((const unsigned*)((const char*)(gbase) + (voff)[_i]), (PG8_LAS unsigned*)(lds + (bufoff) + ldsw + _i * 8192), 16, 0, 0); } while (0)
; #define PG8_LDA(dst, b, h) do { _Pragma("unroll") for (int m = 0; m < 4; ++m) _Pragma("unroll") for (int k = 0; k < 2; ++k) dst[m][k] = *(const PG8_LAS bf16x8*)(lds + PG8_SA(b, h) + aoff + m * 2048 + k * 1024); } while (0)
; #define PG8_LDB(dst, b, h) do { _Pragma("unroll") for (int n = 0; n < 2; ++n) _Pragma("unroll") for (int k = 0; k < 2; ++k) dst[n][k] = *(const PG8_LAS bf16x8*)(lds + PG8_SB(b, h) + boff + n * 2048 + k * 1024); } while (0)
; #define PG8_MMA(ai, bj, At, Bt) do { __builtin_amdgcn_s_setprio(1); _Pragma("unroll") for (int m = 0; m < 4; ++m) _Pragma("unroll") for (int n = 0; n < 2; ++n) _Pragma("unroll") for (int k = 0; k < 2; ++k) \
;         acc[ai][bj][m][n] = __builtin_amdgcn_mfma_f32_16x16x32_bf16(Bt[n][k], At[m][k], acc[ai][bj][m][n], 0, 0, 0); __builtin_amdgcn_s_setprio(0); } while (0)
; #define PG8_WAIT_V(n) asm volatile("s_waitcnt vmcnt(" #n ")" ::: "memory")
; #define PG8_BAR __builtin_amdgcn_s_barrier()
; template <class Epi, class Sched, bool ALIGN_EPI = false, bool SP2 = false>
; __device__ __forceinline__ void gemm_phase(PG8_LAS unsigned char* lds, const Gemm g, const Sched& S, const Epi& E) {
;     ...
;         for (int t = 0; t < nt; t += 2) {
;             const bool last = (t == nt - 2);
;             const char* a1 = cA + (size_t)(t + 1) * kstep;
;             const char* a2 = last ? nA : cA + (size_t)(t + 2) * kstep; const char* b2 = last ? nB : cB + (size_t)(t + 2) * kstep;
;             const char* a3 = a2 + kstep; const char* b3 = b2 + kstep;
;             if (last && has_next) S.a_ready(nxt);
;             if constexpr (SP2) {
;             PG8_LDB(B0, 0, 0); PG8_LDB(B1, 0, 1); PG8_SCHED; PG8_LDA(At, 0, 0); PG8_STAGE(PG8_SA(1, 1), a1 + hstep, voffA);
;             PG8_WAIT_V(8); PG8_WAIT_L(0); PG8_BAR; PG8_MMA(0, 0, At, B0); PG8_MMA(0, 1, At, B1); PG8_BAR; PG8_SCHED;
;             PG8_LDA(At, 0, 1); PG8_STAGE(PG8_SB(0, 0), b2, voffB); PG8_STAGE(PG8_SB(0, 1), b2 + hstep, voffB); PG8_STAGE(PG8_SA(0, 0), a2, voffA);
;             PG8_WAIT_V(8); PG8_WAIT_L(0); PG8_BAR; PG8_MMA(1, 0, At, B0); PG8_MMA(1, 1, At, B1); PG8_BAR; PG8_SCHED;
.LBB0_2033:
	ds_read_b128 v[140:143], v147
	ds_read_b128 v[150:153], v147 offset:1024
	ds_read_b128 v[154:157], v147 offset:2048
	ds_read_b128 v[158:161], v147 offset:3072
	ds_read_b128 v[162:165], v148
	ds_read_b128 v[166:169], v148 offset:1024
	ds_read_b128 v[170:173], v148 offset:2048
	ds_read_b128 v[174:177], v148 offset:3072
	s_add_u32 s30, s28, 0xfff80080
	s_addc_u32 s31, s29, -1
	s_cmp_eq_u32 s53, 28
	s_cselect_b32 s35, s21, s31
	s_cselect_b32 s34, s49, s30
	s_cselect_b32 s31, s19, s52
	s_cselect_b32 s30, s50, s51
	v_lshl_add_u64 v[194:195], s[28:29], 0, v[134:135]
	s_add_i32 m0, s39, 0xc000
	ds_read_b128 v[178:181], v149
	ds_read_b128 v[182:185], v149 offset:1024
	ds_read_b128 v[186:189], v149 offset:2048
	ds_read_b128 v[190:193], v149 offset:3072
	ds_read_b128 v[198:201], v149 offset:4096
	ds_read_b128 v[202:205], v149 offset:5120
	ds_read_b128 v[206:209], v149 offset:6144
	ds_read_b128 v[210:213], v149 offset:7168
	global_load_lds_dwordx4 v[194:195], off
	v_lshl_add_u64 v[194:195], s[28:29], 0, v[132:133]
	s_add_i32 m0, s39, 0xe000
	s_nop 0
	global_load_lds_dwordx4 v[194:195], off
	s_waitcnt vmcnt(8)
	s_waitcnt lgkmcnt(0)
	s_barrier
	s_setprio 1
	s_waitcnt lgkmcnt(0)
	v_mfma_f32_16x16x32_bf16 v[124:127], v[140:143], v[178:181], v[124:127]
	v_mfma_f32_16x16x32_bf16 v[120:123], v[154:157], v[178:181], v[120:123]
	v_mfma_f32_16x16x32_bf16 v[112:115], v[140:143], v[186:189], v[112:115]
	v_mfma_f32_16x16x32_bf16 v[104:107], v[154:157], v[186:189], v[104:107]
	v_mfma_f32_16x16x32_bf16 v[92:95], v[140:143], v[198:201], v[92:95]
	v_mfma_f32_16x16x32_bf16 v[88:91], v[154:157], v[198:201], v[88:91]
	v_mfma_f32_16x16x32_bf16 v[76:79], v[140:143], v[206:209], v[76:79]
	v_mfma_f32_16x16x32_bf16 v[72:75], v[154:157], v[206:209], v[72:75]
	v_mfma_f32_16x16x32_bf16 v[124:127], v[150:153], v[182:185], v[124:127]
	v_mfma_f32_16x16x32_bf16 v[120:123], v[158:161], v[182:185], v[120:123]
	v_mfma_f32_16x16x32_bf16 v[112:115], v[150:153], v[190:193], v[112:115]
	v_mfma_f32_16x16x32_bf16 v[104:107], v[158:161], v[190:193], v[104:107]
	v_mfma_f32_16x16x32_bf16 v[92:95], v[150:153], v[202:205], v[92:95]
	v_mfma_f32_16x16x32_bf16 v[88:91], v[158:161], v[202:205], v[88:91]
	v_mfma_f32_16x16x32_bf16 v[76:79], v[150:153], v[210:213], v[76:79]
	v_mfma_f32_16x16x32_bf16 v[72:75], v[158:161], v[210:213], v[72:75]
	v_mfma_f32_16x16x32_bf16 v[116:119], v[162:165], v[178:181], v[116:119]
	v_mfma_f32_16x16x32_bf16 v[108:111], v[170:173], v[178:181], v[108:111]
	v_mfma_f32_16x16x32_bf16 v[100:103], v[162:165], v[186:189], v[100:103]
	v_mfma_f32_16x16x32_bf16 v[96:99], v[170:173], v[186:189], v[96:99]
	v_mfma_f32_16x16x32_bf16 v[84:87], v[162:165], v[198:201], v[84:87]
	v_mfma_f32_16x16x32_bf16 v[80:83], v[170:173], v[198:201], v[80:83]
	v_mfma_f32_16x16x32_bf16 v[68:71], v[162:165], v[206:209], v[68:71]
	v_mfma_f32_16x16x32_bf16 v[64:67], v[170:173], v[206:209], v[64:67]
	v_mfma_f32_16x16x32_bf16 v[116:119], v[166:169], v[182:185], v[116:119]
	v_mfma_f32_16x16x32_bf16 v[108:111], v[174:177], v[182:185], v[108:111]
	v_mfma_f32_16x16x32_bf16 v[100:103], v[166:169], v[190:193], v[100:103]
	v_mfma_f32_16x16x32_bf16 v[96:99], v[174:177], v[190:193], v[96:99]
	v_mfma_f32_16x16x32_bf16 v[84:87], v[166:169], v[202:205], v[84:87]
	v_mfma_f32_16x16x32_bf16 v[80:83], v[174:177], v[202:205], v[80:83]
	v_mfma_f32_16x16x32_bf16 v[68:71], v[166:169], v[210:213], v[68:71]
	v_mfma_f32_16x16x32_bf16 v[64:67], v[174:177], v[210:213], v[64:67]
	s_setprio 0
	s_barrier
	s_add_i32 s54, s47, s38
	v_lshl_add_u64 v[194:195], s[30:31], 0, v[128:129]
	s_mov_b32 m0, s54
	ds_read_b128 v[178:181], v149 offset:16384
	ds_read_b128 v[182:185], v149 offset:17408
	ds_read_b128 v[186:189], v149 offset:18432
	ds_read_b128 v[190:193], v149 offset:19456
	ds_read_b128 v[198:201], v149 offset:20480
	ds_read_b128 v[202:205], v149 offset:21504
	ds_read_b128 v[206:209], v149 offset:22528
	ds_read_b128 v[210:213], v149 offset:23552
	global_load_lds_dwordx4 v[194:195], off
	s_add_i32 m0, s54, 0x2000
	s_add_u32 s54, s30, 0x80000
	v_lshl_add_u64 v[214:215], s[30:31], 0, v[130:131]
	s_addc_u32 s55, s31, 0
	s_add_i32 s56, s48, s38
	global_load_lds_dwordx4 v[214:215], off
	v_lshl_add_u64 v[216:217], s[54:55], 0, v[128:129]
	s_mov_b32 m0, s56
	v_lshl_add_u64 v[218:219], s[34:35], 0, v[130:131]
	global_load_lds_dwordx4 v[216:217], off
	v_lshl_add_u64 v[216:217], s[54:55], 0, v[130:131]
	s_add_i32 m0, s56, 0x2000
	s_nop 0
	global_load_lds_dwordx4 v[216:217], off
	v_lshl_add_u64 v[216:217], s[34:35], 0, v[128:129]
	s_mov_b32 m0, s39
	s_nop 0
	global_load_lds_dwordx4 v[216:217], off
	s_mov_b32 m0, s40
	s_nop 0
	global_load_lds_dwordx4 v[218:219], off
	s_waitcnt vmcnt(8)
	s_waitcnt lgkmcnt(0)
	s_barrier
; #define PG8_STAGE(bufoff, gbase, voff) do { _Pragma("unroll") for (int _i = 0; _i < 2; ++_i) \
;         __builtin_amdgcn_global_load_lds((const unsigned*)((const char*)(gbase) + (voff)[_i]), (PG8_LAS unsigned*)(lds + (bufoff) + ldsw + _i * 8192), 16, 0, 0); } while (0)
; #define PG8_LDA(dst, b, h) do { _Pragma("unroll") for (int m = 0; m < 4; ++m) _Pragma("unroll") for (int k = 0; k < 2; ++k) dst[m][k] = *(const PG8_LAS bf16x8*)(lds + PG8_SA(b, h) + aoff + m * 2048 + k * 1024); } while (0)
; #define PG8_LDB(dst, b, h) do { _Pragma("unroll") for (int n = 0; n < 2; ++n) _Pragma("unroll") for (int k = 0; k < 2; ++k) dst[n][k] = *(const PG8_LAS bf16x8*)(lds + PG8_SB(b, h) + boff + n * 2048 + k * 1024); } while (0)
; #define PG8_MMA(ai, bj, At, Bt) do { __builtin_amdgcn_s_setprio(1); _Pragma("unroll") for (int m = 0; m < 4; ++m) _Pragma("unroll") for (int n = 0; n < 2; ++n) _Pragma("unroll") for (int k = 0; k < 2; ++k) \
;         acc[ai][bj][m][n] = __builtin_amdgcn_mfma_f32_16x16x32_bf16(Bt[n][k], At[m][k], acc[ai][bj][m][n], 0, 0, 0); __builtin_amdgcn_s_setprio(0); } while (0)
; #define PG8_WAIT_V(n) asm volatile("s_waitcnt vmcnt(" #n ")" ::: "memory")
; #define PG8_WAIT_L(n) asm volatile("s_waitcnt lgkmcnt(" #n ")" ::: "memory")
; #define PG8_BAR __builtin_amdgcn_s_barrier()
; #define PG8_SCHED __builtin_amdgcn_sched_barrier(0)
; template <class Epi, class Sched, bool ALIGN_EPI = false, bool SP2 = false>
; __device__ __forceinline__ void gemm_phase(PG8_LAS unsigned char* lds, const Gemm g, const Sched& S, const Epi& E) {
;     ...
;             PG8_WAIT_V(8); PG8_WAIT_L(0); PG8_BAR; PG8_MMA(1, 0, At, B0); PG8_MMA(1, 1, At, B1); PG8_BAR; PG8_SCHED;
;             PG8_LDB(B0, 1, 0); PG8_LDB(B1, 1, 1); PG8_SCHED; PG8_LDA(At, 1, 0); PG8_STAGE(PG8_SA(0, 1), a2 + hstep, voffA);
;             PG8_WAIT_V(8); PG8_WAIT_L(0); PG8_BAR; PG8_MMA(0, 0, At, B0); PG8_MMA(0, 1, At, B1); PG8_BAR; PG8_SCHED;
	s_setprio 1
	s_waitcnt lgkmcnt(0)
	v_mfma_f32_16x16x32_bf16 v[60:63], v[140:143], v[178:181], v[60:63]
	v_mfma_f32_16x16x32_bf16 v[56:59], v[154:157], v[178:181], v[56:59]
	v_mfma_f32_16x16x32_bf16 v[44:47], v[140:143], v[186:189], v[44:47]
	v_mfma_f32_16x16x32_bf16 v[40:43], v[154:157], v[186:189], v[40:43]
	v_mfma_f32_16x16x32_bf16 v[28:31], v[140:143], v[198:201], v[28:31]
	v_mfma_f32_16x16x32_bf16 v[24:27], v[154:157], v[198:201], v[24:27]
	v_mfma_f32_16x16x32_bf16 v[12:15], v[140:143], v[206:209], v[12:15]
	v_mfma_f32_16x16x32_bf16 v[8:11], v[154:157], v[206:209], v[8:11]
	v_mfma_f32_16x16x32_bf16 v[60:63], v[150:153], v[182:185], v[60:63]
	v_mfma_f32_16x16x32_bf16 v[56:59], v[158:161], v[182:185], v[56:59]
	v_mfma_f32_16x16x32_bf16 v[44:47], v[150:153], v[190:193], v[44:47]
	v_mfma_f32_16x16x32_bf16 v[40:43], v[158:161], v[190:193], v[40:43]
	v_mfma_f32_16x16x32_bf16 v[28:31], v[150:153], v[202:205], v[28:31]
	v_mfma_f32_16x16x32_bf16 v[24:27], v[158:161], v[202:205], v[24:27]
	v_mfma_f32_16x16x32_bf16 v[12:15], v[150:153], v[210:213], v[12:15]
	v_mfma_f32_16x16x32_bf16 v[8:11], v[158:161], v[210:213], v[8:11]
	v_mfma_f32_16x16x32_bf16 v[52:55], v[162:165], v[178:181], v[52:55]
	v_mfma_f32_16x16x32_bf16 v[48:51], v[170:173], v[178:181], v[48:51]
	v_mfma_f32_16x16x32_bf16 v[36:39], v[162:165], v[186:189], v[36:39]
	v_mfma_f32_16x16x32_bf16 v[32:35], v[170:173], v[186:189], v[32:35]
	v_mfma_f32_16x16x32_bf16 v[20:23], v[162:165], v[198:201], v[20:23]
	v_mfma_f32_16x16x32_bf16 v[16:19], v[170:173], v[198:201], v[16:19]
	v_mfma_f32_16x16x32_bf16 v[4:7], v[162:165], v[206:209], v[4:7]
	v_mfma_f32_16x16x32_bf16 v[0:3], v[170:173], v[206:209], v[0:3]
	v_mfma_f32_16x16x32_bf16 v[52:55], v[166:169], v[182:185], v[52:55]
	v_mfma_f32_16x16x32_bf16 v[48:51], v[174:177], v[182:185], v[48:51]
	v_mfma_f32_16x16x32_bf16 v[36:39], v[166:169], v[190:193], v[36:39]
	v_mfma_f32_16x16x32_bf16 v[32:35], v[174:177], v[190:193], v[32:35]
	v_mfma_f32_16x16x32_bf16 v[20:23], v[166:169], v[202:205], v[20:23]
	v_mfma_f32_16x16x32_bf16 v[16:19], v[174:177], v[202:205], v[16:19]
	v_mfma_f32_16x16x32_bf16 v[4:7], v[166:169], v[210:213], v[4:7]
	v_mfma_f32_16x16x32_bf16 v[0:3], v[174:177], v[210:213], v[0:3]
	s_setprio 0
	s_barrier
	s_add_i32 s54, 0, 0x18000
	s_add_i32 s55, 0, 0x1c000
	v_add_u32_e32 v158, s54, v145
	v_add_u32_e32 v174, s55, v145
	ds_read_b128 v[140:143], v158
	ds_read_b128 v[150:153], v158 offset:1024
	ds_read_b128 v[154:157], v158 offset:2048
	ds_read_b128 v[158:161], v158 offset:3072
	ds_read_b128 v[162:165], v174
	ds_read_b128 v[166:169], v174 offset:1024
	ds_read_b128 v[170:173], v174 offset:2048
	ds_read_b128 v[174:177], v174 offset:3072
	s_add_u32 s34, s34, 0x80000
	s_addc_u32 s35, s35, 0
	s_mov_b32 m0, s41
	v_lshl_add_u64 v[220:221], s[34:35], 0, v[128:129]
	ds_read_b128 v[178:181], v149 offset:32768
	ds_read_b128 v[182:185], v149 offset:33792
	ds_read_b128 v[186:189], v149 offset:34816
	ds_read_b128 v[190:193], v149 offset:35840
	ds_read_b128 v[198:201], v149 offset:36864
	ds_read_b128 v[202:205], v149 offset:37888
	ds_read_b128 v[206:209], v149 offset:38912
	ds_read_b128 v[210:213], v149 offset:39936
	global_load_lds_dwordx4 v[220:221], off
	v_lshl_add_u64 v[220:221], s[34:35], 0, v[130:131]
	s_mov_b32 m0, s42
	s_nop 0
	global_load_lds_dwordx4 v[220:221], off
	s_waitcnt vmcnt(8)
	s_waitcnt lgkmcnt(0)
	s_barrier
	s_setprio 1
	s_waitcnt lgkmcnt(0)
	v_mfma_f32_16x16x32_bf16 v[124:127], v[140:143], v[178:181], v[124:127]
	v_mfma_f32_16x16x32_bf16 v[120:123], v[154:157], v[178:181], v[120:123]
	v_mfma_f32_16x16x32_bf16 v[112:115], v[140:143], v[186:189], v[112:115]
	v_mfma_f32_16x16x32_bf16 v[104:107], v[154:157], v[186:189], v[104:107]
	v_mfma_f32_16x16x32_bf16 v[92:95], v[140:143], v[198:201], v[92:95]
	v_mfma_f32_16x16x32_bf16 v[88:91], v[154:157], v[198:201], v[88:91]
	v_mfma_f32_16x16x32_bf16 v[76:79], v[140:143], v[206:209], v[76:79]
	v_mfma_f32_16x16x32_bf16 v[72:75], v[154:157], v[206:209], v[72:75]
	v_mfma_f32_16x16x32_bf16 v[124:127], v[150:153], v[182:185], v[124:127]
	v_mfma_f32_16x16x32_bf16 v[120:123], v[158:161], v[182:185], v[120:123]
	v_mfma_f32_16x16x32_bf16 v[112:115], v[150:153], v[190:193], v[112:115]
	v_mfma_f32_16x16x32_bf16 v[104:107], v[158:161], v[190:193], v[104:107]
	v_mfma_f32_16x16x32_bf16 v[92:95], v[150:153], v[202:205], v[92:95]
	v_mfma_f32_16x16x32_bf16 v[88:91], v[158:161], v[202:205], v[88:91]
	v_mfma_f32_16x16x32_bf16 v[76:79], v[150:153], v[210:213], v[76:79]
	v_mfma_f32_16x16x32_bf16 v[72:75], v[158:161], v[210:213], v[72:75]
	v_mfma_f32_16x16x32_bf16 v[116:119], v[162:165], v[178:181], v[116:119]
	v_mfma_f32_16x16x32_bf16 v[108:111], v[170:173], v[178:181], v[108:111]
	v_mfma_f32_16x16x32_bf16 v[100:103], v[162:165], v[186:189], v[100:103]
	v_mfma_f32_16x16x32_bf16 v[96:99], v[170:173], v[186:189], v[96:99]
	v_mfma_f32_16x16x32_bf16 v[84:87], v[162:165], v[198:201], v[84:87]
	v_mfma_f32_16x16x32_bf16 v[80:83], v[170:173], v[198:201], v[80:83]
	v_mfma_f32_16x16x32_bf16 v[68:71], v[162:165], v[206:209], v[68:71]
	v_mfma_f32_16x16x32_bf16 v[64:67], v[170:173], v[206:209], v[64:67]
	v_mfma_f32_16x16x32_bf16 v[116:119], v[166:169], v[182:185], v[116:119]
	v_mfma_f32_16x16x32_bf16 v[108:111], v[174:177], v[182:185], v[108:111]
	v_mfma_f32_16x16x32_bf16 v[100:103], v[166:169], v[190:193], v[100:103]
	v_mfma_f32_16x16x32_bf16 v[96:99], v[174:177], v[190:193], v[96:99]
	v_mfma_f32_16x16x32_bf16 v[84:87], v[166:169], v[202:205], v[84:87]
	v_mfma_f32_16x16x32_bf16 v[80:83], v[174:177], v[202:205], v[80:83]
	v_mfma_f32_16x16x32_bf16 v[68:71], v[166:169], v[210:213], v[68:71]
	v_mfma_f32_16x16x32_bf16 v[64:67], v[174:177], v[210:213], v[64:67]
	s_setprio 0
	s_barrier
; #define PG8_STAGE(bufoff, gbase, voff) do { _Pragma("unroll") for (int _i = 0; _i < 2; ++_i) \
;         __builtin_amdgcn_global_load_lds((const unsigned*)((const char*)(gbase) + (voff)[_i]), (PG8_LAS unsigned*)(lds + (bufoff) + ldsw + _i * 8192), 16, 0, 0); } while (0)
; #define PG8_LDA(dst, b, h) do { _Pragma("unroll") for (int m = 0; m < 4; ++m) _Pragma("unroll") for (int k = 0; k < 2; ++k) dst[m][k] = *(const PG8_LAS bf16x8*)(lds + PG8_SA(b, h) + aoff + m * 2048 + k * 1024); } while (0)
; #define PG8_WAIT_V(n) asm volatile("s_waitcnt vmcnt(" #n ")" ::: "memory")
; template <class Epi, class Sched, bool ALIGN_EPI = false, bool SP2 = false>
; __device__ __forceinline__ void gemm_phase(PG8_LAS unsigned char* lds, const Gemm g, const Sched& S, const Epi& E) {
;     ...
;             PG8_LDA(At, 1, 1); PG8_STAGE(PG8_SB(1, 0), b3, voffB); PG8_STAGE(PG8_SB(1, 1), b3 + hstep, voffB); PG8_STAGE(PG8_SA(1, 0), a3, voffA);
;             PG8_WAIT_V(8); PG8_WAIT_L(0); PG8_BAR; PG8_MMA(1, 0, At, B0); PG8_MMA(1, 1, At, B1); PG8_BAR; PG8_SCHED;
;             } else {
;             PG8_LDB(B0, 0, 0); PG8_SCHED; PG8_LDA(At, 0, 0); PG8_STAGE(PG8_SA(1, 1), a1 + hstep, voffA);
;             PG8_WAIT_L(8); PG8_BAR; PG8_WAIT_L(0); PG8_MMA(0, 0, At, B0); PG8_BAR; PG8_SCHED;
;             PG8_LDB(B1, 0, 1); PG8_STAGE(PG8_SB(0, 0), b2, voffB);
;             PG8_BAR; PG8_WAIT_L(0); PG8_MMA(0, 1, At, B1); PG8_BAR;
;             PG8_LDA(At, 0, 1); PG8_STAGE(PG8_SA(0, 0), a2, voffA);
;             PG8_BAR; PG8_WAIT_L(0); PG8_MMA(1, 0, At, B0); PG8_BAR; PG8_SCHED;
;             PG8_STAGE(PG8_SB(0, 1), b2 + hstep, voffB);
;             PG8_WAIT_V(6); PG8_BAR; PG8_MMA(1, 1, At, B1); PG8_BAR;
;             PG8_LDB(B0, 1, 0); PG8_SCHED; PG8_LDA(At, 1, 0); PG8_STAGE(PG8_SA(0, 1), a2 + hstep, voffA);
;             PG8_WAIT_L(8); PG8_BAR; PG8_WAIT_L(0); PG8_MMA(0, 0, At, B0); PG8_BAR; PG8_SCHED;
;             PG8_LDB(B1, 1, 1); PG8_STAGE(PG8_SB(1, 0), b3, voffB);
;             PG8_BAR; PG8_WAIT_L(0); PG8_MMA(0, 1, At, B1); PG8_BAR;
;             PG8_LDA(At, 1, 1); PG8_STAGE(PG8_SA(1, 0), a3, voffA);
;             PG8_BAR; PG8_WAIT_L(0); PG8_MMA(1, 0, At, B0); PG8_BAR; PG8_SCHED;
;             PG8_STAGE(PG8_SB(1, 1), b3 + hstep, voffB);
;             PG8_WAIT_V(6); PG8_BAR; PG8_MMA(1, 1, At, B1); PG8_BAR;
;             }
;         }
;         if constexpr (ALIGN_EPI) { if (wr == 0) PG8_BAR; }
	s_add_i32 s34, s54, s38
	v_lshl_add_u64 v[194:195], v[194:195], 0, s[14:15]
	s_mov_b32 m0, s34
	ds_read_b128 v[178:181], v149 offset:49152
	ds_read_b128 v[182:185], v149 offset:50176
	ds_read_b128 v[186:189], v149 offset:51200
	ds_read_b128 v[190:193], v149 offset:52224
	ds_read_b128 v[198:201], v149 offset:53248
	ds_read_b128 v[202:205], v149 offset:54272
	ds_read_b128 v[206:209], v149 offset:55296
	ds_read_b128 v[210:213], v149 offset:56320
	global_load_lds_dwordx4 v[194:195], off
	s_add_i32 m0, s34, 0x2000
	s_add_u32 s30, s30, 0x80080
	v_lshl_add_u64 v[194:195], v[214:215], 0, s[14:15]
	s_addc_u32 s31, s31, 0
	s_add_i32 s34, s55, s38
	global_load_lds_dwordx4 v[194:195], off
	v_lshl_add_u64 v[194:195], s[30:31], 0, v[128:129]
	s_mov_b32 m0, s34
	s_nop 0
	global_load_lds_dwordx4 v[194:195], off
	v_lshl_add_u64 v[194:195], s[30:31], 0, v[130:131]
	s_add_i32 m0, s34, 0x2000
	s_nop 0
	global_load_lds_dwordx4 v[194:195], off
	v_lshl_add_u64 v[194:195], v[216:217], 0, s[14:15]
	s_mov_b32 m0, s44
	s_nop 0
	global_load_lds_dwordx4 v[194:195], off
	v_lshl_add_u64 v[194:195], v[218:219], 0, s[14:15]
	s_mov_b32 m0, s45
	s_nop 0
	global_load_lds_dwordx4 v[194:195], off
	s_waitcnt vmcnt(8)
	s_waitcnt lgkmcnt(0)
	s_barrier
	s_setprio 1
	s_waitcnt lgkmcnt(0)
	v_mfma_f32_16x16x32_bf16 v[60:63], v[140:143], v[178:181], v[60:63]
	v_mfma_f32_16x16x32_bf16 v[56:59], v[154:157], v[178:181], v[56:59]
	v_mfma_f32_16x16x32_bf16 v[44:47], v[140:143], v[186:189], v[44:47]
	v_mfma_f32_16x16x32_bf16 v[40:43], v[154:157], v[186:189], v[40:43]
	v_mfma_f32_16x16x32_bf16 v[28:31], v[140:143], v[198:201], v[28:31]
	v_mfma_f32_16x16x32_bf16 v[24:27], v[154:157], v[198:201], v[24:27]
	v_mfma_f32_16x16x32_bf16 v[12:15], v[140:143], v[206:209], v[12:15]
	v_mfma_f32_16x16x32_bf16 v[8:11], v[154:157], v[206:209], v[8:11]
	v_mfma_f32_16x16x32_bf16 v[60:63], v[150:153], v[182:185], v[60:63]
	v_mfma_f32_16x16x32_bf16 v[56:59], v[158:161], v[182:185], v[56:59]
	v_mfma_f32_16x16x32_bf16 v[44:47], v[150:153], v[190:193], v[44:47]
	v_mfma_f32_16x16x32_bf16 v[40:43], v[158:161], v[190:193], v[40:43]
	v_mfma_f32_16x16x32_bf16 v[28:31], v[150:153], v[202:205], v[28:31]
	v_mfma_f32_16x16x32_bf16 v[24:27], v[158:161], v[202:205], v[24:27]
	v_mfma_f32_16x16x32_bf16 v[12:15], v[150:153], v[210:213], v[12:15]
	v_mfma_f32_16x16x32_bf16 v[8:11], v[158:161], v[210:213], v[8:11]
	v_mfma_f32_16x16x32_bf16 v[52:55], v[162:165], v[178:181], v[52:55]
	v_mfma_f32_16x16x32_bf16 v[48:51], v[170:173], v[178:181], v[48:51]
	v_mfma_f32_16x16x32_bf16 v[36:39], v[162:165], v[186:189], v[36:39]
	v_mfma_f32_16x16x32_bf16 v[32:35], v[170:173], v[186:189], v[32:35]
	v_mfma_f32_16x16x32_bf16 v[20:23], v[162:165], v[198:201], v[20:23]
	v_mfma_f32_16x16x32_bf16 v[16:19], v[170:173], v[198:201], v[16:19]
	v_mfma_f32_16x16x32_bf16 v[4:7], v[162:165], v[206:209], v[4:7]
	v_mfma_f32_16x16x32_bf16 v[0:3], v[170:173], v[206:209], v[0:3]
	v_mfma_f32_16x16x32_bf16 v[52:55], v[166:169], v[182:185], v[52:55]
	v_mfma_f32_16x16x32_bf16 v[48:51], v[174:177], v[182:185], v[48:51]
	v_mfma_f32_16x16x32_bf16 v[36:39], v[166:169], v[190:193], v[36:39]
	v_mfma_f32_16x16x32_bf16 v[32:35], v[174:177], v[190:193], v[32:35]
	v_mfma_f32_16x16x32_bf16 v[20:23], v[166:169], v[202:205], v[20:23]
	v_mfma_f32_16x16x32_bf16 v[16:19], v[174:177], v[202:205], v[16:19]
	v_mfma_f32_16x16x32_bf16 v[4:7], v[166:169], v[210:213], v[4:7]
	v_mfma_f32_16x16x32_bf16 v[0:3], v[174:177], v[210:213], v[0:3]
	s_setprio 0
	s_barrier
	s_add_i32 s53, s53, 2
	s_add_u32 s51, s51, 0x100
	s_addc_u32 s52, s52, 0
	s_add_u32 s28, s28, 0x100
	s_addc_u32 s29, s29, 0
	s_cmp_gt_u32 s53, 29
	s_cbranch_scc0 .LBB0_2033
	s_and_b64 vcc, exec, s[16:17]
	s_cbranch_vccz .LBB0_2036
	s_barrier
